# f1/fa bodies: per-phase s_setprio flips replaced by s_nop 0 (priority A/B, size-neutral)
# baseline (speedup 1.0000x reference)
.LBB0_59:
	s_ashr_i32 s31, s30, 31
	s_lshl_b64 s[14:15], s[30:31], 17
	v_readlane_b32 s18, v254, 29
	v_mov_b64_e32 v[0:1], 0x200
	v_readlane_b32 s19, v254, 30
	s_add_u32 s34, s18, s14
	v_cmp_lt_i64_e32 vcc, s[8:9], v[0:1]
	s_addc_u32 s35, s19, s15
	s_and_b64 s[14:15], vcc, exec
	s_cselect_b32 s45, s35, s41
	s_cselect_b32 s44, s34, s40
	s_ashr_i32 s13, s12, 31
	s_lshl_b64 s[14:15], s[12:13], 17
	s_add_u32 s18, s94, s14
	s_addc_u32 s19, s95, s15
	s_and_b64 s[14:15], vcc, exec
	s_cselect_b32 s15, s19, s43
	s_cselect_b32 s14, s18, s42
	s_add_i32 s47, 16, 0x10000
	v_add_u32_e32 v115, s47, v109
	ds_read_b128 v[0:3], v115
	ds_read_b128 v[4:7], v115 offset:1024
	ds_read_b128 v[8:11], v115 offset:2048
	ds_read_b128 v[12:15], v115 offset:3072
	v_mov_b64_e32 v[112:113], 0x2ff
	v_mov_b32_e32 v111, 0x3e642e9d
	v_mov_b32_e32 v243, 0xbf1f24be
	s_add_u32 s48, s40, 0x10080
	s_addc_u32 s49, s41, 0
	s_add_i32 s92, s16, 0xc000
	v_lshl_add_u64 v[48:49], s[48:49], 0, v[106:107]
	s_mov_b32 m0, s92
	s_add_i32 s1, s16, 0xe000
	ds_read_b128 v[16:19], v114
	ds_read_b128 v[20:23], v114 offset:1024
	ds_read_b128 v[24:27], v114 offset:2048
	ds_read_b128 v[28:31], v114 offset:3072
	ds_read_b128 v[32:35], v114 offset:4096
	ds_read_b128 v[36:39], v114 offset:5120
	ds_read_b128 v[40:43], v114 offset:6144
	ds_read_b128 v[44:47], v114 offset:7168
	global_load_lds_dwordx4 v[48:49], off
	v_lshl_add_u64 v[48:49], s[48:49], 0, v[104:105]
	s_mov_b32 m0, s1
	s_nop 0
	global_load_lds_dwordx4 v[48:49], off
	s_waitcnt lgkmcnt(8)
	s_barrier
	s_waitcnt lgkmcnt(0)
	s_nop 0
	s_waitcnt lgkmcnt(0)
	v_mfma_f32_16x16x32_bf16 v[48:51], v[0:3], v[16:19], 0
	v_mfma_f32_16x16x32_bf16 v[52:55], v[8:11], v[16:19], 0
	v_mfma_f32_16x16x32_bf16 v[56:59], v[0:3], v[24:27], 0
	v_mfma_f32_16x16x32_bf16 v[60:63], v[8:11], v[24:27], 0
	v_mfma_f32_16x16x32_bf16 v[64:67], v[0:3], v[32:35], 0
	v_mfma_f32_16x16x32_bf16 v[68:71], v[8:11], v[32:35], 0
	v_mfma_f32_16x16x32_bf16 v[72:75], v[0:3], v[40:43], 0
	v_mfma_f32_16x16x32_bf16 v[76:79], v[8:11], v[40:43], 0
	v_mfma_f32_16x16x32_bf16 v[48:51], v[4:7], v[20:23], v[48:51]
	v_mfma_f32_16x16x32_bf16 v[52:55], v[12:15], v[20:23], v[52:55]
	v_mfma_f32_16x16x32_bf16 v[56:59], v[4:7], v[28:31], v[56:59]
	v_mfma_f32_16x16x32_bf16 v[60:63], v[12:15], v[28:31], v[60:63]
	v_mfma_f32_16x16x32_bf16 v[64:67], v[4:7], v[36:39], v[64:67]
	v_mfma_f32_16x16x32_bf16 v[68:71], v[12:15], v[36:39], v[68:71]
	v_mfma_f32_16x16x32_bf16 v[72:75], v[4:7], v[44:47], v[72:75]
	v_mfma_f32_16x16x32_bf16 v[76:79], v[12:15], v[44:47], v[76:79]
	s_nop 0
	s_barrier
	s_add_i32 vcc_lo, 16, 0x14000
	v_lshl_add_u64 v[130:131], s[42:43], 0, v[106:107]
	s_mov_b64 s[48:49], 0x100
	s_add_i32 s47, s47, s5
	v_add_u32_e32 v128, vcc_lo, v109
	v_lshl_add_u64 v[96:97], v[130:131], 0, s[48:49]
	s_mov_b32 m0, s47
	v_lshl_add_u64 v[132:133], s[42:43], 0, v[104:105]
	s_add_i32 s13, s47, 0x2000
	ds_read_b128 v[80:83], v128
	ds_read_b128 v[84:87], v128 offset:1024
	ds_read_b128 v[88:91], v128 offset:2048
	ds_read_b128 v[92:95], v128 offset:3072
	global_load_lds_dwordx4 v[96:97], off
	v_lshl_add_u64 v[96:97], v[132:133], 0, s[48:49]
	s_mov_b32 m0, s13
	s_nop 0
	global_load_lds_dwordx4 v[96:97], off
	s_barrier
	s_waitcnt lgkmcnt(0)
	s_nop 0
	s_waitcnt lgkmcnt(0)
	v_mfma_f32_16x16x32_bf16 v[96:99], v[80:83], v[16:19], 0
	v_mfma_f32_16x16x32_bf16 v[16:19], v[88:91], v[16:19], 0
	v_mfma_f32_16x16x32_bf16 v[96:99], v[84:87], v[20:23], v[96:99]
	v_mfma_f32_16x16x32_bf16 v[16:19], v[92:95], v[20:23], v[16:19]
	v_mfma_f32_16x16x32_bf16 v[20:23], v[80:83], v[24:27], 0
	v_mfma_f32_16x16x32_bf16 v[24:27], v[88:91], v[24:27], 0
	v_mfma_f32_16x16x32_bf16 v[20:23], v[84:87], v[28:31], v[20:23]
	v_mfma_f32_16x16x32_bf16 v[24:27], v[92:95], v[28:31], v[24:27]
	v_mfma_f32_16x16x32_bf16 v[28:31], v[80:83], v[32:35], 0
	v_mfma_f32_16x16x32_bf16 v[32:35], v[88:91], v[32:35], 0
	v_mfma_f32_16x16x32_bf16 v[28:31], v[84:87], v[36:39], v[28:31]
	v_mfma_f32_16x16x32_bf16 v[32:35], v[92:95], v[36:39], v[32:35]
	v_mfma_f32_16x16x32_bf16 v[36:39], v[80:83], v[40:43], 0
	v_mfma_f32_16x16x32_bf16 v[40:43], v[88:91], v[40:43], 0
	v_mfma_f32_16x16x32_bf16 v[36:39], v[84:87], v[44:47], v[36:39]
	v_mfma_f32_16x16x32_bf16 v[40:43], v[92:95], v[44:47], v[40:43]
	s_nop 0
	v_lshl_add_u64 v[134:135], s[40:41], 0, v[106:107]
	s_mov_b32 m0, s16
	v_lshl_add_u64 v[136:137], v[134:135], 0, s[48:49]
	s_barrier
	ds_read_b128 v[44:47], v114 offset:16384
	ds_read_b128 v[100:103], v114 offset:17408
	ds_read_b128 v[116:119], v114 offset:18432
	ds_read_b128 v[120:123], v114 offset:19456
	ds_read_b128 v[124:127], v114 offset:20480
	ds_read_b128 v[144:147], v114 offset:21504
	ds_read_b128 v[148:151], v114 offset:22528
	ds_read_b128 v[152:155], v114 offset:23552
	global_load_lds_dwordx4 v[136:137], off
	v_lshl_add_u64 v[136:137], s[40:41], 0, v[104:105]
	v_lshl_add_u64 v[156:157], v[136:137], 0, s[48:49]
	s_mov_b32 m0, s17
	s_nop 0
	global_load_lds_dwordx4 v[156:157], off
	s_barrier
	s_waitcnt lgkmcnt(0)
	s_nop 0
	s_waitcnt lgkmcnt(0)
	v_mfma_f32_16x16x32_bf16 v[156:159], v[0:3], v[44:47], 0
	v_mfma_f32_16x16x32_bf16 v[164:167], v[0:3], v[116:119], 0
	v_mfma_f32_16x16x32_bf16 v[172:175], v[0:3], v[124:127], 0
	v_mfma_f32_16x16x32_bf16 v[0:3], v[0:3], v[148:151], 0
	v_mfma_f32_16x16x32_bf16 v[156:159], v[4:7], v[100:103], v[156:159]
	v_mfma_f32_16x16x32_bf16 v[160:163], v[8:11], v[44:47], 0
	v_mfma_f32_16x16x32_bf16 v[164:167], v[4:7], v[120:123], v[164:167]
	v_mfma_f32_16x16x32_bf16 v[168:171], v[8:11], v[116:119], 0
	v_mfma_f32_16x16x32_bf16 v[172:175], v[4:7], v[144:147], v[172:175]
	v_mfma_f32_16x16x32_bf16 v[176:179], v[8:11], v[124:127], 0
	v_mfma_f32_16x16x32_bf16 v[0:3], v[4:7], v[152:155], v[0:3]
	v_mfma_f32_16x16x32_bf16 v[4:7], v[8:11], v[148:151], 0
	v_mfma_f32_16x16x32_bf16 v[160:163], v[12:15], v[100:103], v[160:163]
	v_mfma_f32_16x16x32_bf16 v[168:171], v[12:15], v[120:123], v[168:171]
	v_mfma_f32_16x16x32_bf16 v[176:179], v[12:15], v[144:147], v[176:179]
	v_mfma_f32_16x16x32_bf16 v[4:7], v[12:15], v[152:155], v[4:7]
	s_nop 0
	s_barrier
	s_add_u32 s48, s42, 0x10100
	s_addc_u32 s49, s43, 0
	s_add_i32 vcc_lo, vcc_lo, s5
	v_lshl_add_u64 v[8:9], s[48:49], 0, v[106:107]
	s_mov_b32 m0, vcc_lo
	s_add_i32 s31, vcc_lo, 0x2000
	global_load_lds_dwordx4 v[8:9], off
	v_lshl_add_u64 v[8:9], s[48:49], 0, v[104:105]
	s_mov_b32 m0, s31
	s_nop 0
	global_load_lds_dwordx4 v[8:9], off
	s_waitcnt vmcnt(6)
	s_barrier
	s_nop 0
	v_mfma_f32_16x16x32_bf16 v[8:11], v[80:83], v[44:47], 0
	v_mfma_f32_16x16x32_bf16 v[12:15], v[88:91], v[44:47], 0
	v_mfma_f32_16x16x32_bf16 v[8:11], v[84:87], v[100:103], v[8:11]
	v_mfma_f32_16x16x32_bf16 v[12:15], v[92:95], v[100:103], v[12:15]
	v_mfma_f32_16x16x32_bf16 v[44:47], v[80:83], v[116:119], 0
	v_mfma_f32_16x16x32_bf16 v[100:103], v[88:91], v[116:119], 0
	v_mfma_f32_16x16x32_bf16 v[116:119], v[80:83], v[124:127], 0
	v_mfma_f32_16x16x32_bf16 v[80:83], v[80:83], v[148:151], 0
	v_mfma_f32_16x16x32_bf16 v[44:47], v[84:87], v[120:123], v[44:47]
	v_mfma_f32_16x16x32_bf16 v[100:103], v[92:95], v[120:123], v[100:103]
	v_mfma_f32_16x16x32_bf16 v[116:119], v[84:87], v[144:147], v[116:119]
	v_mfma_f32_16x16x32_bf16 v[120:123], v[88:91], v[124:127], 0
	v_mfma_f32_16x16x32_bf16 v[80:83], v[84:87], v[152:155], v[80:83]
	v_mfma_f32_16x16x32_bf16 v[84:87], v[88:91], v[148:151], 0
	v_mfma_f32_16x16x32_bf16 v[120:123], v[92:95], v[144:147], v[120:123]
	v_mfma_f32_16x16x32_bf16 v[84:87], v[92:95], v[152:155], v[84:87]
	s_nop 0
	s_add_i32 s20, 16, 0x18000
	v_add_u32_e32 v143, s20, v109
	s_barrier
	ds_read_b128 v[88:91], v143
	ds_read_b128 v[92:95], v143 offset:1024
	ds_read_b128 v[124:127], v143 offset:2048
	ds_read_b128 v[144:147], v143 offset:3072
	s_add_u32 s48, s40, 0x10100
	s_addc_u32 s49, s41, 0
	s_mov_b32 m0, s36
	v_lshl_add_u64 v[204:205], s[48:49], 0, v[106:107]
	ds_read_b128 v[148:151], v114 offset:32768
	ds_read_b128 v[152:155], v114 offset:33792
	ds_read_b128 v[180:183], v114 offset:34816
	ds_read_b128 v[184:187], v114 offset:35840
	ds_read_b128 v[188:191], v114 offset:36864
	ds_read_b128 v[192:195], v114 offset:37888
	ds_read_b128 v[196:199], v114 offset:38912
	ds_read_b128 v[200:203], v114 offset:39936
	global_load_lds_dwordx4 v[204:205], off
	v_lshl_add_u64 v[204:205], s[48:49], 0, v[104:105]
	s_mov_b32 m0, s37
	s_nop 0
	global_load_lds_dwordx4 v[204:205], off
	s_waitcnt lgkmcnt(8)
	s_barrier
	s_waitcnt lgkmcnt(0)
	s_nop 0
	s_waitcnt lgkmcnt(0)
	v_mfma_f32_16x16x32_bf16 v[48:51], v[88:91], v[148:151], v[48:51]
	v_mfma_f32_16x16x32_bf16 v[52:55], v[124:127], v[148:151], v[52:55]
	v_mfma_f32_16x16x32_bf16 v[56:59], v[88:91], v[180:183], v[56:59]
	v_mfma_f32_16x16x32_bf16 v[60:63], v[124:127], v[180:183], v[60:63]
	v_mfma_f32_16x16x32_bf16 v[64:67], v[88:91], v[188:191], v[64:67]
	v_mfma_f32_16x16x32_bf16 v[68:71], v[124:127], v[188:191], v[68:71]
	v_mfma_f32_16x16x32_bf16 v[72:75], v[88:91], v[196:199], v[72:75]
	v_mfma_f32_16x16x32_bf16 v[76:79], v[124:127], v[196:199], v[76:79]
	v_mfma_f32_16x16x32_bf16 v[48:51], v[92:95], v[152:155], v[48:51]
	v_mfma_f32_16x16x32_bf16 v[52:55], v[144:147], v[152:155], v[52:55]
	v_mfma_f32_16x16x32_bf16 v[56:59], v[92:95], v[184:187], v[56:59]
	v_mfma_f32_16x16x32_bf16 v[60:63], v[144:147], v[184:187], v[60:63]
	v_mfma_f32_16x16x32_bf16 v[64:67], v[92:95], v[192:195], v[64:67]
	v_mfma_f32_16x16x32_bf16 v[68:71], v[144:147], v[192:195], v[68:71]
	v_mfma_f32_16x16x32_bf16 v[72:75], v[92:95], v[200:203], v[72:75]
	v_mfma_f32_16x16x32_bf16 v[76:79], v[144:147], v[200:203], v[76:79]
	s_nop 0
	s_barrier
	s_add_i32 s49, 16, 0x1c000
	s_mov_b64 s[50:51], 0x180
	s_add_i32 s48, s20, s5
	v_add_u32_e32 v242, s49, v109
	v_lshl_add_u64 v[130:131], v[130:131], 0, s[50:51]
	s_mov_b32 m0, s48
	s_add_i32 vcc_hi, s48, 0x2000
	ds_read_b128 v[204:207], v242
	ds_read_b128 v[208:211], v242 offset:1024
	ds_read_b128 v[212:215], v242 offset:2048
	ds_read_b128 v[216:219], v242 offset:3072
	global_load_lds_dwordx4 v[130:131], off
	v_lshl_add_u64 v[130:131], v[132:133], 0, s[50:51]
	s_mov_b32 m0, vcc_hi
	s_nop 0
	global_load_lds_dwordx4 v[130:131], off
	s_barrier
	s_waitcnt lgkmcnt(0)
	s_nop 0
	s_waitcnt lgkmcnt(0)
	v_mfma_f32_16x16x32_bf16 v[96:99], v[204:207], v[148:151], v[96:99]
	v_mfma_f32_16x16x32_bf16 v[16:19], v[212:215], v[148:151], v[16:19]
	v_mfma_f32_16x16x32_bf16 v[20:23], v[204:207], v[180:183], v[20:23]
	v_mfma_f32_16x16x32_bf16 v[24:27], v[212:215], v[180:183], v[24:27]
	v_mfma_f32_16x16x32_bf16 v[28:31], v[204:207], v[188:191], v[28:31]
	v_mfma_f32_16x16x32_bf16 v[32:35], v[212:215], v[188:191], v[32:35]
	v_mfma_f32_16x16x32_bf16 v[36:39], v[204:207], v[196:199], v[36:39]
	v_mfma_f32_16x16x32_bf16 v[40:43], v[212:215], v[196:199], v[40:43]
	v_mfma_f32_16x16x32_bf16 v[96:99], v[208:211], v[152:155], v[96:99]
	v_mfma_f32_16x16x32_bf16 v[16:19], v[216:219], v[152:155], v[16:19]
	v_mfma_f32_16x16x32_bf16 v[20:23], v[208:211], v[184:187], v[20:23]
	v_mfma_f32_16x16x32_bf16 v[24:27], v[216:219], v[184:187], v[24:27]
	v_mfma_f32_16x16x32_bf16 v[28:31], v[208:211], v[192:195], v[28:31]
	v_mfma_f32_16x16x32_bf16 v[32:35], v[216:219], v[192:195], v[32:35]
	v_mfma_f32_16x16x32_bf16 v[36:39], v[208:211], v[200:203], v[36:39]
	v_mfma_f32_16x16x32_bf16 v[40:43], v[216:219], v[200:203], v[40:43]
	s_nop 0
	s_mov_b32 m0, s24
	v_lshl_add_u64 v[130:131], v[134:135], 0, s[50:51]
	s_barrier
	ds_read_b128 v[148:151], v114 offset:49152
	ds_read_b128 v[152:155], v114 offset:50176
	ds_read_b128 v[180:183], v114 offset:51200
	ds_read_b128 v[184:187], v114 offset:52224
	ds_read_b128 v[188:191], v114 offset:53248
	ds_read_b128 v[192:195], v114 offset:54272
	ds_read_b128 v[196:199], v114 offset:55296
	ds_read_b128 v[200:203], v114 offset:56320
	global_load_lds_dwordx4 v[130:131], off
	v_lshl_add_u64 v[130:131], v[136:137], 0, s[50:51]
	s_mov_b32 m0, s25
	s_nop 0
	global_load_lds_dwordx4 v[130:131], off
	s_barrier
	s_waitcnt lgkmcnt(0)
	s_nop 0
	s_waitcnt lgkmcnt(0)
	v_mfma_f32_16x16x32_bf16 v[156:159], v[88:91], v[148:151], v[156:159]
	v_mfma_f32_16x16x32_bf16 v[160:163], v[124:127], v[148:151], v[160:163]
	v_mfma_f32_16x16x32_bf16 v[164:167], v[88:91], v[180:183], v[164:167]
	v_mfma_f32_16x16x32_bf16 v[168:171], v[124:127], v[180:183], v[168:171]
	v_mfma_f32_16x16x32_bf16 v[172:175], v[88:91], v[188:191], v[172:175]
	v_mfma_f32_16x16x32_bf16 v[176:179], v[124:127], v[188:191], v[176:179]
	v_mfma_f32_16x16x32_bf16 v[0:3], v[88:91], v[196:199], v[0:3]
	v_mfma_f32_16x16x32_bf16 v[4:7], v[124:127], v[196:199], v[4:7]
	v_mfma_f32_16x16x32_bf16 v[156:159], v[92:95], v[152:155], v[156:159]
	v_mfma_f32_16x16x32_bf16 v[160:163], v[144:147], v[152:155], v[160:163]
	v_mfma_f32_16x16x32_bf16 v[164:167], v[92:95], v[184:187], v[164:167]
	v_mfma_f32_16x16x32_bf16 v[168:171], v[144:147], v[184:187], v[168:171]
	v_mfma_f32_16x16x32_bf16 v[172:175], v[92:95], v[192:195], v[172:175]
	v_mfma_f32_16x16x32_bf16 v[176:179], v[144:147], v[192:195], v[176:179]
	v_mfma_f32_16x16x32_bf16 v[0:3], v[92:95], v[200:203], v[0:3]
	v_mfma_f32_16x16x32_bf16 v[4:7], v[144:147], v[200:203], v[4:7]
	s_nop 0
	s_barrier
	s_add_u32 s50, s42, 0x10180
	s_addc_u32 s51, s43, 0
	s_add_i32 s42, s49, s5
	v_lshl_add_u64 v[88:89], s[50:51], 0, v[106:107]
	s_mov_b32 m0, s42
	s_add_i32 s20, s42, 0x2000
	global_load_lds_dwordx4 v[88:89], off
	v_lshl_add_u64 v[88:89], s[50:51], 0, v[104:105]
	s_mov_b32 m0, s20
	s_nop 0
	global_load_lds_dwordx4 v[88:89], off
	s_waitcnt vmcnt(6)
	s_barrier
	s_nop 0
	v_mfma_f32_16x16x32_bf16 v[8:11], v[204:207], v[148:151], v[8:11]
	v_mfma_f32_16x16x32_bf16 v[12:15], v[212:215], v[148:151], v[12:15]
	v_mfma_f32_16x16x32_bf16 v[44:47], v[204:207], v[180:183], v[44:47]
	v_mfma_f32_16x16x32_bf16 v[88:91], v[212:215], v[180:183], v[100:103]
	v_mfma_f32_16x16x32_bf16 v[92:95], v[204:207], v[188:191], v[116:119]
	v_mfma_f32_16x16x32_bf16 v[100:103], v[212:215], v[188:191], v[120:123]
	v_mfma_f32_16x16x32_bf16 v[80:83], v[204:207], v[196:199], v[80:83]
	v_mfma_f32_16x16x32_bf16 v[84:87], v[212:215], v[196:199], v[84:87]
	v_mfma_f32_16x16x32_bf16 v[8:11], v[208:211], v[152:155], v[8:11]
	v_mfma_f32_16x16x32_bf16 v[12:15], v[216:219], v[152:155], v[12:15]
	v_mfma_f32_16x16x32_bf16 v[44:47], v[208:211], v[184:187], v[44:47]
	v_mfma_f32_16x16x32_bf16 v[88:91], v[216:219], v[184:187], v[88:91]
	v_mfma_f32_16x16x32_bf16 v[92:95], v[208:211], v[192:195], v[92:95]
	v_mfma_f32_16x16x32_bf16 v[100:103], v[216:219], v[192:195], v[100:103]
	v_mfma_f32_16x16x32_bf16 v[80:83], v[208:211], v[200:203], v[80:83]
	v_mfma_f32_16x16x32_bf16 v[84:87], v[216:219], v[200:203], v[84:87]
	s_nop 0
	s_barrier
	ds_read_b128 v[116:119], v115
	ds_read_b128 v[120:123], v115 offset:1024
	ds_read_b128 v[124:127], v115 offset:2048
	ds_read_b128 v[144:147], v115 offset:3072
	s_add_u32 s40, s40, 0x10180
	s_addc_u32 s41, s41, 0
	s_mov_b32 m0, s92
	v_lshl_add_u64 v[130:131], s[40:41], 0, v[106:107]
	ds_read_b128 v[148:151], v114
	ds_read_b128 v[152:155], v114 offset:1024
	ds_read_b128 v[180:183], v114 offset:2048
	ds_read_b128 v[184:187], v114 offset:3072
	ds_read_b128 v[188:191], v114 offset:4096
	ds_read_b128 v[192:195], v114 offset:5120
	ds_read_b128 v[196:199], v114 offset:6144
	ds_read_b128 v[200:203], v114 offset:7168
	global_load_lds_dwordx4 v[130:131], off
	v_lshl_add_u64 v[130:131], s[40:41], 0, v[104:105]
	s_mov_b32 m0, s1
	s_nop 0
	global_load_lds_dwordx4 v[130:131], off
	s_waitcnt lgkmcnt(8)
	s_barrier
	s_waitcnt lgkmcnt(0)
	s_nop 0
	s_waitcnt lgkmcnt(0)
	v_mfma_f32_16x16x32_bf16 v[64:67], v[116:119], v[188:191], v[64:67]
	v_mfma_f32_16x16x32_bf16 v[204:207], v[120:123], v[192:195], v[64:67]
	v_mfma_f32_16x16x32_bf16 v[64:67], v[124:127], v[188:191], v[68:71]
	v_mfma_f32_16x16x32_bf16 v[68:71], v[144:147], v[192:195], v[64:67]
	v_mfma_f32_16x16x32_bf16 v[64:67], v[116:119], v[196:199], v[72:75]
	v_mfma_f32_16x16x32_bf16 v[48:51], v[116:119], v[148:151], v[48:51]
	v_mfma_f32_16x16x32_bf16 v[52:55], v[124:127], v[148:151], v[52:55]
	v_mfma_f32_16x16x32_bf16 v[56:59], v[116:119], v[180:183], v[56:59]
	v_mfma_f32_16x16x32_bf16 v[60:63], v[124:127], v[180:183], v[60:63]
	v_mfma_f32_16x16x32_bf16 v[72:75], v[120:123], v[200:203], v[64:67]
	v_mfma_f32_16x16x32_bf16 v[64:67], v[124:127], v[196:199], v[76:79]
	v_mfma_f32_16x16x32_bf16 v[48:51], v[120:123], v[152:155], v[48:51]
	v_mfma_f32_16x16x32_bf16 v[52:55], v[144:147], v[152:155], v[52:55]
	v_mfma_f32_16x16x32_bf16 v[56:59], v[120:123], v[184:187], v[56:59]
	v_mfma_f32_16x16x32_bf16 v[60:63], v[144:147], v[184:187], v[60:63]
	v_mfma_f32_16x16x32_bf16 v[76:79], v[144:147], v[200:203], v[64:67]
	s_nop 0
	s_barrier
	s_mov_b32 m0, s47
	v_lshl_add_u64 v[240:241], s[14:15], 0, v[106:107]
	ds_read_b128 v[64:67], v128
	ds_read_b128 v[208:211], v128 offset:1024
	ds_read_b128 v[212:215], v128 offset:2048
	ds_read_b128 v[216:219], v128 offset:3072
	global_load_lds_dwordx4 v[240:241], off
	v_lshl_add_u64 v[232:233], s[14:15], 0, v[104:105]
	s_mov_b32 m0, s13
	s_nop 0
	global_load_lds_dwordx4 v[232:233], off
	s_barrier
	s_waitcnt lgkmcnt(0)
	s_nop 0
	s_waitcnt lgkmcnt(0)
	v_mfma_f32_16x16x32_bf16 v[16:19], v[212:215], v[148:151], v[16:19]
	v_mfma_f32_16x16x32_bf16 v[96:99], v[64:67], v[148:151], v[96:99]
	v_mfma_f32_16x16x32_bf16 v[148:151], v[216:219], v[152:155], v[16:19]
	v_mfma_f32_16x16x32_bf16 v[16:19], v[64:67], v[180:183], v[20:23]
	v_mfma_f32_16x16x32_bf16 v[20:23], v[208:211], v[184:187], v[16:19]
	v_mfma_f32_16x16x32_bf16 v[16:19], v[212:215], v[180:183], v[24:27]
	v_mfma_f32_16x16x32_bf16 v[24:27], v[216:219], v[184:187], v[16:19]
	v_mfma_f32_16x16x32_bf16 v[16:19], v[64:67], v[188:191], v[28:31]
	v_mfma_f32_16x16x32_bf16 v[28:31], v[208:211], v[192:195], v[16:19]
	v_mfma_f32_16x16x32_bf16 v[16:19], v[212:215], v[188:191], v[32:35]
	v_mfma_f32_16x16x32_bf16 v[220:223], v[208:211], v[152:155], v[96:99]
	v_mfma_f32_16x16x32_bf16 v[152:155], v[216:219], v[192:195], v[16:19]
	v_mfma_f32_16x16x32_bf16 v[16:19], v[64:67], v[196:199], v[36:39]
	v_mfma_f32_16x16x32_bf16 v[180:183], v[208:211], v[200:203], v[16:19]
	v_mfma_f32_16x16x32_bf16 v[16:19], v[212:215], v[196:199], v[40:43]
	v_mfma_f32_16x16x32_bf16 v[40:43], v[216:219], v[200:203], v[16:19]
	s_nop 0
	s_mov_b32 m0, s16
	v_lshl_add_u64 v[138:139], s[44:45], 0, v[106:107]
	s_barrier
	s_nop 2
	ds_read_b128 v[16:19], v114 offset:16384
	ds_read_b128 v[32:35], v114 offset:17408
	ds_read_b128 v[36:39], v114 offset:18432
	ds_read_b128 v[96:99], v114 offset:19456
	ds_read_b128 v[184:187], v114 offset:20480
	ds_read_b128 v[188:191], v114 offset:21504
	ds_read_b128 v[192:195], v114 offset:22528
	ds_read_b128 v[196:199], v114 offset:23552
	global_load_lds_dwordx4 v[138:139], off
	v_lshl_add_u64 v[140:141], s[44:45], 0, v[104:105]
	s_mov_b32 m0, s17
	s_nop 0
	global_load_lds_dwordx4 v[140:141], off
	s_barrier
	s_waitcnt lgkmcnt(0)
	s_nop 0
	s_waitcnt lgkmcnt(0)
	v_mfma_f32_16x16x32_bf16 v[0:3], v[116:119], v[192:195], v[0:3]
	v_mfma_f32_16x16x32_bf16 v[156:159], v[116:119], v[16:19], v[156:159]
	v_mfma_f32_16x16x32_bf16 v[160:163], v[124:127], v[16:19], v[160:163]
	v_mfma_f32_16x16x32_bf16 v[164:167], v[116:119], v[36:39], v[164:167]
	v_mfma_f32_16x16x32_bf16 v[168:171], v[124:127], v[36:39], v[168:171]
	v_mfma_f32_16x16x32_bf16 v[172:175], v[116:119], v[184:187], v[172:175]
	v_mfma_f32_16x16x32_bf16 v[176:179], v[124:127], v[184:187], v[176:179]
	v_mfma_f32_16x16x32_bf16 v[116:119], v[120:123], v[196:199], v[0:3]
	v_mfma_f32_16x16x32_bf16 v[0:3], v[124:127], v[192:195], v[4:7]
	v_mfma_f32_16x16x32_bf16 v[156:159], v[120:123], v[32:35], v[156:159]
	v_mfma_f32_16x16x32_bf16 v[160:163], v[144:147], v[32:35], v[160:163]
	v_mfma_f32_16x16x32_bf16 v[164:167], v[120:123], v[96:99], v[164:167]
	v_mfma_f32_16x16x32_bf16 v[168:171], v[144:147], v[96:99], v[168:171]
	v_mfma_f32_16x16x32_bf16 v[172:175], v[120:123], v[188:191], v[172:175]
	v_mfma_f32_16x16x32_bf16 v[176:179], v[144:147], v[188:191], v[176:179]
	v_mfma_f32_16x16x32_bf16 v[120:123], v[144:147], v[196:199], v[0:3]
	s_nop 0
	s_barrier
	s_add_u32 s40, s14, 0x10000
	s_addc_u32 s41, s15, 0
	s_mov_b32 m0, vcc_lo
	v_lshl_add_u64 v[0:1], s[40:41], 0, v[106:107]
	global_load_lds_dwordx4 v[0:1], off
	v_lshl_add_u64 v[0:1], s[40:41], 0, v[104:105]
	s_mov_b32 m0, s31
	s_nop 0
	global_load_lds_dwordx4 v[0:1], off
	s_waitcnt vmcnt(6)
	s_barrier
	s_nop 0
	v_mfma_f32_16x16x32_bf16 v[0:3], v[64:67], v[16:19], v[8:11]
	v_mfma_f32_16x16x32_bf16 v[124:127], v[208:211], v[32:35], v[0:3]
	v_mfma_f32_16x16x32_bf16 v[0:3], v[212:215], v[16:19], v[12:15]
	v_mfma_f32_16x16x32_bf16 v[12:15], v[216:219], v[32:35], v[0:3]
	v_mfma_f32_16x16x32_bf16 v[0:3], v[64:67], v[36:39], v[44:47]
	v_mfma_f32_16x16x32_bf16 v[44:47], v[208:211], v[96:99], v[0:3]
	v_mfma_f32_16x16x32_bf16 v[0:3], v[212:215], v[36:39], v[88:91]
	v_mfma_f32_16x16x32_bf16 v[144:147], v[216:219], v[96:99], v[0:3]
	v_mfma_f32_16x16x32_bf16 v[0:3], v[64:67], v[184:187], v[92:95]
	v_mfma_f32_16x16x32_bf16 v[200:203], v[208:211], v[188:191], v[0:3]
	v_mfma_f32_16x16x32_bf16 v[0:3], v[212:215], v[184:187], v[100:103]
	v_mfma_f32_16x16x32_bf16 v[184:187], v[216:219], v[188:191], v[0:3]
	v_mfma_f32_16x16x32_bf16 v[0:3], v[64:67], v[192:195], v[80:83]
	v_mfma_f32_16x16x32_bf16 v[188:191], v[208:211], v[196:199], v[0:3]
	v_mfma_f32_16x16x32_bf16 v[0:3], v[212:215], v[192:195], v[84:87]
	v_mfma_f32_16x16x32_bf16 v[192:195], v[216:219], v[196:199], v[0:3]
	s_nop 0
	s_barrier
	ds_read_b128 v[8:11], v143
	ds_read_b128 v[92:95], v143 offset:1024
	ds_read_b128 v[196:199], v143 offset:2048
	ds_read_b128 v[208:211], v143 offset:3072
	s_add_u32 s40, s44, 0x10000
	s_addc_u32 s41, s45, 0
	s_mov_b32 m0, s36
	v_lshl_add_u64 v[0:1], s[40:41], 0, v[106:107]
	ds_read_b128 v[4:7], v114 offset:32768
	ds_read_b128 v[36:39], v114 offset:33792
	ds_read_b128 v[88:91], v114 offset:34816
	ds_read_b128 v[212:215], v114 offset:35840
	ds_read_b128 v[216:219], v114 offset:36864
	ds_read_b128 v[224:227], v114 offset:37888
	ds_read_b128 v[228:231], v114 offset:38912
	ds_read_b128 v[244:247], v114 offset:39936
	global_load_lds_dwordx4 v[0:1], off
	v_lshl_add_u64 v[0:1], s[40:41], 0, v[104:105]
	s_mov_b32 m0, s37
	s_nop 0
	global_load_lds_dwordx4 v[0:1], off
	s_waitcnt lgkmcnt(8)
	s_barrier
	s_waitcnt lgkmcnt(0)
	s_nop 0
	s_waitcnt lgkmcnt(0)
	v_mfma_f32_16x16x32_bf16 v[0:3], v[8:11], v[4:7], v[48:51]
	v_mfma_f32_16x16x32_bf16 v[248:251], v[92:95], v[36:39], v[0:3]
	v_mfma_f32_16x16x32_bf16 v[0:3], v[196:199], v[4:7], v[52:55]
	v_mfma_f32_16x16x32_bf16 v[96:99], v[208:211], v[36:39], v[0:3]
	v_mfma_f32_16x16x32_bf16 v[0:3], v[8:11], v[88:91], v[56:59]
	v_mfma_f32_16x16x32_bf16 v[80:83], v[92:95], v[212:215], v[0:3]
	v_mfma_f32_16x16x32_bf16 v[0:3], v[196:199], v[88:91], v[60:63]
	v_mfma_f32_16x16x32_bf16 v[64:67], v[208:211], v[212:215], v[0:3]
	v_mfma_f32_16x16x32_bf16 v[0:3], v[8:11], v[216:219], v[204:207]
	v_mfma_f32_16x16x32_bf16 v[48:51], v[92:95], v[224:227], v[0:3]
	v_mfma_f32_16x16x32_bf16 v[0:3], v[196:199], v[216:219], v[68:71]
	v_mfma_f32_16x16x32_bf16 v[32:35], v[208:211], v[224:227], v[0:3]
	v_mfma_f32_16x16x32_bf16 v[0:3], v[8:11], v[228:231], v[72:75]
	v_mfma_f32_16x16x32_bf16 v[16:19], v[92:95], v[244:247], v[0:3]
	v_mfma_f32_16x16x32_bf16 v[0:3], v[196:199], v[228:231], v[76:79]
	v_mfma_f32_16x16x32_bf16 v[0:3], v[208:211], v[244:247], v[0:3]
	s_nop 0
	s_barrier
	s_mov_b32 m0, s48
	v_lshl_add_u64 v[52:53], v[240:241], 0, s[28:29]
	ds_read_b128 v[204:207], v242
	ds_read_b128 v[236:239], v242 offset:1024
	ds_read_b128 v[130:133], v242 offset:2048
	ds_read_b128 v[134:137], v242 offset:3072
	global_load_lds_dwordx4 v[52:53], off
	v_lshl_add_u64 v[52:53], v[232:233], 0, s[28:29]
	s_mov_b32 m0, vcc_hi
	s_nop 0
	global_load_lds_dwordx4 v[52:53], off
	s_barrier
	s_waitcnt lgkmcnt(0)
	s_nop 0
	s_waitcnt lgkmcnt(0)
	v_mfma_f32_16x16x32_bf16 v[52:55], v[204:207], v[4:7], v[220:223]
	v_mfma_f32_16x16x32_bf16 v[4:7], v[130:133], v[4:7], v[148:151]
	v_mfma_f32_16x16x32_bf16 v[100:103], v[134:137], v[36:39], v[4:7]
	v_mfma_f32_16x16x32_bf16 v[4:7], v[204:207], v[88:91], v[20:23]
	v_mfma_f32_16x16x32_bf16 v[84:87], v[236:239], v[212:215], v[4:7]
	v_mfma_f32_16x16x32_bf16 v[4:7], v[130:133], v[88:91], v[24:27]
	v_mfma_f32_16x16x32_bf16 v[68:71], v[134:137], v[212:215], v[4:7]
	v_mfma_f32_16x16x32_bf16 v[4:7], v[204:207], v[216:219], v[28:31]
	v_mfma_f32_16x16x32_bf16 v[220:223], v[236:239], v[36:39], v[52:55]
	v_mfma_f32_16x16x32_bf16 v[52:55], v[236:239], v[224:227], v[4:7]
	v_mfma_f32_16x16x32_bf16 v[4:7], v[130:133], v[216:219], v[152:155]
	v_mfma_f32_16x16x32_bf16 v[36:39], v[134:137], v[224:227], v[4:7]
	v_mfma_f32_16x16x32_bf16 v[4:7], v[204:207], v[228:231], v[180:183]
	v_mfma_f32_16x16x32_bf16 v[20:23], v[236:239], v[244:247], v[4:7]
	v_mfma_f32_16x16x32_bf16 v[4:7], v[130:133], v[228:231], v[40:43]
	v_mfma_f32_16x16x32_bf16 v[4:7], v[134:137], v[244:247], v[4:7]
	s_nop 0
	s_mov_b32 m0, s24
	v_lshl_add_u64 v[24:25], v[138:139], 0, s[28:29]
	s_barrier
	ds_read_b128 v[28:31], v114 offset:49152
	ds_read_b128 v[60:63], v114 offset:50176
	ds_read_b128 v[76:79], v114 offset:51200
	ds_read_b128 v[148:151], v114 offset:52224
	ds_read_b128 v[152:155], v114 offset:53248
	ds_read_b128 v[180:183], v114 offset:54272
	ds_read_b128 v[212:215], v114 offset:55296
	ds_read_b128 v[216:219], v114 offset:56320
	global_load_lds_dwordx4 v[24:25], off
	v_lshl_add_u64 v[24:25], v[140:141], 0, s[28:29]
	s_mov_b32 m0, s25
	s_nop 0
	global_load_lds_dwordx4 v[24:25], off
	s_barrier
	s_waitcnt lgkmcnt(0)
	s_nop 0
	s_waitcnt lgkmcnt(0)
	v_mfma_f32_16x16x32_bf16 v[24:27], v[8:11], v[28:31], v[156:159]
	v_mfma_f32_16x16x32_bf16 v[156:159], v[92:95], v[60:63], v[24:27]
	v_mfma_f32_16x16x32_bf16 v[24:27], v[196:199], v[28:31], v[160:163]
	v_mfma_f32_16x16x32_bf16 v[160:163], v[208:211], v[60:63], v[24:27]
	v_mfma_f32_16x16x32_bf16 v[24:27], v[8:11], v[76:79], v[164:167]
	v_mfma_f32_16x16x32_bf16 v[88:91], v[92:95], v[148:151], v[24:27]
	v_mfma_f32_16x16x32_bf16 v[24:27], v[196:199], v[76:79], v[168:171]
	v_mfma_f32_16x16x32_bf16 v[72:75], v[208:211], v[148:151], v[24:27]
	v_mfma_f32_16x16x32_bf16 v[24:27], v[8:11], v[152:155], v[172:175]
	v_mfma_f32_16x16x32_bf16 v[56:59], v[92:95], v[180:183], v[24:27]
	v_mfma_f32_16x16x32_bf16 v[24:27], v[196:199], v[152:155], v[176:179]
	v_mfma_f32_16x16x32_bf16 v[8:11], v[8:11], v[212:215], v[116:119]
	v_mfma_f32_16x16x32_bf16 v[40:43], v[208:211], v[180:183], v[24:27]
	v_mfma_f32_16x16x32_bf16 v[24:27], v[92:95], v[216:219], v[8:11]
	v_mfma_f32_16x16x32_bf16 v[8:11], v[196:199], v[212:215], v[120:123]
	v_mfma_f32_16x16x32_bf16 v[8:11], v[208:211], v[216:219], v[8:11]
	s_nop 0
	s_barrier
	s_add_u32 s14, s14, 0x10080
	s_addc_u32 s15, s15, 0
	s_mov_b32 m0, s42
	v_lshl_add_u64 v[92:93], s[14:15], 0, v[106:107]
	global_load_lds_dwordx4 v[92:93], off
	v_lshl_add_u64 v[92:93], s[14:15], 0, v[104:105]
	s_mov_b32 m0, s20
	s_nop 0
	global_load_lds_dwordx4 v[92:93], off
	s_waitcnt vmcnt(6)
	s_barrier
	s_nop 0
	v_mfma_f32_16x16x32_bf16 v[12:15], v[130:133], v[28:31], v[12:15]
	v_mfma_f32_16x16x32_bf16 v[92:95], v[204:207], v[28:31], v[124:127]
	v_mfma_f32_16x16x32_bf16 v[120:123], v[134:137], v[60:63], v[12:15]
	v_mfma_f32_16x16x32_bf16 v[12:15], v[204:207], v[76:79], v[44:47]
	v_mfma_f32_16x16x32_bf16 v[116:119], v[236:239], v[60:63], v[92:95]
	v_mfma_f32_16x16x32_bf16 v[92:95], v[236:239], v[148:151], v[12:15]
	v_mfma_f32_16x16x32_bf16 v[12:15], v[130:133], v[76:79], v[144:147]
	v_mfma_f32_16x16x32_bf16 v[76:79], v[134:137], v[148:151], v[12:15]
	v_mfma_f32_16x16x32_bf16 v[12:15], v[204:207], v[152:155], v[200:203]
	v_mfma_f32_16x16x32_bf16 v[60:63], v[236:239], v[180:183], v[12:15]
	v_mfma_f32_16x16x32_bf16 v[12:15], v[130:133], v[152:155], v[184:187]
	v_mfma_f32_16x16x32_bf16 v[44:47], v[134:137], v[180:183], v[12:15]
	v_mfma_f32_16x16x32_bf16 v[12:15], v[204:207], v[212:215], v[188:191]
	v_mfma_f32_16x16x32_bf16 v[28:31], v[236:239], v[216:219], v[12:15]
	v_mfma_f32_16x16x32_bf16 v[12:15], v[130:133], v[212:215], v[192:195]
	v_mfma_f32_16x16x32_bf16 v[12:15], v[134:137], v[216:219], v[12:15]
	s_branch .Lfa1_x
	s_nop 0
	s_nop 0
	s_nop 0
	s_nop 0
	s_nop 0
	s_nop 0
	s_nop 0
	s_nop 0
	s_nop 0
	s_nop 0
	s_nop 0
	s_nop 0
	s_nop 0
	s_nop 0
	s_nop 0
	s_nop 0
	s_nop 0
	s_nop 0
	s_nop 0
	s_nop 0

.LBB0_73:
	s_ashr_i32 s31, s30, 31
	s_lshl_b64 s[14:15], s[30:31], 17
	v_readlane_b32 s40, v254, 29
	v_mov_b64_e32 v[0:1], 0x400
	v_readlane_b32 s41, v254, 30
	s_add_u32 s40, s40, s14
	v_cmp_lt_i64_e32 vcc, s[8:9], v[0:1]
	s_addc_u32 s41, s41, s15
	s_and_b64 s[14:15], vcc, exec
	s_cselect_b32 s45, s41, s35
	s_cselect_b32 s44, s40, s34
	s_ashr_i32 s13, s12, 31
	s_lshl_b64 s[14:15], s[12:13], 17
	s_add_u32 s42, s96, s14
	s_addc_u32 s43, s97, s15
	s_and_b64 s[14:15], vcc, exec
	s_cselect_b32 s15, s43, s19
	s_cselect_b32 s14, s42, s18
	s_add_i32 vcc_hi, 16, 0x10000
	v_add_u32_e32 v107, vcc_hi, v101
	ds_read_b128 v[0:3], v107
	ds_read_b128 v[4:7], v107 offset:1024
	ds_read_b128 v[8:11], v107 offset:2048
	ds_read_b128 v[12:15], v107 offset:3072
	v_mov_b64_e32 v[250:251], 0x300
	v_mov_b64_e32 v[248:249], 0x2ff
	s_add_u32 s48, s34, 0x10080
	s_addc_u32 s49, s35, 0
	s_add_i32 s16, s20, 0xc000
	v_lshl_add_u64 v[48:49], s[48:49], 0, v[98:99]
	s_mov_b32 m0, s16
	s_add_i32 s13, s20, 0xe000
	ds_read_b128 v[16:19], v106
	ds_read_b128 v[20:23], v106 offset:1024
	ds_read_b128 v[24:27], v106 offset:2048
	ds_read_b128 v[28:31], v106 offset:3072
	ds_read_b128 v[32:35], v106 offset:4096
	ds_read_b128 v[36:39], v106 offset:5120
	ds_read_b128 v[40:43], v106 offset:6144
	ds_read_b128 v[44:47], v106 offset:7168
	global_load_lds_dwordx4 v[48:49], off
	v_lshl_add_u64 v[48:49], s[48:49], 0, v[96:97]
	s_mov_b32 m0, s13
	s_nop 0
	global_load_lds_dwordx4 v[48:49], off
	s_waitcnt lgkmcnt(8)
	s_barrier
	s_waitcnt lgkmcnt(0)
	s_nop 0
	s_waitcnt lgkmcnt(0)
	v_mfma_f32_16x16x32_bf16 v[48:51], v[0:3], v[16:19], 0
	v_mfma_f32_16x16x32_bf16 v[52:55], v[8:11], v[16:19], 0
	v_mfma_f32_16x16x32_bf16 v[56:59], v[0:3], v[24:27], 0
	v_mfma_f32_16x16x32_bf16 v[60:63], v[8:11], v[24:27], 0
	v_mfma_f32_16x16x32_bf16 v[64:67], v[0:3], v[32:35], 0
	v_mfma_f32_16x16x32_bf16 v[68:71], v[8:11], v[32:35], 0
	v_mfma_f32_16x16x32_bf16 v[72:75], v[0:3], v[40:43], 0
	v_mfma_f32_16x16x32_bf16 v[76:79], v[8:11], v[40:43], 0
	v_mfma_f32_16x16x32_bf16 v[48:51], v[4:7], v[20:23], v[48:51]
	v_mfma_f32_16x16x32_bf16 v[52:55], v[12:15], v[20:23], v[52:55]
	v_mfma_f32_16x16x32_bf16 v[56:59], v[4:7], v[28:31], v[56:59]
	v_mfma_f32_16x16x32_bf16 v[60:63], v[12:15], v[28:31], v[60:63]
	v_mfma_f32_16x16x32_bf16 v[64:67], v[4:7], v[36:39], v[64:67]
	v_mfma_f32_16x16x32_bf16 v[68:71], v[12:15], v[36:39], v[68:71]
	v_mfma_f32_16x16x32_bf16 v[72:75], v[4:7], v[44:47], v[72:75]
	v_mfma_f32_16x16x32_bf16 v[76:79], v[12:15], v[44:47], v[76:79]
	s_nop 0
	s_barrier
	s_add_i32 vcc_lo, 16, 0x14000
	v_lshl_add_u64 v[138:139], s[18:19], 0, v[98:99]
	s_mov_b64 s[48:49], 0x100
	s_add_i32 vcc_hi, vcc_hi, s5
	v_add_u32_e32 v128, vcc_lo, v101
	v_lshl_add_u64 v[108:109], v[138:139], 0, s[48:49]
	s_mov_b32 m0, vcc_hi
	v_lshl_add_u64 v[140:141], s[18:19], 0, v[96:97]
	s_add_i32 s31, vcc_hi, 0x2000
	ds_read_b128 v[80:83], v128
	ds_read_b128 v[84:87], v128 offset:1024
	ds_read_b128 v[88:91], v128 offset:2048
	ds_read_b128 v[92:95], v128 offset:3072
	global_load_lds_dwordx4 v[108:109], off
	v_lshl_add_u64 v[108:109], v[140:141], 0, s[48:49]
	s_mov_b32 m0, s31
	s_nop 0
	global_load_lds_dwordx4 v[108:109], off
	s_barrier
	s_waitcnt lgkmcnt(0)
	s_nop 0
	s_waitcnt lgkmcnt(0)
	v_mfma_f32_16x16x32_bf16 v[108:111], v[80:83], v[16:19], 0
	v_mfma_f32_16x16x32_bf16 v[16:19], v[88:91], v[16:19], 0
	v_mfma_f32_16x16x32_bf16 v[108:111], v[84:87], v[20:23], v[108:111]
	v_mfma_f32_16x16x32_bf16 v[16:19], v[92:95], v[20:23], v[16:19]
	v_mfma_f32_16x16x32_bf16 v[20:23], v[80:83], v[24:27], 0
	v_mfma_f32_16x16x32_bf16 v[24:27], v[88:91], v[24:27], 0
	v_mfma_f32_16x16x32_bf16 v[20:23], v[84:87], v[28:31], v[20:23]
	v_mfma_f32_16x16x32_bf16 v[24:27], v[92:95], v[28:31], v[24:27]
	v_mfma_f32_16x16x32_bf16 v[28:31], v[80:83], v[32:35], 0
	v_mfma_f32_16x16x32_bf16 v[32:35], v[88:91], v[32:35], 0
	v_mfma_f32_16x16x32_bf16 v[28:31], v[84:87], v[36:39], v[28:31]
	v_mfma_f32_16x16x32_bf16 v[32:35], v[92:95], v[36:39], v[32:35]
	v_mfma_f32_16x16x32_bf16 v[36:39], v[80:83], v[40:43], 0
	v_mfma_f32_16x16x32_bf16 v[40:43], v[88:91], v[40:43], 0
	v_mfma_f32_16x16x32_bf16 v[36:39], v[84:87], v[44:47], v[36:39]
	v_mfma_f32_16x16x32_bf16 v[40:43], v[92:95], v[44:47], v[40:43]
	s_nop 0
	v_lshl_add_u64 v[212:213], s[34:35], 0, v[98:99]
	s_mov_b32 m0, s20
	v_lshl_add_u64 v[148:149], v[212:213], 0, s[48:49]
	v_lshl_add_u64 v[214:215], s[34:35], 0, v[96:97]
	s_barrier
	ds_read_b128 v[44:47], v106 offset:16384
	ds_read_b128 v[112:115], v106 offset:17408
	ds_read_b128 v[116:119], v106 offset:18432
	ds_read_b128 v[120:123], v106 offset:19456
	ds_read_b128 v[124:127], v106 offset:20480
	ds_read_b128 v[130:133], v106 offset:21504
	ds_read_b128 v[134:137], v106 offset:22528
	ds_read_b128 v[144:147], v106 offset:23552
	global_load_lds_dwordx4 v[148:149], off
	v_lshl_add_u64 v[148:149], v[214:215], 0, s[48:49]
	s_mov_b32 m0, s17
	s_nop 0
	global_load_lds_dwordx4 v[148:149], off
	s_barrier
	s_waitcnt lgkmcnt(0)
	s_nop 0
	s_waitcnt lgkmcnt(0)
	v_mfma_f32_16x16x32_bf16 v[148:151], v[0:3], v[44:47], 0
	v_mfma_f32_16x16x32_bf16 v[156:159], v[0:3], v[116:119], 0
	v_mfma_f32_16x16x32_bf16 v[164:167], v[0:3], v[124:127], 0
	v_mfma_f32_16x16x32_bf16 v[0:3], v[0:3], v[134:137], 0
	v_mfma_f32_16x16x32_bf16 v[148:151], v[4:7], v[112:115], v[148:151]
	v_mfma_f32_16x16x32_bf16 v[152:155], v[8:11], v[44:47], 0
	v_mfma_f32_16x16x32_bf16 v[156:159], v[4:7], v[120:123], v[156:159]
	v_mfma_f32_16x16x32_bf16 v[160:163], v[8:11], v[116:119], 0
	v_mfma_f32_16x16x32_bf16 v[164:167], v[4:7], v[130:133], v[164:167]
	v_mfma_f32_16x16x32_bf16 v[168:171], v[8:11], v[124:127], 0
	v_mfma_f32_16x16x32_bf16 v[0:3], v[4:7], v[144:147], v[0:3]
	v_mfma_f32_16x16x32_bf16 v[4:7], v[8:11], v[134:137], 0
	v_mfma_f32_16x16x32_bf16 v[152:155], v[12:15], v[112:115], v[152:155]
	v_mfma_f32_16x16x32_bf16 v[160:163], v[12:15], v[120:123], v[160:163]
	v_mfma_f32_16x16x32_bf16 v[168:171], v[12:15], v[130:133], v[168:171]
	v_mfma_f32_16x16x32_bf16 v[4:7], v[12:15], v[144:147], v[4:7]
	s_nop 0
	s_barrier
	s_add_u32 s48, s18, 0x10100
	s_addc_u32 s49, s19, 0
	s_add_i32 vcc_lo, vcc_lo, s5
	v_lshl_add_u64 v[8:9], s[48:49], 0, v[98:99]
	s_mov_b32 m0, vcc_lo
	s_nop 0
	global_load_lds_dwordx4 v[8:9], off
	v_lshl_add_u64 v[8:9], s[48:49], 0, v[96:97]
	s_add_i32 s48, vcc_lo, 0x2000
	s_mov_b32 m0, s48
	s_nop 0
	global_load_lds_dwordx4 v[8:9], off
	s_waitcnt vmcnt(6)
	s_barrier
	s_nop 0
	v_mfma_f32_16x16x32_bf16 v[8:11], v[80:83], v[44:47], 0
	v_mfma_f32_16x16x32_bf16 v[12:15], v[88:91], v[44:47], 0
	v_mfma_f32_16x16x32_bf16 v[8:11], v[84:87], v[112:115], v[8:11]
	v_mfma_f32_16x16x32_bf16 v[12:15], v[92:95], v[112:115], v[12:15]
	v_mfma_f32_16x16x32_bf16 v[44:47], v[80:83], v[116:119], 0
	v_mfma_f32_16x16x32_bf16 v[112:115], v[88:91], v[116:119], 0
	v_mfma_f32_16x16x32_bf16 v[116:119], v[80:83], v[124:127], 0
	v_mfma_f32_16x16x32_bf16 v[80:83], v[80:83], v[134:137], 0
	v_mfma_f32_16x16x32_bf16 v[44:47], v[84:87], v[120:123], v[44:47]
	v_mfma_f32_16x16x32_bf16 v[112:115], v[92:95], v[120:123], v[112:115]
	v_mfma_f32_16x16x32_bf16 v[116:119], v[84:87], v[130:133], v[116:119]
	v_mfma_f32_16x16x32_bf16 v[120:123], v[88:91], v[124:127], 0
	v_mfma_f32_16x16x32_bf16 v[80:83], v[84:87], v[144:147], v[80:83]
	v_mfma_f32_16x16x32_bf16 v[84:87], v[88:91], v[134:137], 0
	v_mfma_f32_16x16x32_bf16 v[120:123], v[92:95], v[130:133], v[120:123]
	v_mfma_f32_16x16x32_bf16 v[84:87], v[92:95], v[144:147], v[84:87]
	s_nop 0
	s_add_i32 s49, 16, 0x18000
	v_add_u32_e32 v143, s49, v101
	s_barrier
	ds_read_b128 v[88:91], v143
	ds_read_b128 v[92:95], v143 offset:1024
	ds_read_b128 v[124:127], v143 offset:2048
	ds_read_b128 v[130:133], v143 offset:3072
	s_add_u32 s50, s34, 0x10100
	s_addc_u32 s51, s35, 0
	s_mov_b32 m0, s24
	v_lshl_add_u64 v[196:197], s[50:51], 0, v[98:99]
	ds_read_b128 v[134:137], v106 offset:32768
	ds_read_b128 v[144:147], v106 offset:33792
	ds_read_b128 v[172:175], v106 offset:34816
	ds_read_b128 v[176:179], v106 offset:35840
	ds_read_b128 v[180:183], v106 offset:36864
	ds_read_b128 v[184:187], v106 offset:37888
	ds_read_b128 v[188:191], v106 offset:38912
	ds_read_b128 v[192:195], v106 offset:39936
	global_load_lds_dwordx4 v[196:197], off
	v_lshl_add_u64 v[196:197], s[50:51], 0, v[96:97]
	s_mov_b32 m0, s25
	s_nop 0
	global_load_lds_dwordx4 v[196:197], off
	s_waitcnt lgkmcnt(8)
	s_barrier
	s_waitcnt lgkmcnt(0)
	s_nop 0
	s_waitcnt lgkmcnt(0)
	v_mfma_f32_16x16x32_bf16 v[48:51], v[88:91], v[134:137], v[48:51]
	v_mfma_f32_16x16x32_bf16 v[52:55], v[124:127], v[134:137], v[52:55]
	v_mfma_f32_16x16x32_bf16 v[56:59], v[88:91], v[172:175], v[56:59]
	v_mfma_f32_16x16x32_bf16 v[60:63], v[124:127], v[172:175], v[60:63]
	v_mfma_f32_16x16x32_bf16 v[64:67], v[88:91], v[180:183], v[64:67]
	v_mfma_f32_16x16x32_bf16 v[68:71], v[124:127], v[180:183], v[68:71]
	v_mfma_f32_16x16x32_bf16 v[72:75], v[88:91], v[188:191], v[72:75]
	v_mfma_f32_16x16x32_bf16 v[76:79], v[124:127], v[188:191], v[76:79]
	v_mfma_f32_16x16x32_bf16 v[48:51], v[92:95], v[144:147], v[48:51]
	v_mfma_f32_16x16x32_bf16 v[52:55], v[130:133], v[144:147], v[52:55]
	v_mfma_f32_16x16x32_bf16 v[56:59], v[92:95], v[176:179], v[56:59]
	v_mfma_f32_16x16x32_bf16 v[60:63], v[130:133], v[176:179], v[60:63]
	v_mfma_f32_16x16x32_bf16 v[64:67], v[92:95], v[184:187], v[64:67]
	v_mfma_f32_16x16x32_bf16 v[68:71], v[130:133], v[184:187], v[68:71]
	v_mfma_f32_16x16x32_bf16 v[72:75], v[92:95], v[192:195], v[72:75]
	v_mfma_f32_16x16x32_bf16 v[76:79], v[130:133], v[192:195], v[76:79]
	s_nop 0
	s_barrier
	s_add_i32 s51, 16, 0x1c000
	s_mov_b64 s[52:53], 0x180
	s_add_i32 s50, s49, s5
	v_add_u32_e32 v236, s51, v101
	v_lshl_add_u64 v[138:139], v[138:139], 0, s[52:53]
	s_mov_b32 m0, s50
	s_add_i32 s49, s50, 0x2000
	ds_read_b128 v[196:199], v236
	ds_read_b128 v[200:203], v236 offset:1024
	ds_read_b128 v[204:207], v236 offset:2048
	ds_read_b128 v[208:211], v236 offset:3072
	global_load_lds_dwordx4 v[138:139], off
	v_lshl_add_u64 v[138:139], v[140:141], 0, s[52:53]
	s_mov_b32 m0, s49
	s_nop 0
	global_load_lds_dwordx4 v[138:139], off
	s_barrier
	s_waitcnt lgkmcnt(0)
	s_nop 0
	s_waitcnt lgkmcnt(0)
	v_mfma_f32_16x16x32_bf16 v[108:111], v[196:199], v[134:137], v[108:111]
	v_mfma_f32_16x16x32_bf16 v[16:19], v[204:207], v[134:137], v[16:19]
	v_mfma_f32_16x16x32_bf16 v[20:23], v[196:199], v[172:175], v[20:23]
	v_mfma_f32_16x16x32_bf16 v[24:27], v[204:207], v[172:175], v[24:27]
	v_mfma_f32_16x16x32_bf16 v[28:31], v[196:199], v[180:183], v[28:31]
	v_mfma_f32_16x16x32_bf16 v[32:35], v[204:207], v[180:183], v[32:35]
	v_mfma_f32_16x16x32_bf16 v[36:39], v[196:199], v[188:191], v[36:39]
	v_mfma_f32_16x16x32_bf16 v[40:43], v[204:207], v[188:191], v[40:43]
	v_mfma_f32_16x16x32_bf16 v[108:111], v[200:203], v[144:147], v[108:111]
	v_mfma_f32_16x16x32_bf16 v[16:19], v[208:211], v[144:147], v[16:19]
	v_mfma_f32_16x16x32_bf16 v[20:23], v[200:203], v[176:179], v[20:23]
	v_mfma_f32_16x16x32_bf16 v[24:27], v[208:211], v[176:179], v[24:27]
	v_mfma_f32_16x16x32_bf16 v[28:31], v[200:203], v[184:187], v[28:31]
	v_mfma_f32_16x16x32_bf16 v[32:35], v[208:211], v[184:187], v[32:35]
	v_mfma_f32_16x16x32_bf16 v[36:39], v[200:203], v[192:195], v[36:39]
	v_mfma_f32_16x16x32_bf16 v[40:43], v[208:211], v[192:195], v[40:43]
	s_nop 0
	s_mov_b32 m0, s36
	v_lshl_add_u64 v[138:139], v[212:213], 0, s[52:53]
	s_barrier
	ds_read_b128 v[134:137], v106 offset:49152
	ds_read_b128 v[144:147], v106 offset:50176
	ds_read_b128 v[172:175], v106 offset:51200
	ds_read_b128 v[176:179], v106 offset:52224
	ds_read_b128 v[180:183], v106 offset:53248
	ds_read_b128 v[184:187], v106 offset:54272
	ds_read_b128 v[188:191], v106 offset:55296
	ds_read_b128 v[192:195], v106 offset:56320
	global_load_lds_dwordx4 v[138:139], off
	v_lshl_add_u64 v[138:139], v[214:215], 0, s[52:53]
	s_mov_b32 m0, s37
	s_nop 0
	global_load_lds_dwordx4 v[138:139], off
	s_barrier
	s_waitcnt lgkmcnt(0)
	s_nop 0
	s_waitcnt lgkmcnt(0)
	v_mfma_f32_16x16x32_bf16 v[148:151], v[88:91], v[134:137], v[148:151]
	v_mfma_f32_16x16x32_bf16 v[152:155], v[124:127], v[134:137], v[152:155]
	v_mfma_f32_16x16x32_bf16 v[156:159], v[88:91], v[172:175], v[156:159]
	v_mfma_f32_16x16x32_bf16 v[160:163], v[124:127], v[172:175], v[160:163]
	v_mfma_f32_16x16x32_bf16 v[164:167], v[88:91], v[180:183], v[164:167]
	v_mfma_f32_16x16x32_bf16 v[168:171], v[124:127], v[180:183], v[168:171]
	v_mfma_f32_16x16x32_bf16 v[0:3], v[88:91], v[188:191], v[0:3]
	v_mfma_f32_16x16x32_bf16 v[4:7], v[124:127], v[188:191], v[4:7]
	v_mfma_f32_16x16x32_bf16 v[148:151], v[92:95], v[144:147], v[148:151]
	v_mfma_f32_16x16x32_bf16 v[152:155], v[130:133], v[144:147], v[152:155]
	v_mfma_f32_16x16x32_bf16 v[156:159], v[92:95], v[176:179], v[156:159]
	v_mfma_f32_16x16x32_bf16 v[160:163], v[130:133], v[176:179], v[160:163]
	v_mfma_f32_16x16x32_bf16 v[164:167], v[92:95], v[184:187], v[164:167]
	v_mfma_f32_16x16x32_bf16 v[168:171], v[130:133], v[184:187], v[168:171]
	v_mfma_f32_16x16x32_bf16 v[0:3], v[92:95], v[192:195], v[0:3]
	v_mfma_f32_16x16x32_bf16 v[4:7], v[130:133], v[192:195], v[4:7]
	s_nop 0
	s_barrier
	s_add_u32 s52, s18, 0x10180
	s_addc_u32 s53, s19, 0
	s_add_i32 s19, s51, s5
	v_lshl_add_u64 v[88:89], s[52:53], 0, v[98:99]
	s_mov_b32 m0, s19
	s_add_i32 s18, s19, 0x2000
	global_load_lds_dwordx4 v[88:89], off
	v_lshl_add_u64 v[88:89], s[52:53], 0, v[96:97]
	s_mov_b32 m0, s18
	s_nop 0
	global_load_lds_dwordx4 v[88:89], off
	s_waitcnt vmcnt(6)
	s_barrier
	s_nop 0
	v_mfma_f32_16x16x32_bf16 v[8:11], v[196:199], v[134:137], v[8:11]
	v_mfma_f32_16x16x32_bf16 v[12:15], v[204:207], v[134:137], v[12:15]
	v_mfma_f32_16x16x32_bf16 v[44:47], v[196:199], v[172:175], v[44:47]
	v_mfma_f32_16x16x32_bf16 v[88:91], v[204:207], v[172:175], v[112:115]
	v_mfma_f32_16x16x32_bf16 v[92:95], v[196:199], v[180:183], v[116:119]
	v_mfma_f32_16x16x32_bf16 v[112:115], v[204:207], v[180:183], v[120:123]
	v_mfma_f32_16x16x32_bf16 v[80:83], v[196:199], v[188:191], v[80:83]
	v_mfma_f32_16x16x32_bf16 v[84:87], v[204:207], v[188:191], v[84:87]
	v_mfma_f32_16x16x32_bf16 v[8:11], v[200:203], v[144:147], v[8:11]
	v_mfma_f32_16x16x32_bf16 v[12:15], v[208:211], v[144:147], v[12:15]
	v_mfma_f32_16x16x32_bf16 v[44:47], v[200:203], v[176:179], v[44:47]
	v_mfma_f32_16x16x32_bf16 v[88:91], v[208:211], v[176:179], v[88:91]
	v_mfma_f32_16x16x32_bf16 v[92:95], v[200:203], v[184:187], v[92:95]
	v_mfma_f32_16x16x32_bf16 v[112:115], v[208:211], v[184:187], v[112:115]
	v_mfma_f32_16x16x32_bf16 v[80:83], v[200:203], v[192:195], v[80:83]
	v_mfma_f32_16x16x32_bf16 v[84:87], v[208:211], v[192:195], v[84:87]
	s_nop 0
	s_barrier
	ds_read_b128 v[116:119], v107
	ds_read_b128 v[120:123], v107 offset:1024
	ds_read_b128 v[124:127], v107 offset:2048
	ds_read_b128 v[130:133], v107 offset:3072
	s_add_u32 s34, s34, 0x10180
	s_addc_u32 s35, s35, 0
	s_mov_b32 m0, s16
	v_lshl_add_u64 v[138:139], s[34:35], 0, v[98:99]
	ds_read_b128 v[134:137], v106
	ds_read_b128 v[144:147], v106 offset:1024
	ds_read_b128 v[172:175], v106 offset:2048
	ds_read_b128 v[176:179], v106 offset:3072
	ds_read_b128 v[180:183], v106 offset:4096
	ds_read_b128 v[184:187], v106 offset:5120
	ds_read_b128 v[188:191], v106 offset:6144
	ds_read_b128 v[192:195], v106 offset:7168
	global_load_lds_dwordx4 v[138:139], off
	v_lshl_add_u64 v[138:139], s[34:35], 0, v[96:97]
	s_mov_b32 m0, s13
	s_nop 0
	global_load_lds_dwordx4 v[138:139], off
	s_waitcnt lgkmcnt(8)
	s_barrier
	s_waitcnt lgkmcnt(0)
	s_nop 0
	s_waitcnt lgkmcnt(0)
	v_mfma_f32_16x16x32_bf16 v[64:67], v[116:119], v[180:183], v[64:67]
	v_mfma_f32_16x16x32_bf16 v[196:199], v[120:123], v[184:187], v[64:67]
	v_mfma_f32_16x16x32_bf16 v[64:67], v[124:127], v[180:183], v[68:71]
	v_mfma_f32_16x16x32_bf16 v[68:71], v[130:133], v[184:187], v[64:67]
	v_mfma_f32_16x16x32_bf16 v[64:67], v[116:119], v[188:191], v[72:75]
	v_mfma_f32_16x16x32_bf16 v[48:51], v[116:119], v[134:137], v[48:51]
	v_mfma_f32_16x16x32_bf16 v[52:55], v[124:127], v[134:137], v[52:55]
	v_mfma_f32_16x16x32_bf16 v[56:59], v[116:119], v[172:175], v[56:59]
	v_mfma_f32_16x16x32_bf16 v[60:63], v[124:127], v[172:175], v[60:63]
	v_mfma_f32_16x16x32_bf16 v[200:203], v[120:123], v[192:195], v[64:67]
	v_mfma_f32_16x16x32_bf16 v[64:67], v[124:127], v[188:191], v[76:79]
	v_mfma_f32_16x16x32_bf16 v[48:51], v[120:123], v[144:147], v[48:51]
	v_mfma_f32_16x16x32_bf16 v[52:55], v[130:133], v[144:147], v[52:55]
	v_mfma_f32_16x16x32_bf16 v[56:59], v[120:123], v[176:179], v[56:59]
	v_mfma_f32_16x16x32_bf16 v[60:63], v[130:133], v[176:179], v[60:63]
	v_mfma_f32_16x16x32_bf16 v[76:79], v[130:133], v[192:195], v[64:67]
	s_nop 0
	s_barrier
	s_mov_b32 m0, vcc_hi
	v_lshl_add_u64 v[138:139], s[14:15], 0, v[98:99]
	ds_read_b128 v[64:67], v128
	ds_read_b128 v[72:75], v128 offset:1024
	ds_read_b128 v[204:207], v128 offset:2048
	ds_read_b128 v[208:211], v128 offset:3072
	global_load_lds_dwordx4 v[138:139], off
	v_lshl_add_u64 v[140:141], s[14:15], 0, v[96:97]
	s_mov_b32 m0, s31
	s_nop 0
	global_load_lds_dwordx4 v[140:141], off
	s_barrier
	s_waitcnt lgkmcnt(0)
	s_nop 0
	s_waitcnt lgkmcnt(0)
	v_mfma_f32_16x16x32_bf16 v[32:35], v[204:207], v[180:183], v[32:35]
	v_mfma_f32_16x16x32_bf16 v[108:111], v[64:67], v[134:137], v[108:111]
	v_mfma_f32_16x16x32_bf16 v[16:19], v[204:207], v[134:137], v[16:19]
	v_mfma_f32_16x16x32_bf16 v[134:137], v[208:211], v[184:187], v[32:35]
	v_mfma_f32_16x16x32_bf16 v[32:35], v[64:67], v[188:191], v[36:39]
	v_mfma_f32_16x16x32_bf16 v[108:111], v[72:75], v[144:147], v[108:111]
	v_mfma_f32_16x16x32_bf16 v[16:19], v[208:211], v[144:147], v[16:19]
	v_mfma_f32_16x16x32_bf16 v[20:23], v[64:67], v[172:175], v[20:23]
	v_mfma_f32_16x16x32_bf16 v[24:27], v[204:207], v[172:175], v[24:27]
	v_mfma_f32_16x16x32_bf16 v[28:31], v[64:67], v[180:183], v[28:31]
	v_mfma_f32_16x16x32_bf16 v[144:147], v[72:75], v[192:195], v[32:35]
	v_mfma_f32_16x16x32_bf16 v[32:35], v[204:207], v[188:191], v[40:43]
	v_mfma_f32_16x16x32_bf16 v[20:23], v[72:75], v[176:179], v[20:23]
	v_mfma_f32_16x16x32_bf16 v[24:27], v[208:211], v[176:179], v[24:27]
	v_mfma_f32_16x16x32_bf16 v[28:31], v[72:75], v[184:187], v[28:31]
	v_mfma_f32_16x16x32_bf16 v[172:175], v[208:211], v[192:195], v[32:35]
	s_nop 0
	s_mov_b32 m0, s20
	v_lshl_add_u64 v[232:233], s[44:45], 0, v[98:99]
	s_barrier
	ds_read_b128 v[32:35], v106 offset:16384
	ds_read_b128 v[36:39], v106 offset:17408
	ds_read_b128 v[40:43], v106 offset:18432
	ds_read_b128 v[176:179], v106 offset:19456
	ds_read_b128 v[180:183], v106 offset:20480
	ds_read_b128 v[184:187], v106 offset:21504
	ds_read_b128 v[188:191], v106 offset:22528
	ds_read_b128 v[192:195], v106 offset:23552
	global_load_lds_dwordx4 v[232:233], off
	v_lshl_add_u64 v[240:241], s[44:45], 0, v[96:97]
	s_mov_b32 m0, s17
	s_nop 0
	global_load_lds_dwordx4 v[240:241], off
	s_barrier
	s_waitcnt lgkmcnt(0)
	s_nop 0
	s_waitcnt lgkmcnt(0)
	v_mfma_f32_16x16x32_bf16 v[0:3], v[116:119], v[188:191], v[0:3]
	v_mfma_f32_16x16x32_bf16 v[148:151], v[116:119], v[32:35], v[148:151]
	v_mfma_f32_16x16x32_bf16 v[152:155], v[124:127], v[32:35], v[152:155]
	v_mfma_f32_16x16x32_bf16 v[156:159], v[116:119], v[40:43], v[156:159]
	v_mfma_f32_16x16x32_bf16 v[160:163], v[124:127], v[40:43], v[160:163]
	v_mfma_f32_16x16x32_bf16 v[164:167], v[116:119], v[180:183], v[164:167]
	v_mfma_f32_16x16x32_bf16 v[168:171], v[124:127], v[180:183], v[168:171]
	v_mfma_f32_16x16x32_bf16 v[116:119], v[120:123], v[192:195], v[0:3]
	v_mfma_f32_16x16x32_bf16 v[0:3], v[124:127], v[188:191], v[4:7]
	v_mfma_f32_16x16x32_bf16 v[148:151], v[120:123], v[36:39], v[148:151]
	v_mfma_f32_16x16x32_bf16 v[152:155], v[130:133], v[36:39], v[152:155]
	v_mfma_f32_16x16x32_bf16 v[156:159], v[120:123], v[176:179], v[156:159]
	v_mfma_f32_16x16x32_bf16 v[160:163], v[130:133], v[176:179], v[160:163]
	v_mfma_f32_16x16x32_bf16 v[164:167], v[120:123], v[184:187], v[164:167]
	v_mfma_f32_16x16x32_bf16 v[168:171], v[130:133], v[184:187], v[168:171]
	v_mfma_f32_16x16x32_bf16 v[120:123], v[130:133], v[192:195], v[0:3]
	s_nop 0
	s_barrier
	s_add_u32 s34, s14, 0x10000
	s_addc_u32 s35, s15, 0
	s_mov_b32 m0, vcc_lo
	v_lshl_add_u64 v[0:1], s[34:35], 0, v[98:99]
	global_load_lds_dwordx4 v[0:1], off
	v_lshl_add_u64 v[0:1], s[34:35], 0, v[96:97]
	s_mov_b32 m0, s48
	s_nop 0
	global_load_lds_dwordx4 v[0:1], off
	s_waitcnt vmcnt(6)
	s_barrier
	s_nop 0
	v_mfma_f32_16x16x32_bf16 v[0:3], v[64:67], v[32:35], v[8:11]
	v_mfma_f32_16x16x32_bf16 v[124:127], v[72:75], v[36:39], v[0:3]
	v_mfma_f32_16x16x32_bf16 v[0:3], v[204:207], v[32:35], v[12:15]
	v_mfma_f32_16x16x32_bf16 v[130:133], v[208:211], v[36:39], v[0:3]
	v_mfma_f32_16x16x32_bf16 v[0:3], v[64:67], v[40:43], v[44:47]
	v_mfma_f32_16x16x32_bf16 v[212:215], v[72:75], v[176:179], v[0:3]
	v_mfma_f32_16x16x32_bf16 v[0:3], v[204:207], v[40:43], v[88:91]
	v_mfma_f32_16x16x32_bf16 v[176:179], v[208:211], v[176:179], v[0:3]
	v_mfma_f32_16x16x32_bf16 v[0:3], v[64:67], v[180:183], v[92:95]
	v_mfma_f32_16x16x32_bf16 v[216:219], v[72:75], v[184:187], v[0:3]
	v_mfma_f32_16x16x32_bf16 v[0:3], v[204:207], v[180:183], v[112:115]
	v_mfma_f32_16x16x32_bf16 v[112:115], v[208:211], v[184:187], v[0:3]
	v_mfma_f32_16x16x32_bf16 v[0:3], v[64:67], v[188:191], v[80:83]
	v_mfma_f32_16x16x32_bf16 v[180:183], v[72:75], v[192:195], v[0:3]
	v_mfma_f32_16x16x32_bf16 v[0:3], v[204:207], v[188:191], v[84:87]
	v_mfma_f32_16x16x32_bf16 v[184:187], v[208:211], v[192:195], v[0:3]
	s_nop 0
	s_barrier
	ds_read_b128 v[84:87], v143
	ds_read_b128 v[92:95], v143 offset:1024
	ds_read_b128 v[188:191], v143 offset:2048
	ds_read_b128 v[192:195], v143 offset:3072
	s_add_u32 s34, s44, 0x10000
	s_addc_u32 s35, s45, 0
	s_mov_b32 m0, s24
	v_lshl_add_u64 v[0:1], s[34:35], 0, v[98:99]
	ds_read_b128 v[4:7], v106 offset:32768
	ds_read_b128 v[12:15], v106 offset:33792
	ds_read_b128 v[36:39], v106 offset:34816
	ds_read_b128 v[44:47], v106 offset:35840
	ds_read_b128 v[80:83], v106 offset:36864
	ds_read_b128 v[88:91], v106 offset:37888
	ds_read_b128 v[204:207], v106 offset:38912
	ds_read_b128 v[208:211], v106 offset:39936
	global_load_lds_dwordx4 v[0:1], off
	v_lshl_add_u64 v[0:1], s[34:35], 0, v[96:97]
	s_mov_b32 m0, s25
	s_nop 0
	global_load_lds_dwordx4 v[0:1], off
	s_waitcnt lgkmcnt(8)
	s_barrier
	s_waitcnt lgkmcnt(0)
	s_nop 0
	s_waitcnt lgkmcnt(0)
	v_mfma_f32_16x16x32_bf16 v[0:3], v[84:87], v[4:7], v[48:51]
	v_mfma_f32_16x16x32_bf16 v[220:223], v[92:95], v[12:15], v[0:3]
	v_mfma_f32_16x16x32_bf16 v[0:3], v[188:191], v[4:7], v[52:55]
	v_mfma_f32_16x16x32_bf16 v[224:227], v[192:195], v[12:15], v[0:3]
	v_mfma_f32_16x16x32_bf16 v[0:3], v[84:87], v[36:39], v[56:59]
	v_mfma_f32_16x16x32_bf16 v[72:75], v[92:95], v[44:47], v[0:3]
	v_mfma_f32_16x16x32_bf16 v[0:3], v[188:191], v[36:39], v[60:63]
	v_mfma_f32_16x16x32_bf16 v[64:67], v[192:195], v[44:47], v[0:3]
	v_mfma_f32_16x16x32_bf16 v[0:3], v[84:87], v[80:83], v[196:199]
	v_mfma_f32_16x16x32_bf16 v[40:43], v[92:95], v[88:91], v[0:3]
	v_mfma_f32_16x16x32_bf16 v[0:3], v[188:191], v[80:83], v[68:71]
	v_mfma_f32_16x16x32_bf16 v[32:35], v[192:195], v[88:91], v[0:3]
	v_mfma_f32_16x16x32_bf16 v[0:3], v[84:87], v[204:207], v[200:203]
	v_mfma_f32_16x16x32_bf16 v[8:11], v[92:95], v[208:211], v[0:3]
	v_mfma_f32_16x16x32_bf16 v[0:3], v[188:191], v[204:207], v[76:79]
	v_mfma_f32_16x16x32_bf16 v[0:3], v[192:195], v[208:211], v[0:3]
	s_nop 0
	s_barrier
	s_mov_b32 m0, s50
	v_lshl_add_u64 v[48:49], v[138:139], 0, s[28:29]
	ds_read_b128 v[196:199], v236
	ds_read_b128 v[200:203], v236 offset:1024
	ds_read_b128 v[228:231], v236 offset:2048
	ds_read_b128 v[236:239], v236 offset:3072
	global_load_lds_dwordx4 v[48:49], off
	v_lshl_add_u64 v[48:49], v[140:141], 0, s[28:29]
	s_mov_b32 m0, s49
	s_nop 0
	global_load_lds_dwordx4 v[48:49], off
	s_barrier
	s_waitcnt lgkmcnt(0)
	s_nop 0
	s_waitcnt lgkmcnt(0)
	v_mfma_f32_16x16x32_bf16 v[48:51], v[196:199], v[4:7], v[108:111]
	v_mfma_f32_16x16x32_bf16 v[4:7], v[228:231], v[4:7], v[16:19]
	v_mfma_f32_16x16x32_bf16 v[244:247], v[236:239], v[12:15], v[4:7]
	v_mfma_f32_16x16x32_bf16 v[4:7], v[196:199], v[36:39], v[20:23]
	v_mfma_f32_16x16x32_bf16 v[76:79], v[200:203], v[44:47], v[4:7]
	v_mfma_f32_16x16x32_bf16 v[4:7], v[228:231], v[36:39], v[24:27]
	v_mfma_f32_16x16x32_bf16 v[68:71], v[236:239], v[44:47], v[4:7]
	v_mfma_f32_16x16x32_bf16 v[4:7], v[196:199], v[80:83], v[28:31]
	v_mfma_f32_16x16x32_bf16 v[44:47], v[200:203], v[88:91], v[4:7]
	v_mfma_f32_16x16x32_bf16 v[4:7], v[228:231], v[80:83], v[134:137]
	v_mfma_f32_16x16x32_bf16 v[36:39], v[236:239], v[88:91], v[4:7]
	v_mfma_f32_16x16x32_bf16 v[4:7], v[196:199], v[204:207], v[144:147]
	v_mfma_f32_16x16x32_bf16 v[108:111], v[200:203], v[12:15], v[48:51]
	v_mfma_f32_16x16x32_bf16 v[12:15], v[200:203], v[208:211], v[4:7]
	v_mfma_f32_16x16x32_bf16 v[4:7], v[228:231], v[204:207], v[172:175]
	v_mfma_f32_16x16x32_bf16 v[4:7], v[236:239], v[208:211], v[4:7]
	s_nop 0
	s_mov_b32 m0, s36
	v_lshl_add_u64 v[16:17], v[232:233], 0, s[28:29]
	s_barrier
	ds_read_b128 v[20:23], v106 offset:49152
	ds_read_b128 v[28:31], v106 offset:50176
	ds_read_b128 v[52:55], v106 offset:51200
	ds_read_b128 v[60:63], v106 offset:52224
	ds_read_b128 v[134:137], v106 offset:53248
	ds_read_b128 v[144:147], v106 offset:54272
	ds_read_b128 v[172:175], v106 offset:55296
	ds_read_b128 v[204:207], v106 offset:56320
	global_load_lds_dwordx4 v[16:17], off
	v_lshl_add_u64 v[16:17], v[240:241], 0, s[28:29]
	s_mov_b32 m0, s37
	s_nop 0
	global_load_lds_dwordx4 v[16:17], off
	s_barrier
	s_waitcnt lgkmcnt(0)
	s_nop 0
	s_waitcnt lgkmcnt(0)
	v_mfma_f32_16x16x32_bf16 v[16:19], v[84:87], v[20:23], v[148:151]
	v_mfma_f32_16x16x32_bf16 v[148:151], v[92:95], v[28:31], v[16:19]
	v_mfma_f32_16x16x32_bf16 v[16:19], v[188:191], v[20:23], v[152:155]
	v_mfma_f32_16x16x32_bf16 v[152:155], v[192:195], v[28:31], v[16:19]
	v_mfma_f32_16x16x32_bf16 v[16:19], v[84:87], v[52:55], v[156:159]
	v_mfma_f32_16x16x32_bf16 v[88:91], v[92:95], v[60:63], v[16:19]
	v_mfma_f32_16x16x32_bf16 v[16:19], v[188:191], v[52:55], v[160:163]
	v_mfma_f32_16x16x32_bf16 v[80:83], v[192:195], v[60:63], v[16:19]
	v_mfma_f32_16x16x32_bf16 v[16:19], v[84:87], v[134:137], v[164:167]
	v_mfma_f32_16x16x32_bf16 v[56:59], v[92:95], v[144:147], v[16:19]
	v_mfma_f32_16x16x32_bf16 v[16:19], v[188:191], v[134:137], v[168:171]
	v_mfma_f32_16x16x32_bf16 v[48:51], v[192:195], v[144:147], v[16:19]
	v_mfma_f32_16x16x32_bf16 v[16:19], v[84:87], v[172:175], v[116:119]
	v_mfma_f32_16x16x32_bf16 v[24:27], v[92:95], v[204:207], v[16:19]
	v_mfma_f32_16x16x32_bf16 v[16:19], v[188:191], v[172:175], v[120:123]
	v_mfma_f32_16x16x32_bf16 v[16:19], v[192:195], v[204:207], v[16:19]
	s_nop 0
	s_barrier
	s_add_u32 s14, s14, 0x10080
	s_addc_u32 s15, s15, 0
	s_mov_b32 m0, s19
	v_lshl_add_u64 v[84:85], s[14:15], 0, v[98:99]
	global_load_lds_dwordx4 v[84:85], off
	v_lshl_add_u64 v[84:85], s[14:15], 0, v[96:97]
	s_mov_b32 m0, s18
	s_nop 0
	global_load_lds_dwordx4 v[84:85], off
	s_waitcnt vmcnt(6)
	s_barrier
	s_nop 0
	v_mfma_f32_16x16x32_bf16 v[84:87], v[196:199], v[20:23], v[124:127]
	v_mfma_f32_16x16x32_bf16 v[20:23], v[228:231], v[20:23], v[130:133]
	v_mfma_f32_16x16x32_bf16 v[120:123], v[236:239], v[28:31], v[20:23]
	v_mfma_f32_16x16x32_bf16 v[20:23], v[196:199], v[52:55], v[212:215]
	v_mfma_f32_16x16x32_bf16 v[92:95], v[200:203], v[60:63], v[20:23]
	v_mfma_f32_16x16x32_bf16 v[20:23], v[228:231], v[52:55], v[176:179]
	v_mfma_f32_16x16x32_bf16 v[116:119], v[200:203], v[28:31], v[84:87]
	v_mfma_f32_16x16x32_bf16 v[84:87], v[236:239], v[60:63], v[20:23]
	v_mfma_f32_16x16x32_bf16 v[20:23], v[196:199], v[134:137], v[216:219]
	v_mfma_f32_16x16x32_bf16 v[60:63], v[200:203], v[144:147], v[20:23]
	v_mfma_f32_16x16x32_bf16 v[20:23], v[228:231], v[134:137], v[112:115]
	v_mfma_f32_16x16x32_bf16 v[52:55], v[236:239], v[144:147], v[20:23]
	v_mfma_f32_16x16x32_bf16 v[20:23], v[196:199], v[172:175], v[180:183]
	v_mfma_f32_16x16x32_bf16 v[28:31], v[200:203], v[204:207], v[20:23]
	v_mfma_f32_16x16x32_bf16 v[20:23], v[228:231], v[172:175], v[184:187]
	v_mfma_f32_16x16x32_bf16 v[20:23], v[236:239], v[204:207], v[20:23]
	s_branch .Lfa2_x
	s_nop 0
	s_nop 0
	s_nop 0
	s_nop 0

.LBB0_88:
	s_ashr_i32 s36, s35, 6
	s_ashr_i32 s37, s36, 31
	s_ashr_i32 s31, s30, 31
	s_lshl_b64 s[36:37], s[36:37], 18
	s_lshl_b64 s[44:45], s[30:31], 17
	v_readlane_b32 s46, v254, 55
	v_readlane_b32 s47, v254, 56
	s_add_u32 s20, s46, s36
	s_addc_u32 s31, s47, s37
	s_add_u32 s44, s20, s44
	s_addc_u32 s45, s31, s45
	s_and_b64 s[36:37], s[40:41], exec
	s_cselect_b32 s41, s45, s15
	s_cselect_b32 s40, s44, s14
	s_add_i32 s20, 16, 0x10000
	v_add_u32_e32 v35, s20, v33
	ds_read_b128 v[0:3], v35
	ds_read_b128 v[4:7], v35 offset:1024
	ds_read_b128 v[8:11], v35 offset:2048
	ds_read_b128 v[12:15], v35 offset:3072
	s_add_u32 s36, s14, 0x10080
	s_addc_u32 s37, s15, 0
	s_add_i32 s46, s4, 0xc000
	v_lshl_add_u64 v[60:61], s[36:37], 0, v[28:29]
	s_mov_b32 m0, s46
	s_add_i32 s31, s4, 0xe000
	ds_read_b128 v[16:19], v34
	ds_read_b128 v[20:23], v34 offset:1024
	ds_read_b128 v[36:39], v34 offset:2048
	ds_read_b128 v[40:43], v34 offset:3072
	ds_read_b128 v[44:47], v34 offset:4096
	ds_read_b128 v[48:51], v34 offset:5120
	ds_read_b128 v[52:55], v34 offset:6144
	ds_read_b128 v[56:59], v34 offset:7168
	global_load_lds_dwordx4 v[60:61], off
	v_lshl_add_u64 v[60:61], s[36:37], 0, v[26:27]
	s_mov_b32 m0, s31
	s_nop 0
	global_load_lds_dwordx4 v[60:61], off
	s_waitcnt lgkmcnt(8)
	s_barrier
	s_waitcnt lgkmcnt(0)
	s_nop 0
	s_waitcnt lgkmcnt(0)
	v_mfma_f32_16x16x32_bf16 v[60:63], v[0:3], v[16:19], 0
	v_mfma_f32_16x16x32_bf16 v[64:67], v[8:11], v[16:19], 0
	v_mfma_f32_16x16x32_bf16 v[68:71], v[0:3], v[36:39], 0
	v_mfma_f32_16x16x32_bf16 v[72:75], v[8:11], v[36:39], 0
	v_mfma_f32_16x16x32_bf16 v[76:79], v[0:3], v[44:47], 0
	v_mfma_f32_16x16x32_bf16 v[80:83], v[8:11], v[44:47], 0
	v_mfma_f32_16x16x32_bf16 v[84:87], v[0:3], v[52:55], 0
	v_mfma_f32_16x16x32_bf16 v[88:91], v[8:11], v[52:55], 0
	v_mfma_f32_16x16x32_bf16 v[60:63], v[4:7], v[20:23], v[60:63]
	v_mfma_f32_16x16x32_bf16 v[64:67], v[12:15], v[20:23], v[64:67]
	v_mfma_f32_16x16x32_bf16 v[68:71], v[4:7], v[40:43], v[68:71]
	v_mfma_f32_16x16x32_bf16 v[72:75], v[12:15], v[40:43], v[72:75]
	v_mfma_f32_16x16x32_bf16 v[76:79], v[4:7], v[48:51], v[76:79]
	v_mfma_f32_16x16x32_bf16 v[80:83], v[12:15], v[48:51], v[80:83]
	v_mfma_f32_16x16x32_bf16 v[84:87], v[4:7], v[56:59], v[84:87]
	v_mfma_f32_16x16x32_bf16 v[88:91], v[12:15], v[56:59], v[88:91]
	s_nop 0
	s_barrier
	s_add_i32 s37, 16, 0x14000
	v_lshl_add_u64 v[130:131], s[18:19], 0, v[128:129]
	s_mov_b64 s[48:49], 0x100
	s_add_i32 s36, s20, s1
	v_add_u32_e32 v138, s37, v33
	v_lshl_add_u64 v[108:109], v[130:131], 0, s[48:49]
	s_mov_b32 m0, s36
	v_lshl_add_u64 v[132:133], s[18:19], 0, v[24:25]
	s_add_i32 s18, s36, 0x2000
	ds_read_b128 v[92:95], v138
	ds_read_b128 v[96:99], v138 offset:1024
	ds_read_b128 v[100:103], v138 offset:2048
	ds_read_b128 v[104:107], v138 offset:3072
	global_load_lds_dwordx4 v[108:109], off
	v_lshl_add_u64 v[108:109], v[132:133], 0, s[48:49]
	s_mov_b32 m0, s18
	s_nop 0
	global_load_lds_dwordx4 v[108:109], off
	s_barrier
	s_waitcnt lgkmcnt(0)
	s_nop 0
	s_waitcnt lgkmcnt(0)
	v_mfma_f32_16x16x32_bf16 v[108:111], v[92:95], v[16:19], 0
	v_mfma_f32_16x16x32_bf16 v[16:19], v[100:103], v[16:19], 0
	v_mfma_f32_16x16x32_bf16 v[108:111], v[96:99], v[20:23], v[108:111]
	v_mfma_f32_16x16x32_bf16 v[16:19], v[104:107], v[20:23], v[16:19]
	v_mfma_f32_16x16x32_bf16 v[20:23], v[92:95], v[36:39], 0
	v_mfma_f32_16x16x32_bf16 v[36:39], v[100:103], v[36:39], 0
	v_mfma_f32_16x16x32_bf16 v[20:23], v[96:99], v[40:43], v[20:23]
	v_mfma_f32_16x16x32_bf16 v[36:39], v[104:107], v[40:43], v[36:39]
	v_mfma_f32_16x16x32_bf16 v[40:43], v[92:95], v[44:47], 0
	v_mfma_f32_16x16x32_bf16 v[44:47], v[100:103], v[44:47], 0
	v_mfma_f32_16x16x32_bf16 v[40:43], v[96:99], v[48:51], v[40:43]
	v_mfma_f32_16x16x32_bf16 v[44:47], v[104:107], v[48:51], v[44:47]
	v_mfma_f32_16x16x32_bf16 v[48:51], v[92:95], v[52:55], 0
	v_mfma_f32_16x16x32_bf16 v[52:55], v[100:103], v[52:55], 0
	v_mfma_f32_16x16x32_bf16 v[48:51], v[96:99], v[56:59], v[48:51]
	v_mfma_f32_16x16x32_bf16 v[52:55], v[104:107], v[56:59], v[52:55]
	s_nop 0
	v_lshl_add_u64 v[134:135], s[14:15], 0, v[28:29]
	s_mov_b32 m0, s4
	v_lshl_add_u64 v[136:137], v[134:135], 0, s[48:49]
	s_barrier
	ds_read_b128 v[56:59], v34 offset:16384
	ds_read_b128 v[112:115], v34 offset:17408
	ds_read_b128 v[116:119], v34 offset:18432
	ds_read_b128 v[120:123], v34 offset:19456
	ds_read_b128 v[124:127], v34 offset:20480
	ds_read_b128 v[144:147], v34 offset:21504
	ds_read_b128 v[148:151], v34 offset:22528
	ds_read_b128 v[152:155], v34 offset:23552
	global_load_lds_dwordx4 v[136:137], off
	v_lshl_add_u64 v[136:137], s[14:15], 0, v[26:27]
	v_lshl_add_u64 v[156:157], v[136:137], 0, s[48:49]
	s_mov_b32 m0, s5
	s_nop 0
	global_load_lds_dwordx4 v[156:157], off
	s_barrier
	s_waitcnt lgkmcnt(0)
	s_nop 0
	s_waitcnt lgkmcnt(0)
	v_mfma_f32_16x16x32_bf16 v[156:159], v[0:3], v[56:59], 0
	v_mfma_f32_16x16x32_bf16 v[164:167], v[0:3], v[116:119], 0
	v_mfma_f32_16x16x32_bf16 v[172:175], v[0:3], v[124:127], 0
	v_mfma_f32_16x16x32_bf16 v[0:3], v[0:3], v[148:151], 0
	v_mfma_f32_16x16x32_bf16 v[156:159], v[4:7], v[112:115], v[156:159]
	v_mfma_f32_16x16x32_bf16 v[160:163], v[8:11], v[56:59], 0
	v_mfma_f32_16x16x32_bf16 v[164:167], v[4:7], v[120:123], v[164:167]
	v_mfma_f32_16x16x32_bf16 v[168:171], v[8:11], v[116:119], 0
	v_mfma_f32_16x16x32_bf16 v[172:175], v[4:7], v[144:147], v[172:175]
	v_mfma_f32_16x16x32_bf16 v[176:179], v[8:11], v[124:127], 0
	v_mfma_f32_16x16x32_bf16 v[0:3], v[4:7], v[152:155], v[0:3]
	v_mfma_f32_16x16x32_bf16 v[4:7], v[8:11], v[148:151], 0
	v_mfma_f32_16x16x32_bf16 v[160:163], v[12:15], v[112:115], v[160:163]
	v_mfma_f32_16x16x32_bf16 v[168:171], v[12:15], v[120:123], v[168:171]
	v_mfma_f32_16x16x32_bf16 v[176:179], v[12:15], v[144:147], v[176:179]
	v_mfma_f32_16x16x32_bf16 v[4:7], v[12:15], v[152:155], v[4:7]
	s_nop 0
	s_barrier
	s_mov_b64 s[48:49], 0x900
	s_add_i32 s20, s37, s1
	v_lshl_add_u64 v[8:9], v[130:131], 0, s[48:49]
	s_mov_b32 m0, s20
	s_add_i32 s19, s20, 0x2000
	global_load_lds_dwordx4 v[8:9], off
	v_lshl_add_u64 v[8:9], v[132:133], 0, s[48:49]
	s_mov_b32 m0, s19
	s_nop 0
	global_load_lds_dwordx4 v[8:9], off
	s_waitcnt vmcnt(6)
	s_barrier
	s_nop 0
	v_mfma_f32_16x16x32_bf16 v[8:11], v[92:95], v[56:59], 0
	v_mfma_f32_16x16x32_bf16 v[12:15], v[100:103], v[56:59], 0
	v_mfma_f32_16x16x32_bf16 v[8:11], v[96:99], v[112:115], v[8:11]
	v_mfma_f32_16x16x32_bf16 v[12:15], v[104:107], v[112:115], v[12:15]
	v_mfma_f32_16x16x32_bf16 v[56:59], v[92:95], v[116:119], 0
	v_mfma_f32_16x16x32_bf16 v[112:115], v[100:103], v[116:119], 0
	v_mfma_f32_16x16x32_bf16 v[116:119], v[92:95], v[124:127], 0
	v_mfma_f32_16x16x32_bf16 v[92:95], v[92:95], v[148:151], 0
	v_mfma_f32_16x16x32_bf16 v[56:59], v[96:99], v[120:123], v[56:59]
	v_mfma_f32_16x16x32_bf16 v[112:115], v[104:107], v[120:123], v[112:115]
	v_mfma_f32_16x16x32_bf16 v[116:119], v[96:99], v[144:147], v[116:119]
	v_mfma_f32_16x16x32_bf16 v[120:123], v[100:103], v[124:127], 0
	v_mfma_f32_16x16x32_bf16 v[92:95], v[96:99], v[152:155], v[92:95]
	v_mfma_f32_16x16x32_bf16 v[96:99], v[100:103], v[148:151], 0
	v_mfma_f32_16x16x32_bf16 v[120:123], v[104:107], v[144:147], v[120:123]
	v_mfma_f32_16x16x32_bf16 v[96:99], v[104:107], v[152:155], v[96:99]
	s_nop 0
	s_add_i32 s37, 16, 0x18000
	v_add_u32_e32 v139, s37, v33
	s_barrier
	ds_read_b128 v[100:103], v139
	ds_read_b128 v[104:107], v139 offset:1024
	ds_read_b128 v[124:127], v139 offset:2048
	ds_read_b128 v[144:147], v139 offset:3072
	s_add_u32 s48, s14, 0x10100
	s_addc_u32 s49, s15, 0
	s_mov_b32 m0, s16
	v_lshl_add_u64 v[204:205], s[48:49], 0, v[28:29]
	ds_read_b128 v[148:151], v34 offset:32768
	ds_read_b128 v[152:155], v34 offset:33792
	ds_read_b128 v[180:183], v34 offset:34816
	ds_read_b128 v[184:187], v34 offset:35840
	ds_read_b128 v[188:191], v34 offset:36864
	ds_read_b128 v[192:195], v34 offset:37888
	ds_read_b128 v[196:199], v34 offset:38912
	ds_read_b128 v[200:203], v34 offset:39936
	global_load_lds_dwordx4 v[204:205], off
	v_lshl_add_u64 v[204:205], s[48:49], 0, v[26:27]
	s_mov_b32 m0, s17
	s_nop 0
	global_load_lds_dwordx4 v[204:205], off
	s_waitcnt lgkmcnt(8)
	s_barrier
	s_waitcnt lgkmcnt(0)
	s_nop 0
	s_waitcnt lgkmcnt(0)
	v_mfma_f32_16x16x32_bf16 v[60:63], v[100:103], v[148:151], v[60:63]
	v_mfma_f32_16x16x32_bf16 v[64:67], v[124:127], v[148:151], v[64:67]
	v_mfma_f32_16x16x32_bf16 v[68:71], v[100:103], v[180:183], v[68:71]
	v_mfma_f32_16x16x32_bf16 v[72:75], v[124:127], v[180:183], v[72:75]
	v_mfma_f32_16x16x32_bf16 v[76:79], v[100:103], v[188:191], v[76:79]
	v_mfma_f32_16x16x32_bf16 v[80:83], v[124:127], v[188:191], v[80:83]
	v_mfma_f32_16x16x32_bf16 v[84:87], v[100:103], v[196:199], v[84:87]
	v_mfma_f32_16x16x32_bf16 v[88:91], v[124:127], v[196:199], v[88:91]
	v_mfma_f32_16x16x32_bf16 v[60:63], v[104:107], v[152:155], v[60:63]
	v_mfma_f32_16x16x32_bf16 v[64:67], v[144:147], v[152:155], v[64:67]
	v_mfma_f32_16x16x32_bf16 v[68:71], v[104:107], v[184:187], v[68:71]
	v_mfma_f32_16x16x32_bf16 v[72:75], v[144:147], v[184:187], v[72:75]
	v_mfma_f32_16x16x32_bf16 v[76:79], v[104:107], v[192:195], v[76:79]
	v_mfma_f32_16x16x32_bf16 v[80:83], v[144:147], v[192:195], v[80:83]
	v_mfma_f32_16x16x32_bf16 v[84:87], v[104:107], v[200:203], v[84:87]
	v_mfma_f32_16x16x32_bf16 v[88:91], v[144:147], v[200:203], v[88:91]
	s_nop 0
	s_barrier
	s_add_i32 s48, 16, 0x1c000
	s_mov_b64 s[50:51], 0x180
	s_add_i32 s49, s37, s1
	v_add_u32_e32 v140, s48, v33
	v_lshl_add_u64 v[220:221], v[130:131], 0, s[50:51]
	s_mov_b32 m0, s49
	s_add_i32 s37, s49, 0x2000
	ds_read_b128 v[204:207], v140
	ds_read_b128 v[208:211], v140 offset:1024
	ds_read_b128 v[212:215], v140 offset:2048
	ds_read_b128 v[216:219], v140 offset:3072
	global_load_lds_dwordx4 v[220:221], off
	v_lshl_add_u64 v[220:221], v[132:133], 0, s[50:51]
	s_mov_b32 m0, s37
	s_nop 0
	global_load_lds_dwordx4 v[220:221], off
	s_barrier
	s_waitcnt lgkmcnt(0)
	s_nop 0
	s_waitcnt lgkmcnt(0)
	v_mfma_f32_16x16x32_bf16 v[108:111], v[204:207], v[148:151], v[108:111]
	v_mfma_f32_16x16x32_bf16 v[16:19], v[212:215], v[148:151], v[16:19]
	v_mfma_f32_16x16x32_bf16 v[20:23], v[204:207], v[180:183], v[20:23]
	v_mfma_f32_16x16x32_bf16 v[36:39], v[212:215], v[180:183], v[36:39]
	v_mfma_f32_16x16x32_bf16 v[40:43], v[204:207], v[188:191], v[40:43]
	v_mfma_f32_16x16x32_bf16 v[44:47], v[212:215], v[188:191], v[44:47]
	v_mfma_f32_16x16x32_bf16 v[48:51], v[204:207], v[196:199], v[48:51]
	v_mfma_f32_16x16x32_bf16 v[52:55], v[212:215], v[196:199], v[52:55]
	v_mfma_f32_16x16x32_bf16 v[108:111], v[208:211], v[152:155], v[108:111]
	v_mfma_f32_16x16x32_bf16 v[16:19], v[216:219], v[152:155], v[16:19]
	v_mfma_f32_16x16x32_bf16 v[20:23], v[208:211], v[184:187], v[20:23]
	v_mfma_f32_16x16x32_bf16 v[36:39], v[216:219], v[184:187], v[36:39]
	v_mfma_f32_16x16x32_bf16 v[40:43], v[208:211], v[192:195], v[40:43]
	v_mfma_f32_16x16x32_bf16 v[44:47], v[216:219], v[192:195], v[44:47]
	v_mfma_f32_16x16x32_bf16 v[48:51], v[208:211], v[200:203], v[48:51]
	v_mfma_f32_16x16x32_bf16 v[52:55], v[216:219], v[200:203], v[52:55]
	s_nop 0
	s_mov_b32 m0, s24
	v_lshl_add_u64 v[134:135], v[134:135], 0, s[50:51]
	s_barrier
	ds_read_b128 v[148:151], v34 offset:49152
	ds_read_b128 v[152:155], v34 offset:50176
	ds_read_b128 v[180:183], v34 offset:51200
	ds_read_b128 v[184:187], v34 offset:52224
	ds_read_b128 v[188:191], v34 offset:53248
	ds_read_b128 v[192:195], v34 offset:54272
	ds_read_b128 v[196:199], v34 offset:55296
	ds_read_b128 v[200:203], v34 offset:56320
	global_load_lds_dwordx4 v[134:135], off
	v_lshl_add_u64 v[134:135], v[136:137], 0, s[50:51]
	s_mov_b32 m0, s25
	s_nop 0
	global_load_lds_dwordx4 v[134:135], off
	s_barrier
	s_waitcnt lgkmcnt(0)
	s_nop 0
	s_waitcnt lgkmcnt(0)
	v_mfma_f32_16x16x32_bf16 v[156:159], v[100:103], v[148:151], v[156:159]
	v_mfma_f32_16x16x32_bf16 v[160:163], v[124:127], v[148:151], v[160:163]
	v_mfma_f32_16x16x32_bf16 v[164:167], v[100:103], v[180:183], v[164:167]
	v_mfma_f32_16x16x32_bf16 v[168:171], v[124:127], v[180:183], v[168:171]
	v_mfma_f32_16x16x32_bf16 v[172:175], v[100:103], v[188:191], v[172:175]
	v_mfma_f32_16x16x32_bf16 v[176:179], v[124:127], v[188:191], v[176:179]
	v_mfma_f32_16x16x32_bf16 v[0:3], v[100:103], v[196:199], v[0:3]
	v_mfma_f32_16x16x32_bf16 v[4:7], v[124:127], v[196:199], v[4:7]
	v_mfma_f32_16x16x32_bf16 v[156:159], v[104:107], v[152:155], v[156:159]
	v_mfma_f32_16x16x32_bf16 v[160:163], v[144:147], v[152:155], v[160:163]
	v_mfma_f32_16x16x32_bf16 v[164:167], v[104:107], v[184:187], v[164:167]
	v_mfma_f32_16x16x32_bf16 v[168:171], v[144:147], v[184:187], v[168:171]
	v_mfma_f32_16x16x32_bf16 v[172:175], v[104:107], v[192:195], v[172:175]
	v_mfma_f32_16x16x32_bf16 v[176:179], v[144:147], v[192:195], v[176:179]
	v_mfma_f32_16x16x32_bf16 v[0:3], v[104:107], v[200:203], v[0:3]
	v_mfma_f32_16x16x32_bf16 v[4:7], v[144:147], v[200:203], v[4:7]
	s_nop 0
	s_barrier
	s_mov_b64 s[50:51], 0x980
	s_add_i32 s48, s48, s1
	v_lshl_add_u64 v[100:101], v[130:131], 0, s[50:51]
	s_mov_b32 m0, s48
	s_add_i32 s47, s48, 0x2000
	global_load_lds_dwordx4 v[100:101], off
	v_lshl_add_u64 v[100:101], v[132:133], 0, s[50:51]
	s_mov_b32 m0, s47
	s_nop 0
	global_load_lds_dwordx4 v[100:101], off
	s_waitcnt vmcnt(6)
	s_barrier
	s_nop 0
	v_mfma_f32_16x16x32_bf16 v[8:11], v[204:207], v[148:151], v[8:11]
	v_mfma_f32_16x16x32_bf16 v[12:15], v[212:215], v[148:151], v[12:15]
	v_mfma_f32_16x16x32_bf16 v[56:59], v[204:207], v[180:183], v[56:59]
	v_mfma_f32_16x16x32_bf16 v[100:103], v[212:215], v[180:183], v[112:115]
	v_mfma_f32_16x16x32_bf16 v[104:107], v[204:207], v[188:191], v[116:119]
	v_mfma_f32_16x16x32_bf16 v[112:115], v[212:215], v[188:191], v[120:123]
	v_mfma_f32_16x16x32_bf16 v[92:95], v[204:207], v[196:199], v[92:95]
	v_mfma_f32_16x16x32_bf16 v[96:99], v[212:215], v[196:199], v[96:99]
	v_mfma_f32_16x16x32_bf16 v[8:11], v[208:211], v[152:155], v[8:11]
	v_mfma_f32_16x16x32_bf16 v[12:15], v[216:219], v[152:155], v[12:15]
	v_mfma_f32_16x16x32_bf16 v[56:59], v[208:211], v[184:187], v[56:59]
	v_mfma_f32_16x16x32_bf16 v[100:103], v[216:219], v[184:187], v[100:103]
	v_mfma_f32_16x16x32_bf16 v[104:107], v[208:211], v[192:195], v[104:107]
	v_mfma_f32_16x16x32_bf16 v[112:115], v[216:219], v[192:195], v[112:115]
	v_mfma_f32_16x16x32_bf16 v[92:95], v[208:211], v[200:203], v[92:95]
	v_mfma_f32_16x16x32_bf16 v[96:99], v[216:219], v[200:203], v[96:99]
	s_nop 0
	s_barrier
	ds_read_b128 v[116:119], v35
	ds_read_b128 v[120:123], v35 offset:1024
	ds_read_b128 v[124:127], v35 offset:2048
	ds_read_b128 v[144:147], v35 offset:3072
	s_add_u32 s14, s14, 0x10180
	s_addc_u32 s15, s15, 0
	s_mov_b32 m0, s46
	v_lshl_add_u64 v[130:131], s[14:15], 0, v[28:29]
	ds_read_b128 v[148:151], v34
	ds_read_b128 v[152:155], v34 offset:1024
	ds_read_b128 v[180:183], v34 offset:2048
	ds_read_b128 v[184:187], v34 offset:3072
	ds_read_b128 v[188:191], v34 offset:4096
	ds_read_b128 v[192:195], v34 offset:5120
	ds_read_b128 v[196:199], v34 offset:6144
	ds_read_b128 v[200:203], v34 offset:7168
	global_load_lds_dwordx4 v[130:131], off
	v_lshl_add_u64 v[130:131], s[14:15], 0, v[26:27]
	s_mov_b32 m0, s31
	s_nop 0
	global_load_lds_dwordx4 v[130:131], off
	s_waitcnt lgkmcnt(8)
	s_barrier
	s_waitcnt lgkmcnt(0)
	s_nop 0
	s_waitcnt lgkmcnt(0)
	v_mfma_f32_16x16x32_bf16 v[60:63], v[116:119], v[148:151], v[60:63]
	v_mfma_f32_16x16x32_bf16 v[64:67], v[124:127], v[148:151], v[64:67]
	v_mfma_f32_16x16x32_bf16 v[68:71], v[116:119], v[180:183], v[68:71]
	v_mfma_f32_16x16x32_bf16 v[72:75], v[124:127], v[180:183], v[72:75]
	v_mfma_f32_16x16x32_bf16 v[76:79], v[116:119], v[188:191], v[76:79]
	v_mfma_f32_16x16x32_bf16 v[80:83], v[124:127], v[188:191], v[80:83]
	v_mfma_f32_16x16x32_bf16 v[84:87], v[116:119], v[196:199], v[84:87]
	v_mfma_f32_16x16x32_bf16 v[88:91], v[124:127], v[196:199], v[88:91]
	v_mfma_f32_16x16x32_bf16 v[60:63], v[120:123], v[152:155], v[60:63]
	v_mfma_f32_16x16x32_bf16 v[64:67], v[144:147], v[152:155], v[64:67]
	v_mfma_f32_16x16x32_bf16 v[68:71], v[120:123], v[184:187], v[68:71]
	v_mfma_f32_16x16x32_bf16 v[72:75], v[144:147], v[184:187], v[72:75]
	v_mfma_f32_16x16x32_bf16 v[76:79], v[120:123], v[192:195], v[76:79]
	v_mfma_f32_16x16x32_bf16 v[80:83], v[144:147], v[192:195], v[80:83]
	v_mfma_f32_16x16x32_bf16 v[84:87], v[120:123], v[200:203], v[84:87]
	v_mfma_f32_16x16x32_bf16 v[88:91], v[144:147], v[200:203], v[88:91]
	s_nop 0
	s_barrier
	s_mov_b32 m0, s36
	v_lshl_add_u64 v[130:131], s[42:43], 0, v[128:129]
	ds_read_b128 v[204:207], v138
	ds_read_b128 v[208:211], v138 offset:1024
	ds_read_b128 v[212:215], v138 offset:2048
	ds_read_b128 v[216:219], v138 offset:3072
	global_load_lds_dwordx4 v[130:131], off
	v_lshl_add_u64 v[132:133], s[42:43], 0, v[24:25]
	s_mov_b32 m0, s18
	s_nop 0
	global_load_lds_dwordx4 v[132:133], off
	s_barrier
	s_waitcnt lgkmcnt(0)
	s_nop 0
	s_waitcnt lgkmcnt(0)
	v_mfma_f32_16x16x32_bf16 v[108:111], v[204:207], v[148:151], v[108:111]
	v_mfma_f32_16x16x32_bf16 v[16:19], v[212:215], v[148:151], v[16:19]
	v_mfma_f32_16x16x32_bf16 v[20:23], v[204:207], v[180:183], v[20:23]
	v_mfma_f32_16x16x32_bf16 v[36:39], v[212:215], v[180:183], v[36:39]
	v_mfma_f32_16x16x32_bf16 v[40:43], v[204:207], v[188:191], v[40:43]
	v_mfma_f32_16x16x32_bf16 v[44:47], v[212:215], v[188:191], v[44:47]
	v_mfma_f32_16x16x32_bf16 v[48:51], v[204:207], v[196:199], v[48:51]
	v_mfma_f32_16x16x32_bf16 v[52:55], v[212:215], v[196:199], v[52:55]
	v_mfma_f32_16x16x32_bf16 v[108:111], v[208:211], v[152:155], v[108:111]
	v_mfma_f32_16x16x32_bf16 v[16:19], v[216:219], v[152:155], v[16:19]
	v_mfma_f32_16x16x32_bf16 v[20:23], v[208:211], v[184:187], v[20:23]
	v_mfma_f32_16x16x32_bf16 v[36:39], v[216:219], v[184:187], v[36:39]
	v_mfma_f32_16x16x32_bf16 v[40:43], v[208:211], v[192:195], v[40:43]
	v_mfma_f32_16x16x32_bf16 v[44:47], v[216:219], v[192:195], v[44:47]
	v_mfma_f32_16x16x32_bf16 v[48:51], v[208:211], v[200:203], v[48:51]
	v_mfma_f32_16x16x32_bf16 v[52:55], v[216:219], v[200:203], v[52:55]
	s_nop 0
	s_mov_b32 m0, s4
	v_lshl_add_u64 v[134:135], s[40:41], 0, v[28:29]
	s_barrier
	ds_read_b128 v[148:151], v34 offset:16384
	ds_read_b128 v[152:155], v34 offset:17408
	ds_read_b128 v[180:183], v34 offset:18432
	ds_read_b128 v[184:187], v34 offset:19456
	ds_read_b128 v[188:191], v34 offset:20480
	ds_read_b128 v[192:195], v34 offset:21504
	ds_read_b128 v[196:199], v34 offset:22528
	ds_read_b128 v[200:203], v34 offset:23552
	global_load_lds_dwordx4 v[134:135], off
	v_lshl_add_u64 v[136:137], s[40:41], 0, v[26:27]
	s_mov_b32 m0, s5
	s_nop 0
	global_load_lds_dwordx4 v[136:137], off
	s_barrier
	s_waitcnt lgkmcnt(0)
	s_nop 0
	s_waitcnt lgkmcnt(0)
	v_mfma_f32_16x16x32_bf16 v[156:159], v[116:119], v[148:151], v[156:159]
	v_mfma_f32_16x16x32_bf16 v[160:163], v[124:127], v[148:151], v[160:163]
	v_mfma_f32_16x16x32_bf16 v[164:167], v[116:119], v[180:183], v[164:167]
	v_mfma_f32_16x16x32_bf16 v[168:171], v[124:127], v[180:183], v[168:171]
	v_mfma_f32_16x16x32_bf16 v[172:175], v[116:119], v[188:191], v[172:175]
	v_mfma_f32_16x16x32_bf16 v[176:179], v[124:127], v[188:191], v[176:179]
	v_mfma_f32_16x16x32_bf16 v[0:3], v[116:119], v[196:199], v[0:3]
	v_mfma_f32_16x16x32_bf16 v[4:7], v[124:127], v[196:199], v[4:7]
	v_mfma_f32_16x16x32_bf16 v[156:159], v[120:123], v[152:155], v[156:159]
	v_mfma_f32_16x16x32_bf16 v[160:163], v[144:147], v[152:155], v[160:163]
	v_mfma_f32_16x16x32_bf16 v[164:167], v[120:123], v[184:187], v[164:167]
	v_mfma_f32_16x16x32_bf16 v[168:171], v[144:147], v[184:187], v[168:171]
	v_mfma_f32_16x16x32_bf16 v[172:175], v[120:123], v[192:195], v[172:175]
	v_mfma_f32_16x16x32_bf16 v[176:179], v[144:147], v[192:195], v[176:179]
	v_mfma_f32_16x16x32_bf16 v[0:3], v[120:123], v[200:203], v[0:3]
	v_mfma_f32_16x16x32_bf16 v[116:119], v[144:147], v[200:203], v[4:7]
	s_nop 0
	s_barrier
	s_mov_b64 s[14:15], 0x800
	s_mov_b32 m0, s20
	v_lshl_add_u64 v[4:5], v[130:131], 0, s[14:15]
	global_load_lds_dwordx4 v[4:5], off
	v_lshl_add_u64 v[4:5], v[132:133], 0, s[14:15]
	s_mov_b32 m0, s19
	s_nop 0
	global_load_lds_dwordx4 v[4:5], off
	s_waitcnt vmcnt(6)
	s_barrier
	s_nop 0
	v_mfma_f32_16x16x32_bf16 v[4:7], v[204:207], v[148:151], v[8:11]
	v_mfma_f32_16x16x32_bf16 v[8:11], v[208:211], v[152:155], v[4:7]
	v_mfma_f32_16x16x32_bf16 v[4:7], v[212:215], v[148:151], v[12:15]
	v_mfma_f32_16x16x32_bf16 v[12:15], v[216:219], v[152:155], v[4:7]
	v_mfma_f32_16x16x32_bf16 v[4:7], v[204:207], v[180:183], v[56:59]
	v_mfma_f32_16x16x32_bf16 v[56:59], v[208:211], v[184:187], v[4:7]
	v_mfma_f32_16x16x32_bf16 v[4:7], v[212:215], v[180:183], v[100:103]
	v_mfma_f32_16x16x32_bf16 v[100:103], v[216:219], v[184:187], v[4:7]
	v_mfma_f32_16x16x32_bf16 v[4:7], v[204:207], v[188:191], v[104:107]
	v_mfma_f32_16x16x32_bf16 v[104:107], v[208:211], v[192:195], v[4:7]
	v_mfma_f32_16x16x32_bf16 v[4:7], v[212:215], v[188:191], v[112:115]
	v_mfma_f32_16x16x32_bf16 v[112:115], v[216:219], v[192:195], v[4:7]
	v_mfma_f32_16x16x32_bf16 v[4:7], v[204:207], v[196:199], v[92:95]
	v_mfma_f32_16x16x32_bf16 v[92:95], v[208:211], v[200:203], v[4:7]
	v_mfma_f32_16x16x32_bf16 v[4:7], v[212:215], v[196:199], v[96:99]
	v_mfma_f32_16x16x32_bf16 v[96:99], v[216:219], v[200:203], v[4:7]
	s_nop 0
	s_barrier
	s_nop 4
	ds_read_b128 v[4:7], v139
	ds_read_b128 v[120:123], v139 offset:1024
	ds_read_b128 v[124:127], v139 offset:2048
	ds_read_b128 v[144:147], v139 offset:3072
	s_add_u32 s14, s40, 0x10000
	s_addc_u32 s15, s41, 0
	s_mov_b32 m0, s16
	v_lshl_add_u64 v[204:205], s[14:15], 0, v[28:29]
	ds_read_b128 v[148:151], v34 offset:32768
	ds_read_b128 v[152:155], v34 offset:33792
	ds_read_b128 v[180:183], v34 offset:34816
	ds_read_b128 v[184:187], v34 offset:35840
	ds_read_b128 v[188:191], v34 offset:36864
	ds_read_b128 v[192:195], v34 offset:37888
	ds_read_b128 v[196:199], v34 offset:38912
	ds_read_b128 v[200:203], v34 offset:39936
	global_load_lds_dwordx4 v[204:205], off
	v_lshl_add_u64 v[204:205], s[14:15], 0, v[26:27]
	s_mov_b32 m0, s17
	s_nop 0
	global_load_lds_dwordx4 v[204:205], off
	s_waitcnt lgkmcnt(8)
	s_barrier
	s_waitcnt lgkmcnt(0)
	s_nop 0
	s_waitcnt lgkmcnt(0)
	v_mfma_f32_16x16x32_bf16 v[60:63], v[4:7], v[148:151], v[60:63]
	v_mfma_f32_16x16x32_bf16 v[64:67], v[124:127], v[148:151], v[64:67]
	v_mfma_f32_16x16x32_bf16 v[68:71], v[4:7], v[180:183], v[68:71]
	v_mfma_f32_16x16x32_bf16 v[72:75], v[124:127], v[180:183], v[72:75]
	v_mfma_f32_16x16x32_bf16 v[76:79], v[4:7], v[188:191], v[76:79]
	v_mfma_f32_16x16x32_bf16 v[80:83], v[124:127], v[188:191], v[80:83]
	v_mfma_f32_16x16x32_bf16 v[84:87], v[4:7], v[196:199], v[84:87]
	v_mfma_f32_16x16x32_bf16 v[88:91], v[124:127], v[196:199], v[88:91]
	v_mfma_f32_16x16x32_bf16 v[60:63], v[120:123], v[152:155], v[60:63]
	v_mfma_f32_16x16x32_bf16 v[64:67], v[144:147], v[152:155], v[64:67]
	v_mfma_f32_16x16x32_bf16 v[68:71], v[120:123], v[184:187], v[68:71]
	v_mfma_f32_16x16x32_bf16 v[72:75], v[144:147], v[184:187], v[72:75]
	v_mfma_f32_16x16x32_bf16 v[76:79], v[120:123], v[192:195], v[76:79]
	v_mfma_f32_16x16x32_bf16 v[80:83], v[144:147], v[192:195], v[80:83]
	v_mfma_f32_16x16x32_bf16 v[84:87], v[120:123], v[200:203], v[84:87]
	v_mfma_f32_16x16x32_bf16 v[88:91], v[144:147], v[200:203], v[88:91]
	s_nop 0
	s_barrier
	s_mov_b32 m0, s49
	v_lshl_add_u64 v[220:221], v[130:131], 0, s[28:29]
	ds_read_b128 v[204:207], v140
	ds_read_b128 v[208:211], v140 offset:1024
	ds_read_b128 v[212:215], v140 offset:2048
	ds_read_b128 v[216:219], v140 offset:3072
	global_load_lds_dwordx4 v[220:221], off
	v_lshl_add_u64 v[220:221], v[132:133], 0, s[28:29]
	s_mov_b32 m0, s37
	s_nop 0
	global_load_lds_dwordx4 v[220:221], off
	s_barrier
	s_waitcnt lgkmcnt(0)
	s_nop 0
	s_waitcnt lgkmcnt(0)
	v_mfma_f32_16x16x32_bf16 v[16:19], v[212:215], v[148:151], v[16:19]
	v_mfma_f32_16x16x32_bf16 v[108:111], v[204:207], v[148:151], v[108:111]
	v_mfma_f32_16x16x32_bf16 v[148:151], v[216:219], v[152:155], v[16:19]
	v_mfma_f32_16x16x32_bf16 v[16:19], v[204:207], v[180:183], v[20:23]
	v_mfma_f32_16x16x32_bf16 v[108:111], v[208:211], v[152:155], v[108:111]
	v_mfma_f32_16x16x32_bf16 v[152:155], v[208:211], v[184:187], v[16:19]
	v_mfma_f32_16x16x32_bf16 v[16:19], v[212:215], v[180:183], v[36:39]
	v_mfma_f32_16x16x32_bf16 v[36:39], v[216:219], v[184:187], v[16:19]
	v_mfma_f32_16x16x32_bf16 v[16:19], v[204:207], v[188:191], v[40:43]
	v_mfma_f32_16x16x32_bf16 v[40:43], v[208:211], v[192:195], v[16:19]
	v_mfma_f32_16x16x32_bf16 v[16:19], v[212:215], v[188:191], v[44:47]
	v_mfma_f32_16x16x32_bf16 v[44:47], v[216:219], v[192:195], v[16:19]
	v_mfma_f32_16x16x32_bf16 v[16:19], v[204:207], v[196:199], v[48:51]
	v_mfma_f32_16x16x32_bf16 v[48:51], v[208:211], v[200:203], v[16:19]
	v_mfma_f32_16x16x32_bf16 v[16:19], v[212:215], v[196:199], v[52:55]
	v_mfma_f32_16x16x32_bf16 v[52:55], v[216:219], v[200:203], v[16:19]
	s_nop 0
	s_mov_b32 m0, s24
	s_nop 4
	v_lshl_add_u64 v[16:17], v[134:135], 0, s[28:29]
	s_barrier
	ds_read_b128 v[180:183], v34 offset:49152
	ds_read_b128 v[184:187], v34 offset:50176
	ds_read_b128 v[188:191], v34 offset:51200
	ds_read_b128 v[192:195], v34 offset:52224
	ds_read_b128 v[196:199], v34 offset:53248
	ds_read_b128 v[200:203], v34 offset:54272
	ds_read_b128 v[220:223], v34 offset:55296
	ds_read_b128 v[224:227], v34 offset:56320
	global_load_lds_dwordx4 v[16:17], off
	v_lshl_add_u64 v[16:17], v[136:137], 0, s[28:29]
	s_mov_b32 m0, s25
	s_nop 0
	global_load_lds_dwordx4 v[16:17], off
	s_barrier
	s_waitcnt lgkmcnt(0)
	s_nop 0
	s_waitcnt lgkmcnt(0)
	v_mfma_f32_16x16x32_bf16 v[16:19], v[4:7], v[180:183], v[156:159]
	v_mfma_f32_16x16x32_bf16 v[156:159], v[120:123], v[184:187], v[16:19]
	v_mfma_f32_16x16x32_bf16 v[16:19], v[124:127], v[180:183], v[160:163]
	v_mfma_f32_16x16x32_bf16 v[160:163], v[144:147], v[184:187], v[16:19]
	v_mfma_f32_16x16x32_bf16 v[16:19], v[4:7], v[188:191], v[164:167]
	v_mfma_f32_16x16x32_bf16 v[164:167], v[120:123], v[192:195], v[16:19]
	v_mfma_f32_16x16x32_bf16 v[16:19], v[124:127], v[188:191], v[168:171]
	v_mfma_f32_16x16x32_bf16 v[168:171], v[144:147], v[192:195], v[16:19]
	v_mfma_f32_16x16x32_bf16 v[16:19], v[4:7], v[196:199], v[172:175]
	v_mfma_f32_16x16x32_bf16 v[0:3], v[4:7], v[220:223], v[0:3]
	v_mfma_f32_16x16x32_bf16 v[20:23], v[120:123], v[200:203], v[16:19]
	v_mfma_f32_16x16x32_bf16 v[16:19], v[124:127], v[196:199], v[176:179]
	v_mfma_f32_16x16x32_bf16 v[4:7], v[120:123], v[224:227], v[0:3]
	v_mfma_f32_16x16x32_bf16 v[0:3], v[124:127], v[220:223], v[116:119]
	v_mfma_f32_16x16x32_bf16 v[16:19], v[144:147], v[200:203], v[16:19]
	v_mfma_f32_16x16x32_bf16 v[0:3], v[144:147], v[224:227], v[0:3]
	s_nop 0
	s_barrier
	s_mov_b64 s[14:15], 0x880
	s_mov_b32 m0, s48
	v_lshl_add_u64 v[116:117], v[130:131], 0, s[14:15]
	global_load_lds_dwordx4 v[116:117], off
	v_lshl_add_u64 v[116:117], v[132:133], 0, s[14:15]
	s_mov_b32 m0, s47
	s_nop 0
	global_load_lds_dwordx4 v[116:117], off
	s_waitcnt vmcnt(6)
	s_barrier
	s_nop 0
	v_mfma_f32_16x16x32_bf16 v[8:11], v[204:207], v[180:183], v[8:11]
	v_mfma_f32_16x16x32_bf16 v[116:119], v[208:211], v[184:187], v[8:11]
	v_mfma_f32_16x16x32_bf16 v[8:11], v[212:215], v[180:183], v[12:15]
	v_mfma_f32_16x16x32_bf16 v[120:123], v[216:219], v[184:187], v[8:11]
	v_mfma_f32_16x16x32_bf16 v[8:11], v[204:207], v[188:191], v[56:59]
	v_mfma_f32_16x16x32_bf16 v[56:59], v[208:211], v[192:195], v[8:11]
	v_mfma_f32_16x16x32_bf16 v[8:11], v[212:215], v[188:191], v[100:103]
	v_mfma_f32_16x16x32_bf16 v[100:103], v[216:219], v[192:195], v[8:11]
	v_mfma_f32_16x16x32_bf16 v[8:11], v[204:207], v[196:199], v[104:107]
	v_mfma_f32_16x16x32_bf16 v[104:107], v[208:211], v[200:203], v[8:11]
	v_mfma_f32_16x16x32_bf16 v[8:11], v[212:215], v[196:199], v[112:115]
	v_mfma_f32_16x16x32_bf16 v[112:115], v[216:219], v[200:203], v[8:11]
	v_mfma_f32_16x16x32_bf16 v[8:11], v[204:207], v[220:223], v[92:95]
	v_mfma_f32_16x16x32_bf16 v[12:15], v[208:211], v[224:227], v[8:11]
	v_mfma_f32_16x16x32_bf16 v[8:11], v[212:215], v[220:223], v[96:99]
	v_mfma_f32_16x16x32_bf16 v[8:11], v[216:219], v[224:227], v[8:11]
	v_mbcnt_lo_u32_b32 v228, -1, 0
	v_mbcnt_hi_u32_b32 v228, -1, v228
	v_and_b32_e32 v228, 16, v228
	v_lshrrev_b32_e32 v229, 1, v228
	v_add_u32_e32 v228, v228, v229
	v_mov_b32_e32 v229, 0
	s_nop 0
	s_lshl_b32 s13, s13, 2
	s_and_b32 s14, s13, 0xffffff00
	v_add_u32_e32 v92, s14, v32
	v_ashrrev_i32_e32 v93, 31, v92
	s_and_b32 s92, s13, 0xfc
	s_ashr_i32 s13, s12, 31
	v_lshlrev_b64 v[94:95], 8, v[92:93]
	v_lshl_add_u64 v[94:95], v[94:95], 0, s[12:13]
	v_lshl_add_u64 v[96:97], v[94:95], 0, s[92:93]
	v_lshlrev_b64 v[96:97], 8, v[96:97]
	v_lshl_add_u64 v[96:97], v[30:31], 0, v[96:97]
	s_barrier
	v_cvt_pk_bf16_f32 v244, v60, v61
	v_cvt_pk_bf16_f32 v245, v62, v63
	v_cvt_pk_bf16_f32 v246, v64, v65
	v_cvt_pk_bf16_f32 v247, v66, v67
	v_lshl_add_u64 v[96:97], v[96:97], 0, v[228:229]
	s_nop 0
	v_permlane16_swap_b32_e32 v244, v246
	v_permlane16_swap_b32_e32 v245, v247
	global_store_dwordx4 v[96:97], v[244:247], off
	s_nop 1
	s_or_b32 s14, s92, 2
	s_mov_b32 s15, s93
	v_lshl_add_u64 v[60:61], v[94:95], 0, s[14:15]
	v_lshlrev_b64 v[60:61], 8, v[60:61]
	v_lshl_add_u64 v[60:61], v[30:31], 0, v[60:61]
	v_cvt_pk_bf16_f32 v244, v108, v109
	v_cvt_pk_bf16_f32 v245, v110, v111
	v_cvt_pk_bf16_f32 v246, v148, v149
	v_cvt_pk_bf16_f32 v247, v150, v151
	v_lshl_add_u64 v[60:61], v[60:61], 0, v[228:229]
	s_nop 0
	v_permlane16_swap_b32_e32 v244, v246
	v_permlane16_swap_b32_e32 v245, v247
	global_store_dwordx4 v[60:61], v[244:247], off
	s_nop 1
	v_or_b32_e32 v60, 16, v92
	v_ashrrev_i32_e32 v61, 31, v60
	v_lshlrev_b64 v[60:61], 8, v[60:61]
	v_lshl_add_u64 v[60:61], v[60:61], 0, s[12:13]
	v_lshl_add_u64 v[62:63], v[60:61], 0, s[92:93]
	v_lshl_add_u64 v[60:61], v[60:61], 0, s[14:15]
	v_lshlrev_b64 v[60:61], 8, v[60:61]
	v_lshl_add_u64 v[60:61], v[30:31], 0, v[60:61]
	v_cvt_pk_bf16_f32 v244, v152, v153
	v_cvt_pk_bf16_f32 v245, v154, v155
	v_cvt_pk_bf16_f32 v246, v36, v37
	v_cvt_pk_bf16_f32 v247, v38, v39
	v_lshl_add_u64 v[60:61], v[60:61], 0, v[228:229]
	s_nop 0
	v_permlane16_swap_b32_e32 v244, v246
	v_permlane16_swap_b32_e32 v245, v247
	global_store_dwordx4 v[60:61], v[244:247], off
	s_nop 1
	v_or_b32_e32 v36, 32, v92
	v_ashrrev_i32_e32 v37, 31, v36
	v_lshlrev_b64 v[62:63], 8, v[62:63]
	v_lshlrev_b64 v[36:37], 8, v[36:37]
	v_lshl_add_u64 v[62:63], v[30:31], 0, v[62:63]
	v_lshl_add_u64 v[36:37], v[36:37], 0, s[12:13]
	v_cvt_pk_bf16_f32 v244, v68, v69
	v_cvt_pk_bf16_f32 v245, v70, v71
	v_cvt_pk_bf16_f32 v246, v72, v73
	v_cvt_pk_bf16_f32 v247, v74, v75
	v_lshl_add_u64 v[62:63], v[62:63], 0, v[228:229]
	s_nop 0
	v_permlane16_swap_b32_e32 v244, v246
	v_permlane16_swap_b32_e32 v245, v247
	global_store_dwordx4 v[62:63], v[244:247], off
	s_nop 1
	v_lshl_add_u64 v[38:39], v[36:37], 0, s[92:93]
	v_lshlrev_b64 v[38:39], 8, v[38:39]
	v_lshl_add_u64 v[38:39], v[30:31], 0, v[38:39]
	v_lshl_add_u64 v[36:37], v[36:37], 0, s[14:15]
	v_cvt_pk_bf16_f32 v244, v76, v77
	v_cvt_pk_bf16_f32 v245, v78, v79
	v_cvt_pk_bf16_f32 v246, v80, v81
	v_cvt_pk_bf16_f32 v247, v82, v83
	v_lshl_add_u64 v[38:39], v[38:39], 0, v[228:229]
	s_nop 0
	v_permlane16_swap_b32_e32 v244, v246
	v_permlane16_swap_b32_e32 v245, v247
	global_store_dwordx4 v[38:39], v[244:247], off
	s_nop 1
	v_lshlrev_b64 v[36:37], 8, v[36:37]
	v_lshl_add_u64 v[36:37], v[30:31], 0, v[36:37]
	v_cvt_pk_bf16_f32 v244, v40, v41
	v_cvt_pk_bf16_f32 v245, v42, v43
	v_cvt_pk_bf16_f32 v246, v44, v45
	v_cvt_pk_bf16_f32 v247, v46, v47
	v_lshl_add_u64 v[36:37], v[36:37], 0, v[228:229]
	s_nop 0
	v_permlane16_swap_b32_e32 v244, v246
	v_permlane16_swap_b32_e32 v245, v247
	global_store_dwordx4 v[36:37], v[244:247], off
	s_nop 1
	v_or_b32_e32 v36, 48, v92
	v_ashrrev_i32_e32 v37, 31, v36
	v_lshlrev_b64 v[36:37], 8, v[36:37]
	v_lshl_add_u64 v[36:37], v[36:37], 0, s[12:13]
	v_lshl_add_u64 v[38:39], v[36:37], 0, s[92:93]
	v_lshlrev_b64 v[38:39], 8, v[38:39]
	v_lshl_add_u64 v[38:39], v[30:31], 0, v[38:39]
	v_lshl_add_u64 v[36:37], v[36:37], 0, s[14:15]
	v_cvt_pk_bf16_f32 v244, v84, v85
	v_cvt_pk_bf16_f32 v245, v86, v87
	v_cvt_pk_bf16_f32 v246, v88, v89
	v_cvt_pk_bf16_f32 v247, v90, v91
	v_lshl_add_u64 v[38:39], v[38:39], 0, v[228:229]
	s_nop 0
	v_permlane16_swap_b32_e32 v244, v246
	v_permlane16_swap_b32_e32 v245, v247
	global_store_dwordx4 v[38:39], v[244:247], off
	s_nop 1
	v_lshlrev_b64 v[36:37], 8, v[36:37]
	v_lshl_add_u64 v[36:37], v[30:31], 0, v[36:37]
	v_cvt_pk_bf16_f32 v244, v48, v49
	v_cvt_pk_bf16_f32 v245, v50, v51
	v_cvt_pk_bf16_f32 v246, v52, v53
	v_cvt_pk_bf16_f32 v247, v54, v55
	v_lshl_add_u64 v[36:37], v[36:37], 0, v[228:229]
	s_nop 0
	v_permlane16_swap_b32_e32 v244, v246
	v_permlane16_swap_b32_e32 v245, v247
	global_store_dwordx4 v[36:37], v[244:247], off
	s_nop 1
	v_add_u32_e32 v36, 0x80, v92
	v_ashrrev_i32_e32 v37, 31, v36
	v_lshlrev_b64 v[36:37], 8, v[36:37]
	v_lshl_add_u64 v[36:37], v[36:37], 0, s[12:13]
	v_lshl_add_u64 v[38:39], v[36:37], 0, s[92:93]
	v_lshlrev_b64 v[38:39], 8, v[38:39]
	v_lshl_add_u64 v[38:39], v[30:31], 0, v[38:39]
	v_lshl_add_u64 v[36:37], v[36:37], 0, s[14:15]
	v_cvt_pk_bf16_f32 v244, v156, v157
	v_cvt_pk_bf16_f32 v245, v158, v159
	v_cvt_pk_bf16_f32 v246, v160, v161
	v_cvt_pk_bf16_f32 v247, v162, v163
	v_lshl_add_u64 v[38:39], v[38:39], 0, v[228:229]
	s_nop 0
	v_permlane16_swap_b32_e32 v244, v246
	v_permlane16_swap_b32_e32 v245, v247
	global_store_dwordx4 v[38:39], v[244:247], off
	s_nop 1
	v_lshlrev_b64 v[36:37], 8, v[36:37]
	v_lshl_add_u64 v[36:37], v[30:31], 0, v[36:37]
	v_cvt_pk_bf16_f32 v244, v116, v117
	v_cvt_pk_bf16_f32 v245, v118, v119
	v_cvt_pk_bf16_f32 v246, v120, v121
	v_cvt_pk_bf16_f32 v247, v122, v123
	v_lshl_add_u64 v[36:37], v[36:37], 0, v[228:229]
	s_nop 0
	v_permlane16_swap_b32_e32 v244, v246
	v_permlane16_swap_b32_e32 v245, v247
	global_store_dwordx4 v[36:37], v[244:247], off
	s_nop 1
	v_add_u32_e32 v36, 0x90, v92
	v_ashrrev_i32_e32 v37, 31, v36
	v_lshlrev_b64 v[36:37], 8, v[36:37]
	v_lshl_add_u64 v[36:37], v[36:37], 0, s[12:13]
	v_lshl_add_u64 v[38:39], v[36:37], 0, s[92:93]
	v_lshlrev_b64 v[38:39], 8, v[38:39]
	v_lshl_add_u64 v[38:39], v[30:31], 0, v[38:39]
	v_lshl_add_u64 v[36:37], v[36:37], 0, s[14:15]
	v_cvt_pk_bf16_f32 v244, v164, v165
	v_cvt_pk_bf16_f32 v245, v166, v167
	v_cvt_pk_bf16_f32 v246, v168, v169
	v_cvt_pk_bf16_f32 v247, v170, v171
	v_lshl_add_u64 v[38:39], v[38:39], 0, v[228:229]
	s_nop 0
	v_permlane16_swap_b32_e32 v244, v246
	v_permlane16_swap_b32_e32 v245, v247
	global_store_dwordx4 v[38:39], v[244:247], off
	s_nop 1
	v_lshlrev_b64 v[36:37], 8, v[36:37]
	v_lshl_add_u64 v[36:37], v[30:31], 0, v[36:37]
	v_cvt_pk_bf16_f32 v244, v56, v57
	v_cvt_pk_bf16_f32 v245, v58, v59
	v_cvt_pk_bf16_f32 v246, v100, v101
	v_cvt_pk_bf16_f32 v247, v102, v103
	v_lshl_add_u64 v[36:37], v[36:37], 0, v[228:229]
	s_nop 0
	v_permlane16_swap_b32_e32 v244, v246
	v_permlane16_swap_b32_e32 v245, v247
	global_store_dwordx4 v[36:37], v[244:247], off
	s_nop 1
	v_add_u32_e32 v36, 0xa0, v92
	v_ashrrev_i32_e32 v37, 31, v36
	v_lshlrev_b64 v[36:37], 8, v[36:37]
	v_lshl_add_u64 v[36:37], v[36:37], 0, s[12:13]
	v_lshl_add_u64 v[38:39], v[36:37], 0, s[92:93]
	v_lshlrev_b64 v[38:39], 8, v[38:39]
	v_lshl_add_u64 v[38:39], v[30:31], 0, v[38:39]
	v_cvt_pk_bf16_f32 v244, v20, v21
	v_cvt_pk_bf16_f32 v245, v22, v23
	v_cvt_pk_bf16_f32 v246, v16, v17
	v_cvt_pk_bf16_f32 v247, v18, v19
	v_lshl_add_u64 v[38:39], v[38:39], 0, v[228:229]
	s_nop 0
	v_permlane16_swap_b32_e32 v244, v246
	v_permlane16_swap_b32_e32 v245, v247
	global_store_dwordx4 v[38:39], v[244:247], off
	s_nop 1
	v_lshl_add_u64 v[16:17], v[36:37], 0, s[14:15]
	v_lshlrev_b64 v[16:17], 8, v[16:17]
	v_lshl_add_u64 v[16:17], v[30:31], 0, v[16:17]
	v_cvt_pk_bf16_f32 v244, v104, v105
	v_cvt_pk_bf16_f32 v245, v106, v107
	v_cvt_pk_bf16_f32 v246, v112, v113
	v_cvt_pk_bf16_f32 v247, v114, v115
	v_lshl_add_u64 v[16:17], v[16:17], 0, v[228:229]
	s_nop 0
	v_permlane16_swap_b32_e32 v244, v246
	v_permlane16_swap_b32_e32 v245, v247
	global_store_dwordx4 v[16:17], v[244:247], off
	s_nop 1
	v_add_u32_e32 v16, 0xb0, v92
	v_ashrrev_i32_e32 v17, 31, v16
	v_lshlrev_b64 v[16:17], 8, v[16:17]
	v_lshl_add_u64 v[16:17], v[16:17], 0, s[12:13]
	v_lshl_add_u64 v[18:19], v[16:17], 0, s[92:93]
	v_lshlrev_b64 v[18:19], 8, v[18:19]
	v_lshl_add_u64 v[18:19], v[30:31], 0, v[18:19]
	v_cvt_pk_bf16_f32 v244, v4, v5
	v_cvt_pk_bf16_f32 v245, v6, v7
	v_cvt_pk_bf16_f32 v246, v0, v1
	v_cvt_pk_bf16_f32 v247, v2, v3
	v_lshl_add_u64 v[18:19], v[18:19], 0, v[228:229]
	s_nop 0
	v_permlane16_swap_b32_e32 v244, v246
	v_permlane16_swap_b32_e32 v245, v247
	global_store_dwordx4 v[18:19], v[244:247], off
	s_nop 1
	v_lshl_add_u64 v[0:1], v[16:17], 0, s[14:15]
	v_lshlrev_b64 v[0:1], 8, v[0:1]
	v_lshl_add_u64 v[0:1], v[30:31], 0, v[0:1]
	v_cvt_pk_bf16_f32 v244, v12, v13
	v_cvt_pk_bf16_f32 v245, v14, v15
	v_cvt_pk_bf16_f32 v246, v8, v9
	v_cvt_pk_bf16_f32 v247, v10, v11
	v_lshl_add_u64 v[0:1], v[0:1], 0, v[228:229]
	s_nop 0
	v_permlane16_swap_b32_e32 v244, v246
	v_permlane16_swap_b32_e32 v245, v247
	global_store_dwordx4 v[0:1], v[244:247], off
	s_nop 1
	s_add_i32 s34, s34, s90
	s_andn2_b64 vcc, exec, s[38:39]
	s_mov_b32 s12, s30
	s_mov_b32 s13, s35
	s_mov_b64 s[18:19], s[42:43]
	s_mov_b64 s[14:15], s[44:45]
	v_readlane_b32 s20, v255, 27
	s_cbranch_vccz .LBB0_97

.LBB0_104:
	s_ashr_i32 s42, s35, 7
	s_ashr_i32 s43, s42, 31
	s_ashr_i32 s13, s12, 31
	s_lshl_b64 s[42:43], s[42:43], 18
	s_lshl_b64 s[46:47], s[12:13], 17
	v_readlane_b32 s48, v254, 55
	v_readlane_b32 s49, v254, 56
	s_add_u32 s13, s48, s42
	s_addc_u32 s20, s49, s43
	s_add_u32 s42, s13, s46
	s_addc_u32 s43, s20, s47
	s_and_b64 s[40:41], s[40:41], exec
	s_cselect_b32 s41, s43, s15
	s_cselect_b32 s40, s42, s14
	s_add_i32 s37, 16, 0x10000
	v_add_u32_e32 v69, s37, v67
	ds_read_b128 v[0:3], v69
	ds_read_b128 v[4:7], v69 offset:1024
	ds_read_b128 v[8:11], v69 offset:2048
	ds_read_b128 v[12:15], v69 offset:3072
	s_add_u32 s48, s14, 0x10080
	s_addc_u32 s49, s15, 0
	s_add_i32 s46, s4, 0xc000
	v_lshl_add_u64 v[48:49], s[48:49], 0, v[62:63]
	s_mov_b32 m0, s46
	s_add_i32 s13, s4, 0xe000
	ds_read_b128 v[16:19], v68
	ds_read_b128 v[20:23], v68 offset:1024
	ds_read_b128 v[24:27], v68 offset:2048
	ds_read_b128 v[28:31], v68 offset:3072
	ds_read_b128 v[32:35], v68 offset:4096
	ds_read_b128 v[36:39], v68 offset:5120
	ds_read_b128 v[40:43], v68 offset:6144
	ds_read_b128 v[44:47], v68 offset:7168
	global_load_lds_dwordx4 v[48:49], off
	v_lshl_add_u64 v[48:49], s[48:49], 0, v[58:59]
	s_mov_b32 m0, s13
	s_nop 0
	global_load_lds_dwordx4 v[48:49], off
	s_waitcnt lgkmcnt(8)
	s_barrier
	s_waitcnt lgkmcnt(0)
	s_nop 0
	s_waitcnt lgkmcnt(0)
	v_mfma_f32_16x16x32_bf16 v[48:51], v[0:3], v[16:19], 0
	v_mfma_f32_16x16x32_bf16 v[52:55], v[8:11], v[16:19], 0
	v_mfma_f32_16x16x32_bf16 v[70:73], v[0:3], v[24:27], 0
	v_mfma_f32_16x16x32_bf16 v[74:77], v[8:11], v[24:27], 0
	v_mfma_f32_16x16x32_bf16 v[78:81], v[0:3], v[32:35], 0
	v_mfma_f32_16x16x32_bf16 v[82:85], v[8:11], v[32:35], 0
	v_mfma_f32_16x16x32_bf16 v[86:89], v[0:3], v[40:43], 0
	v_mfma_f32_16x16x32_bf16 v[90:93], v[8:11], v[40:43], 0
	v_mfma_f32_16x16x32_bf16 v[48:51], v[4:7], v[20:23], v[48:51]
	v_mfma_f32_16x16x32_bf16 v[52:55], v[12:15], v[20:23], v[52:55]
	v_mfma_f32_16x16x32_bf16 v[70:73], v[4:7], v[28:31], v[70:73]
	v_mfma_f32_16x16x32_bf16 v[74:77], v[12:15], v[28:31], v[74:77]
	v_mfma_f32_16x16x32_bf16 v[78:81], v[4:7], v[36:39], v[78:81]
	v_mfma_f32_16x16x32_bf16 v[82:85], v[12:15], v[36:39], v[82:85]
	v_mfma_f32_16x16x32_bf16 v[86:89], v[4:7], v[44:47], v[86:89]
	v_mfma_f32_16x16x32_bf16 v[90:93], v[12:15], v[44:47], v[90:93]
	s_nop 0
	s_barrier
	s_add_i32 s20, 16, 0x14000
	v_lshl_add_u64 v[64:65], s[18:19], 0, v[60:61]
	s_mov_b64 s[48:49], 0x100
	s_add_i32 s37, s37, s1
	v_add_u32_e32 v136, s20, v67
	v_lshl_add_u64 v[110:111], v[64:65], 0, s[48:49]
	s_mov_b32 m0, s37
	v_lshl_add_u64 v[126:127], s[18:19], 0, v[56:57]
	s_add_i32 s18, s37, 0x2000
	ds_read_b128 v[94:97], v136
	ds_read_b128 v[98:101], v136 offset:1024
	ds_read_b128 v[102:105], v136 offset:2048
	ds_read_b128 v[106:109], v136 offset:3072
	global_load_lds_dwordx4 v[110:111], off
	v_lshl_add_u64 v[110:111], v[126:127], 0, s[48:49]
	s_mov_b32 m0, s18
	s_nop 0
	global_load_lds_dwordx4 v[110:111], off
	s_barrier
	s_waitcnt lgkmcnt(0)
	s_nop 0
	s_waitcnt lgkmcnt(0)
	v_mfma_f32_16x16x32_bf16 v[110:113], v[94:97], v[16:19], 0
	v_mfma_f32_16x16x32_bf16 v[16:19], v[102:105], v[16:19], 0
	v_mfma_f32_16x16x32_bf16 v[110:113], v[98:101], v[20:23], v[110:113]
	v_mfma_f32_16x16x32_bf16 v[16:19], v[106:109], v[20:23], v[16:19]
	v_mfma_f32_16x16x32_bf16 v[20:23], v[94:97], v[24:27], 0
	v_mfma_f32_16x16x32_bf16 v[24:27], v[102:105], v[24:27], 0
	v_mfma_f32_16x16x32_bf16 v[20:23], v[98:101], v[28:31], v[20:23]
	v_mfma_f32_16x16x32_bf16 v[24:27], v[106:109], v[28:31], v[24:27]
	v_mfma_f32_16x16x32_bf16 v[28:31], v[94:97], v[32:35], 0
	v_mfma_f32_16x16x32_bf16 v[32:35], v[102:105], v[32:35], 0
	v_mfma_f32_16x16x32_bf16 v[28:31], v[98:101], v[36:39], v[28:31]
	v_mfma_f32_16x16x32_bf16 v[32:35], v[106:109], v[36:39], v[32:35]
	v_mfma_f32_16x16x32_bf16 v[36:39], v[94:97], v[40:43], 0
	v_mfma_f32_16x16x32_bf16 v[40:43], v[102:105], v[40:43], 0
	v_mfma_f32_16x16x32_bf16 v[36:39], v[98:101], v[44:47], v[36:39]
	v_mfma_f32_16x16x32_bf16 v[40:43], v[106:109], v[44:47], v[40:43]
	s_nop 0
	v_lshl_add_u64 v[130:131], s[14:15], 0, v[62:63]
	s_mov_b32 m0, s4
	v_lshl_add_u64 v[132:133], v[130:131], 0, s[48:49]
	s_barrier
	ds_read_b128 v[44:47], v68 offset:16384
	ds_read_b128 v[114:117], v68 offset:17408
	ds_read_b128 v[118:121], v68 offset:18432
	ds_read_b128 v[122:125], v68 offset:19456
	ds_read_b128 v[144:147], v68 offset:20480
	ds_read_b128 v[148:151], v68 offset:21504
	ds_read_b128 v[152:155], v68 offset:22528
	ds_read_b128 v[156:159], v68 offset:23552
	global_load_lds_dwordx4 v[132:133], off
	v_lshl_add_u64 v[132:133], s[14:15], 0, v[58:59]
	v_lshl_add_u64 v[134:135], v[132:133], 0, s[48:49]
	s_mov_b32 m0, s5
	s_nop 0
	global_load_lds_dwordx4 v[134:135], off
	s_barrier
	s_waitcnt lgkmcnt(0)
	s_nop 0
	s_waitcnt lgkmcnt(0)
	v_mfma_f32_16x16x32_bf16 v[160:163], v[0:3], v[44:47], 0
	v_mfma_f32_16x16x32_bf16 v[168:171], v[0:3], v[118:121], 0
	v_mfma_f32_16x16x32_bf16 v[176:179], v[0:3], v[144:147], 0
	v_mfma_f32_16x16x32_bf16 v[0:3], v[0:3], v[152:155], 0
	v_mfma_f32_16x16x32_bf16 v[160:163], v[4:7], v[114:117], v[160:163]
	v_mfma_f32_16x16x32_bf16 v[164:167], v[8:11], v[44:47], 0
	v_mfma_f32_16x16x32_bf16 v[168:171], v[4:7], v[122:125], v[168:171]
	v_mfma_f32_16x16x32_bf16 v[172:175], v[8:11], v[118:121], 0
	v_mfma_f32_16x16x32_bf16 v[176:179], v[4:7], v[148:151], v[176:179]
	v_mfma_f32_16x16x32_bf16 v[180:183], v[8:11], v[144:147], 0
	v_mfma_f32_16x16x32_bf16 v[0:3], v[4:7], v[156:159], v[0:3]
	v_mfma_f32_16x16x32_bf16 v[4:7], v[8:11], v[152:155], 0
	v_mfma_f32_16x16x32_bf16 v[164:167], v[12:15], v[114:117], v[164:167]
	v_mfma_f32_16x16x32_bf16 v[172:175], v[12:15], v[122:125], v[172:175]
	v_mfma_f32_16x16x32_bf16 v[180:183], v[12:15], v[148:151], v[180:183]
	v_mfma_f32_16x16x32_bf16 v[4:7], v[12:15], v[156:159], v[4:7]
	s_nop 0
	s_barrier
	s_mov_b64 s[48:49], 0x900
	s_add_i32 s20, s20, s1
	v_lshl_add_u64 v[8:9], v[64:65], 0, s[48:49]
	s_mov_b32 m0, s20
	s_add_i32 s19, s20, 0x2000
	global_load_lds_dwordx4 v[8:9], off
	v_lshl_add_u64 v[8:9], v[126:127], 0, s[48:49]
	s_mov_b32 m0, s19
	s_nop 0
	global_load_lds_dwordx4 v[8:9], off
	s_waitcnt vmcnt(6)
	s_barrier
	s_nop 0
	v_mfma_f32_16x16x32_bf16 v[8:11], v[94:97], v[44:47], 0
	v_mfma_f32_16x16x32_bf16 v[12:15], v[102:105], v[44:47], 0
	v_mfma_f32_16x16x32_bf16 v[8:11], v[98:101], v[114:117], v[8:11]
	v_mfma_f32_16x16x32_bf16 v[12:15], v[106:109], v[114:117], v[12:15]
	v_mfma_f32_16x16x32_bf16 v[44:47], v[94:97], v[118:121], 0
	v_mfma_f32_16x16x32_bf16 v[114:117], v[102:105], v[118:121], 0
	v_mfma_f32_16x16x32_bf16 v[118:121], v[94:97], v[144:147], 0
	v_mfma_f32_16x16x32_bf16 v[94:97], v[94:97], v[152:155], 0
	v_mfma_f32_16x16x32_bf16 v[44:47], v[98:101], v[122:125], v[44:47]
	v_mfma_f32_16x16x32_bf16 v[114:117], v[106:109], v[122:125], v[114:117]
	v_mfma_f32_16x16x32_bf16 v[118:121], v[98:101], v[148:151], v[118:121]
	v_mfma_f32_16x16x32_bf16 v[122:125], v[102:105], v[144:147], 0
	v_mfma_f32_16x16x32_bf16 v[94:97], v[98:101], v[156:159], v[94:97]
	v_mfma_f32_16x16x32_bf16 v[98:101], v[102:105], v[152:155], 0
	v_mfma_f32_16x16x32_bf16 v[122:125], v[106:109], v[148:151], v[122:125]
	v_mfma_f32_16x16x32_bf16 v[98:101], v[106:109], v[156:159], v[98:101]
	s_nop 0
	s_add_i32 s45, 16, 0x18000
	v_add_u32_e32 v137, s45, v67
	s_barrier
	ds_read_b128 v[102:105], v137
	ds_read_b128 v[106:109], v137 offset:1024
	ds_read_b128 v[144:147], v137 offset:2048
	ds_read_b128 v[148:151], v137 offset:3072
	s_add_u32 s48, s14, 0x10100
	s_addc_u32 s49, s15, 0
	s_mov_b32 m0, s16
	v_lshl_add_u64 v[134:135], s[48:49], 0, v[62:63]
	ds_read_b128 v[152:155], v68 offset:32768
	ds_read_b128 v[156:159], v68 offset:33792
	ds_read_b128 v[184:187], v68 offset:34816
	ds_read_b128 v[188:191], v68 offset:35840
	ds_read_b128 v[192:195], v68 offset:36864
	ds_read_b128 v[196:199], v68 offset:37888
	ds_read_b128 v[200:203], v68 offset:38912
	ds_read_b128 v[204:207], v68 offset:39936
	global_load_lds_dwordx4 v[134:135], off
	v_lshl_add_u64 v[134:135], s[48:49], 0, v[58:59]
	s_mov_b32 m0, s17
	s_nop 0
	global_load_lds_dwordx4 v[134:135], off
	s_waitcnt lgkmcnt(8)
	s_barrier
	s_waitcnt lgkmcnt(0)
	s_nop 0
	s_waitcnt lgkmcnt(0)
	v_mfma_f32_16x16x32_bf16 v[48:51], v[102:105], v[152:155], v[48:51]
	v_mfma_f32_16x16x32_bf16 v[52:55], v[144:147], v[152:155], v[52:55]
	v_mfma_f32_16x16x32_bf16 v[70:73], v[102:105], v[184:187], v[70:73]
	v_mfma_f32_16x16x32_bf16 v[74:77], v[144:147], v[184:187], v[74:77]
	v_mfma_f32_16x16x32_bf16 v[78:81], v[102:105], v[192:195], v[78:81]
	v_mfma_f32_16x16x32_bf16 v[82:85], v[144:147], v[192:195], v[82:85]
	v_mfma_f32_16x16x32_bf16 v[86:89], v[102:105], v[200:203], v[86:89]
	v_mfma_f32_16x16x32_bf16 v[90:93], v[144:147], v[200:203], v[90:93]
	v_mfma_f32_16x16x32_bf16 v[48:51], v[106:109], v[156:159], v[48:51]
	v_mfma_f32_16x16x32_bf16 v[52:55], v[148:151], v[156:159], v[52:55]
	v_mfma_f32_16x16x32_bf16 v[70:73], v[106:109], v[188:191], v[70:73]
	v_mfma_f32_16x16x32_bf16 v[74:77], v[148:151], v[188:191], v[74:77]
	v_mfma_f32_16x16x32_bf16 v[78:81], v[106:109], v[196:199], v[78:81]
	v_mfma_f32_16x16x32_bf16 v[82:85], v[148:151], v[196:199], v[82:85]
	v_mfma_f32_16x16x32_bf16 v[86:89], v[106:109], v[204:207], v[86:89]
	v_mfma_f32_16x16x32_bf16 v[90:93], v[148:151], v[204:207], v[90:93]
	s_nop 0
	s_barrier
	s_add_i32 s48, 16, 0x1c000
	s_mov_b64 s[50:51], 0x180
	s_add_i32 s49, s45, s1
	v_add_u32_e32 v138, s48, v67
	v_lshl_add_u64 v[134:135], v[64:65], 0, s[50:51]
	s_mov_b32 m0, s49
	s_add_i32 s45, s49, 0x2000
	ds_read_b128 v[208:211], v138
	ds_read_b128 v[212:215], v138 offset:1024
	ds_read_b128 v[216:219], v138 offset:2048
	ds_read_b128 v[220:223], v138 offset:3072
	global_load_lds_dwordx4 v[134:135], off
	v_lshl_add_u64 v[134:135], v[126:127], 0, s[50:51]
	s_mov_b32 m0, s45
	s_nop 0
	global_load_lds_dwordx4 v[134:135], off
	s_barrier
	s_waitcnt lgkmcnt(0)
	s_nop 0
	s_waitcnt lgkmcnt(0)
	v_mfma_f32_16x16x32_bf16 v[110:113], v[208:211], v[152:155], v[110:113]
	v_mfma_f32_16x16x32_bf16 v[16:19], v[216:219], v[152:155], v[16:19]
	v_mfma_f32_16x16x32_bf16 v[20:23], v[208:211], v[184:187], v[20:23]
	v_mfma_f32_16x16x32_bf16 v[24:27], v[216:219], v[184:187], v[24:27]
	v_mfma_f32_16x16x32_bf16 v[28:31], v[208:211], v[192:195], v[28:31]
	v_mfma_f32_16x16x32_bf16 v[32:35], v[216:219], v[192:195], v[32:35]
	v_mfma_f32_16x16x32_bf16 v[36:39], v[208:211], v[200:203], v[36:39]
	v_mfma_f32_16x16x32_bf16 v[40:43], v[216:219], v[200:203], v[40:43]
	v_mfma_f32_16x16x32_bf16 v[110:113], v[212:215], v[156:159], v[110:113]
	v_mfma_f32_16x16x32_bf16 v[16:19], v[220:223], v[156:159], v[16:19]
	v_mfma_f32_16x16x32_bf16 v[20:23], v[212:215], v[188:191], v[20:23]
	v_mfma_f32_16x16x32_bf16 v[24:27], v[220:223], v[188:191], v[24:27]
	v_mfma_f32_16x16x32_bf16 v[28:31], v[212:215], v[196:199], v[28:31]
	v_mfma_f32_16x16x32_bf16 v[32:35], v[220:223], v[196:199], v[32:35]
	v_mfma_f32_16x16x32_bf16 v[36:39], v[212:215], v[204:207], v[36:39]
	v_mfma_f32_16x16x32_bf16 v[40:43], v[220:223], v[204:207], v[40:43]
	s_nop 0
	s_mov_b32 m0, s24
	v_lshl_add_u64 v[130:131], v[130:131], 0, s[50:51]
	s_barrier
	ds_read_b128 v[152:155], v68 offset:49152
	ds_read_b128 v[156:159], v68 offset:50176
	ds_read_b128 v[184:187], v68 offset:51200
	ds_read_b128 v[188:191], v68 offset:52224
	ds_read_b128 v[192:195], v68 offset:53248
	ds_read_b128 v[196:199], v68 offset:54272
	ds_read_b128 v[200:203], v68 offset:55296
	ds_read_b128 v[204:207], v68 offset:56320
	global_load_lds_dwordx4 v[130:131], off
	v_lshl_add_u64 v[130:131], v[132:133], 0, s[50:51]
	s_mov_b32 m0, s25
	s_nop 0
	global_load_lds_dwordx4 v[130:131], off
	s_barrier
	s_waitcnt lgkmcnt(0)
	s_nop 0
	s_waitcnt lgkmcnt(0)
	v_mfma_f32_16x16x32_bf16 v[160:163], v[102:105], v[152:155], v[160:163]
	v_mfma_f32_16x16x32_bf16 v[164:167], v[144:147], v[152:155], v[164:167]
	v_mfma_f32_16x16x32_bf16 v[168:171], v[102:105], v[184:187], v[168:171]
	v_mfma_f32_16x16x32_bf16 v[172:175], v[144:147], v[184:187], v[172:175]
	v_mfma_f32_16x16x32_bf16 v[176:179], v[102:105], v[192:195], v[176:179]
	v_mfma_f32_16x16x32_bf16 v[180:183], v[144:147], v[192:195], v[180:183]
	v_mfma_f32_16x16x32_bf16 v[0:3], v[102:105], v[200:203], v[0:3]
	v_mfma_f32_16x16x32_bf16 v[4:7], v[144:147], v[200:203], v[4:7]
	v_mfma_f32_16x16x32_bf16 v[160:163], v[106:109], v[156:159], v[160:163]
	v_mfma_f32_16x16x32_bf16 v[164:167], v[148:151], v[156:159], v[164:167]
	v_mfma_f32_16x16x32_bf16 v[168:171], v[106:109], v[188:191], v[168:171]
	v_mfma_f32_16x16x32_bf16 v[172:175], v[148:151], v[188:191], v[172:175]
	v_mfma_f32_16x16x32_bf16 v[176:179], v[106:109], v[196:199], v[176:179]
	v_mfma_f32_16x16x32_bf16 v[180:183], v[148:151], v[196:199], v[180:183]
	v_mfma_f32_16x16x32_bf16 v[0:3], v[106:109], v[204:207], v[0:3]
	v_mfma_f32_16x16x32_bf16 v[4:7], v[148:151], v[204:207], v[4:7]
	s_nop 0
	s_barrier
	s_mov_b64 s[50:51], 0x980
	s_add_i32 s48, s48, s1
	v_lshl_add_u64 v[64:65], v[64:65], 0, s[50:51]
	s_mov_b32 m0, s48
	s_add_i32 s47, s48, 0x2000
	global_load_lds_dwordx4 v[64:65], off
	v_lshl_add_u64 v[64:65], v[126:127], 0, s[50:51]
	s_mov_b32 m0, s47
	s_nop 0
	global_load_lds_dwordx4 v[64:65], off
	s_waitcnt vmcnt(6)
	s_barrier
	s_nop 0
	v_mfma_f32_16x16x32_bf16 v[8:11], v[208:211], v[152:155], v[8:11]
	v_mfma_f32_16x16x32_bf16 v[12:15], v[216:219], v[152:155], v[12:15]
	v_mfma_f32_16x16x32_bf16 v[44:47], v[208:211], v[184:187], v[44:47]
	v_mfma_f32_16x16x32_bf16 v[102:105], v[216:219], v[184:187], v[114:117]
	v_mfma_f32_16x16x32_bf16 v[106:109], v[208:211], v[192:195], v[118:121]
	v_mfma_f32_16x16x32_bf16 v[114:117], v[216:219], v[192:195], v[122:125]
	v_mfma_f32_16x16x32_bf16 v[94:97], v[208:211], v[200:203], v[94:97]
	v_mfma_f32_16x16x32_bf16 v[98:101], v[216:219], v[200:203], v[98:101]
	v_mfma_f32_16x16x32_bf16 v[8:11], v[212:215], v[156:159], v[8:11]
	v_mfma_f32_16x16x32_bf16 v[12:15], v[220:223], v[156:159], v[12:15]
	v_mfma_f32_16x16x32_bf16 v[44:47], v[212:215], v[188:191], v[44:47]
	v_mfma_f32_16x16x32_bf16 v[102:105], v[220:223], v[188:191], v[102:105]
	v_mfma_f32_16x16x32_bf16 v[106:109], v[212:215], v[196:199], v[106:109]
	v_mfma_f32_16x16x32_bf16 v[114:117], v[220:223], v[196:199], v[114:117]
	v_mfma_f32_16x16x32_bf16 v[94:97], v[212:215], v[204:207], v[94:97]
	v_mfma_f32_16x16x32_bf16 v[98:101], v[220:223], v[204:207], v[98:101]
	s_nop 0
	s_barrier
	ds_read_b128 v[118:121], v69
	ds_read_b128 v[122:125], v69 offset:1024
	ds_read_b128 v[144:147], v69 offset:2048
	ds_read_b128 v[148:151], v69 offset:3072
	s_add_u32 s14, s14, 0x10180
	s_addc_u32 s15, s15, 0
	s_mov_b32 m0, s46
	v_lshl_add_u64 v[64:65], s[14:15], 0, v[62:63]
	ds_read_b128 v[152:155], v68
	ds_read_b128 v[156:159], v68 offset:1024
	ds_read_b128 v[184:187], v68 offset:2048
	ds_read_b128 v[188:191], v68 offset:3072
	ds_read_b128 v[192:195], v68 offset:4096
	ds_read_b128 v[196:199], v68 offset:5120
	ds_read_b128 v[200:203], v68 offset:6144
	ds_read_b128 v[204:207], v68 offset:7168
	global_load_lds_dwordx4 v[64:65], off
	v_lshl_add_u64 v[64:65], s[14:15], 0, v[58:59]
	s_mov_b32 m0, s13
	s_nop 0
	global_load_lds_dwordx4 v[64:65], off
	s_waitcnt lgkmcnt(8)
	s_barrier
	s_waitcnt lgkmcnt(0)
	s_nop 0
	s_waitcnt lgkmcnt(0)
	v_mfma_f32_16x16x32_bf16 v[48:51], v[118:121], v[152:155], v[48:51]
	v_mfma_f32_16x16x32_bf16 v[52:55], v[144:147], v[152:155], v[52:55]
	v_mfma_f32_16x16x32_bf16 v[70:73], v[118:121], v[184:187], v[70:73]
	v_mfma_f32_16x16x32_bf16 v[74:77], v[144:147], v[184:187], v[74:77]
	v_mfma_f32_16x16x32_bf16 v[78:81], v[118:121], v[192:195], v[78:81]
	v_mfma_f32_16x16x32_bf16 v[82:85], v[144:147], v[192:195], v[82:85]
	v_mfma_f32_16x16x32_bf16 v[86:89], v[118:121], v[200:203], v[86:89]
	v_mfma_f32_16x16x32_bf16 v[90:93], v[144:147], v[200:203], v[90:93]
	v_mfma_f32_16x16x32_bf16 v[48:51], v[122:125], v[156:159], v[48:51]
	v_mfma_f32_16x16x32_bf16 v[52:55], v[148:151], v[156:159], v[52:55]
	v_mfma_f32_16x16x32_bf16 v[70:73], v[122:125], v[188:191], v[70:73]
	v_mfma_f32_16x16x32_bf16 v[74:77], v[148:151], v[188:191], v[74:77]
	v_mfma_f32_16x16x32_bf16 v[78:81], v[122:125], v[196:199], v[78:81]
	v_mfma_f32_16x16x32_bf16 v[82:85], v[148:151], v[196:199], v[82:85]
	v_mfma_f32_16x16x32_bf16 v[86:89], v[122:125], v[204:207], v[86:89]
	v_mfma_f32_16x16x32_bf16 v[90:93], v[148:151], v[204:207], v[90:93]
	s_nop 0
	s_barrier
	s_mov_b32 m0, s37
	v_lshl_add_u64 v[64:65], s[30:31], 0, v[60:61]
	ds_read_b128 v[208:211], v136
	ds_read_b128 v[212:215], v136 offset:1024
	ds_read_b128 v[216:219], v136 offset:2048
	ds_read_b128 v[220:223], v136 offset:3072
	global_load_lds_dwordx4 v[64:65], off
	v_lshl_add_u64 v[126:127], s[30:31], 0, v[56:57]
	s_mov_b32 m0, s18
	s_nop 0
	global_load_lds_dwordx4 v[126:127], off
	s_barrier
	s_waitcnt lgkmcnt(0)
	s_nop 0
	s_waitcnt lgkmcnt(0)
	v_mfma_f32_16x16x32_bf16 v[110:113], v[208:211], v[152:155], v[110:113]
	v_mfma_f32_16x16x32_bf16 v[16:19], v[216:219], v[152:155], v[16:19]
	v_mfma_f32_16x16x32_bf16 v[20:23], v[208:211], v[184:187], v[20:23]
	v_mfma_f32_16x16x32_bf16 v[24:27], v[216:219], v[184:187], v[24:27]
	v_mfma_f32_16x16x32_bf16 v[28:31], v[208:211], v[192:195], v[28:31]
	v_mfma_f32_16x16x32_bf16 v[32:35], v[216:219], v[192:195], v[32:35]
	v_mfma_f32_16x16x32_bf16 v[36:39], v[208:211], v[200:203], v[36:39]
	v_mfma_f32_16x16x32_bf16 v[40:43], v[216:219], v[200:203], v[40:43]
	v_mfma_f32_16x16x32_bf16 v[110:113], v[212:215], v[156:159], v[110:113]
	v_mfma_f32_16x16x32_bf16 v[16:19], v[220:223], v[156:159], v[16:19]
	v_mfma_f32_16x16x32_bf16 v[20:23], v[212:215], v[188:191], v[20:23]
	v_mfma_f32_16x16x32_bf16 v[24:27], v[220:223], v[188:191], v[24:27]
	v_mfma_f32_16x16x32_bf16 v[28:31], v[212:215], v[196:199], v[28:31]
	v_mfma_f32_16x16x32_bf16 v[32:35], v[220:223], v[196:199], v[32:35]
	v_mfma_f32_16x16x32_bf16 v[36:39], v[212:215], v[204:207], v[36:39]
	v_mfma_f32_16x16x32_bf16 v[40:43], v[220:223], v[204:207], v[40:43]
	s_nop 0
	s_mov_b32 m0, s4
	v_lshl_add_u64 v[130:131], s[40:41], 0, v[62:63]
	s_barrier
	ds_read_b128 v[152:155], v68 offset:16384
	ds_read_b128 v[156:159], v68 offset:17408
	ds_read_b128 v[184:187], v68 offset:18432
	ds_read_b128 v[188:191], v68 offset:19456
	ds_read_b128 v[192:195], v68 offset:20480
	ds_read_b128 v[196:199], v68 offset:21504
	ds_read_b128 v[200:203], v68 offset:22528
	ds_read_b128 v[204:207], v68 offset:23552
	global_load_lds_dwordx4 v[130:131], off
	v_lshl_add_u64 v[132:133], s[40:41], 0, v[58:59]
	s_mov_b32 m0, s5
	s_nop 0
	global_load_lds_dwordx4 v[132:133], off
	s_barrier
	s_waitcnt lgkmcnt(0)
	s_nop 0
	s_waitcnt lgkmcnt(0)
	v_mfma_f32_16x16x32_bf16 v[160:163], v[118:121], v[152:155], v[160:163]
	v_mfma_f32_16x16x32_bf16 v[164:167], v[144:147], v[152:155], v[164:167]
	v_mfma_f32_16x16x32_bf16 v[168:171], v[118:121], v[184:187], v[168:171]
	v_mfma_f32_16x16x32_bf16 v[172:175], v[144:147], v[184:187], v[172:175]
	v_mfma_f32_16x16x32_bf16 v[176:179], v[118:121], v[192:195], v[176:179]
	v_mfma_f32_16x16x32_bf16 v[180:183], v[144:147], v[192:195], v[180:183]
	v_mfma_f32_16x16x32_bf16 v[0:3], v[118:121], v[200:203], v[0:3]
	v_mfma_f32_16x16x32_bf16 v[4:7], v[144:147], v[200:203], v[4:7]
	v_mfma_f32_16x16x32_bf16 v[160:163], v[122:125], v[156:159], v[160:163]
	v_mfma_f32_16x16x32_bf16 v[164:167], v[148:151], v[156:159], v[164:167]
	v_mfma_f32_16x16x32_bf16 v[168:171], v[122:125], v[188:191], v[168:171]
	v_mfma_f32_16x16x32_bf16 v[172:175], v[148:151], v[188:191], v[172:175]
	v_mfma_f32_16x16x32_bf16 v[176:179], v[122:125], v[196:199], v[176:179]
	v_mfma_f32_16x16x32_bf16 v[180:183], v[148:151], v[196:199], v[180:183]
	v_mfma_f32_16x16x32_bf16 v[0:3], v[122:125], v[204:207], v[0:3]
	v_mfma_f32_16x16x32_bf16 v[118:121], v[148:151], v[204:207], v[4:7]
	s_nop 0
	s_barrier
	s_mov_b64 s[14:15], 0x800
	s_mov_b32 m0, s20
	v_lshl_add_u64 v[4:5], v[64:65], 0, s[14:15]
	global_load_lds_dwordx4 v[4:5], off
	v_lshl_add_u64 v[4:5], v[126:127], 0, s[14:15]
	s_mov_b32 m0, s19
	s_nop 0
	global_load_lds_dwordx4 v[4:5], off
	s_waitcnt vmcnt(6)
	s_barrier
	s_nop 0
	v_mfma_f32_16x16x32_bf16 v[4:7], v[208:211], v[152:155], v[8:11]
	v_mfma_f32_16x16x32_bf16 v[8:11], v[212:215], v[156:159], v[4:7]
	v_mfma_f32_16x16x32_bf16 v[4:7], v[216:219], v[152:155], v[12:15]
	v_mfma_f32_16x16x32_bf16 v[12:15], v[220:223], v[156:159], v[4:7]
	v_mfma_f32_16x16x32_bf16 v[4:7], v[208:211], v[184:187], v[44:47]
	v_mfma_f32_16x16x32_bf16 v[44:47], v[212:215], v[188:191], v[4:7]
	v_mfma_f32_16x16x32_bf16 v[4:7], v[216:219], v[184:187], v[102:105]
	v_mfma_f32_16x16x32_bf16 v[102:105], v[220:223], v[188:191], v[4:7]
	v_mfma_f32_16x16x32_bf16 v[4:7], v[208:211], v[192:195], v[106:109]
	v_mfma_f32_16x16x32_bf16 v[106:109], v[212:215], v[196:199], v[4:7]
	v_mfma_f32_16x16x32_bf16 v[4:7], v[216:219], v[192:195], v[114:117]
	v_mfma_f32_16x16x32_bf16 v[114:117], v[220:223], v[196:199], v[4:7]
	v_mfma_f32_16x16x32_bf16 v[4:7], v[208:211], v[200:203], v[94:97]
	v_mfma_f32_16x16x32_bf16 v[94:97], v[212:215], v[204:207], v[4:7]
	v_mfma_f32_16x16x32_bf16 v[4:7], v[216:219], v[200:203], v[98:101]
	v_mfma_f32_16x16x32_bf16 v[98:101], v[220:223], v[204:207], v[4:7]
	s_nop 0
	s_barrier
	s_nop 4
	ds_read_b128 v[4:7], v137
	ds_read_b128 v[122:125], v137 offset:1024
	ds_read_b128 v[144:147], v137 offset:2048
	ds_read_b128 v[148:151], v137 offset:3072
	s_add_u32 s14, s40, 0x10000
	s_addc_u32 s15, s41, 0
	s_mov_b32 m0, s16
	v_lshl_add_u64 v[134:135], s[14:15], 0, v[62:63]
	ds_read_b128 v[152:155], v68 offset:32768
	ds_read_b128 v[156:159], v68 offset:33792
	ds_read_b128 v[184:187], v68 offset:34816
	ds_read_b128 v[188:191], v68 offset:35840
	ds_read_b128 v[192:195], v68 offset:36864
	ds_read_b128 v[196:199], v68 offset:37888
	ds_read_b128 v[200:203], v68 offset:38912
	ds_read_b128 v[204:207], v68 offset:39936
	global_load_lds_dwordx4 v[134:135], off
	v_lshl_add_u64 v[134:135], s[14:15], 0, v[58:59]
	s_mov_b32 m0, s17
	s_nop 0
	global_load_lds_dwordx4 v[134:135], off
	s_waitcnt lgkmcnt(8)
	s_barrier
	s_waitcnt lgkmcnt(0)
	s_nop 0
	s_waitcnt lgkmcnt(0)
	v_mfma_f32_16x16x32_bf16 v[48:51], v[4:7], v[152:155], v[48:51]
	v_mfma_f32_16x16x32_bf16 v[208:211], v[122:125], v[156:159], v[48:51]
	v_mfma_f32_16x16x32_bf16 v[48:51], v[144:147], v[152:155], v[52:55]
	v_mfma_f32_16x16x32_bf16 v[212:215], v[148:151], v[156:159], v[48:51]
	v_mfma_f32_16x16x32_bf16 v[48:51], v[4:7], v[184:187], v[70:73]
	v_mfma_f32_16x16x32_bf16 v[70:73], v[122:125], v[188:191], v[48:51]
	v_mfma_f32_16x16x32_bf16 v[48:51], v[144:147], v[184:187], v[74:77]
	v_mfma_f32_16x16x32_bf16 v[74:77], v[148:151], v[188:191], v[48:51]
	v_mfma_f32_16x16x32_bf16 v[48:51], v[4:7], v[192:195], v[78:81]
	v_mfma_f32_16x16x32_bf16 v[78:81], v[122:125], v[196:199], v[48:51]
	v_mfma_f32_16x16x32_bf16 v[48:51], v[144:147], v[192:195], v[82:85]
	v_mfma_f32_16x16x32_bf16 v[82:85], v[148:151], v[196:199], v[48:51]
	v_mfma_f32_16x16x32_bf16 v[48:51], v[4:7], v[200:203], v[86:89]
	v_mfma_f32_16x16x32_bf16 v[52:55], v[122:125], v[204:207], v[48:51]
	v_mfma_f32_16x16x32_bf16 v[48:51], v[144:147], v[200:203], v[90:93]
	v_mfma_f32_16x16x32_bf16 v[48:51], v[148:151], v[204:207], v[48:51]
	s_nop 0
	s_barrier
	s_mov_b32 m0, s49
	v_lshl_add_u64 v[134:135], v[64:65], 0, s[28:29]
	ds_read_b128 v[86:89], v138
	ds_read_b128 v[90:93], v138 offset:1024
	ds_read_b128 v[216:219], v138 offset:2048
	ds_read_b128 v[220:223], v138 offset:3072
	global_load_lds_dwordx4 v[134:135], off
	v_lshl_add_u64 v[134:135], v[126:127], 0, s[28:29]
	s_mov_b32 m0, s45
	s_nop 0
	global_load_lds_dwordx4 v[134:135], off
	s_barrier
	s_waitcnt lgkmcnt(0)
	s_nop 0
	s_waitcnt lgkmcnt(0)
	v_mfma_f32_16x16x32_bf16 v[16:19], v[216:219], v[152:155], v[16:19]
	v_mfma_f32_16x16x32_bf16 v[110:113], v[86:89], v[152:155], v[110:113]
	v_mfma_f32_16x16x32_bf16 v[152:155], v[220:223], v[156:159], v[16:19]
	v_mfma_f32_16x16x32_bf16 v[16:19], v[86:89], v[184:187], v[20:23]
	v_mfma_f32_16x16x32_bf16 v[110:113], v[90:93], v[156:159], v[110:113]
	v_mfma_f32_16x16x32_bf16 v[156:159], v[90:93], v[188:191], v[16:19]
	v_mfma_f32_16x16x32_bf16 v[16:19], v[216:219], v[184:187], v[24:27]
	v_mfma_f32_16x16x32_bf16 v[184:187], v[220:223], v[188:191], v[16:19]
	v_mfma_f32_16x16x32_bf16 v[16:19], v[86:89], v[192:195], v[28:31]
	v_mfma_f32_16x16x32_bf16 v[188:191], v[90:93], v[196:199], v[16:19]
	v_mfma_f32_16x16x32_bf16 v[16:19], v[216:219], v[192:195], v[32:35]
	v_mfma_f32_16x16x32_bf16 v[192:195], v[220:223], v[196:199], v[16:19]
	v_mfma_f32_16x16x32_bf16 v[16:19], v[86:89], v[200:203], v[36:39]
	v_mfma_f32_16x16x32_bf16 v[196:199], v[90:93], v[204:207], v[16:19]
	v_mfma_f32_16x16x32_bf16 v[16:19], v[216:219], v[200:203], v[40:43]
	v_mfma_f32_16x16x32_bf16 v[200:203], v[220:223], v[204:207], v[16:19]
	s_nop 0
	s_mov_b32 m0, s24
	s_nop 4
	v_lshl_add_u64 v[16:17], v[130:131], 0, s[28:29]
	s_barrier
	ds_read_b128 v[24:27], v68 offset:49152
	ds_read_b128 v[28:31], v68 offset:50176
	ds_read_b128 v[40:43], v68 offset:51200
	ds_read_b128 v[204:207], v68 offset:52224
	ds_read_b128 v[224:227], v68 offset:53248
	ds_read_b128 v[228:231], v68 offset:54272
	ds_read_b128 v[244:247], v68 offset:55296
	ds_read_b128 v[248:251], v68 offset:56320
	global_load_lds_dwordx4 v[16:17], off
	v_lshl_add_u64 v[16:17], v[132:133], 0, s[28:29]
	s_mov_b32 m0, s25
	s_nop 0
	global_load_lds_dwordx4 v[16:17], off
	s_barrier
	s_waitcnt lgkmcnt(0)
	s_nop 0
	s_waitcnt lgkmcnt(0)
	v_mfma_f32_16x16x32_bf16 v[16:19], v[4:7], v[24:27], v[160:163]
	v_mfma_f32_16x16x32_bf16 v[160:163], v[122:125], v[28:31], v[16:19]
	v_mfma_f32_16x16x32_bf16 v[16:19], v[144:147], v[24:27], v[164:167]
	v_mfma_f32_16x16x32_bf16 v[164:167], v[148:151], v[28:31], v[16:19]
	v_mfma_f32_16x16x32_bf16 v[16:19], v[4:7], v[40:43], v[168:171]
	v_mfma_f32_16x16x32_bf16 v[36:39], v[122:125], v[204:207], v[16:19]
	v_mfma_f32_16x16x32_bf16 v[16:19], v[144:147], v[40:43], v[172:175]
	v_mfma_f32_16x16x32_bf16 v[32:35], v[148:151], v[204:207], v[16:19]
	v_mfma_f32_16x16x32_bf16 v[16:19], v[4:7], v[224:227], v[176:179]
	v_mfma_f32_16x16x32_bf16 v[0:3], v[4:7], v[244:247], v[0:3]
	v_mfma_f32_16x16x32_bf16 v[20:23], v[122:125], v[228:231], v[16:19]
	v_mfma_f32_16x16x32_bf16 v[16:19], v[144:147], v[224:227], v[180:183]
	v_mfma_f32_16x16x32_bf16 v[4:7], v[122:125], v[248:251], v[0:3]
	v_mfma_f32_16x16x32_bf16 v[0:3], v[144:147], v[244:247], v[118:121]
	v_mfma_f32_16x16x32_bf16 v[16:19], v[148:151], v[228:231], v[16:19]
	v_mfma_f32_16x16x32_bf16 v[0:3], v[148:151], v[248:251], v[0:3]
	s_nop 0
	s_barrier
	s_mov_b64 s[14:15], 0x880
	s_mov_b32 m0, s48
	v_lshl_add_u64 v[64:65], v[64:65], 0, s[14:15]
	global_load_lds_dwordx4 v[64:65], off
	v_lshl_add_u64 v[64:65], v[126:127], 0, s[14:15]
	s_mov_b32 m0, s47
	s_nop 0
	global_load_lds_dwordx4 v[64:65], off
	s_waitcnt vmcnt(6)
	s_barrier
	s_nop 0
	v_mfma_f32_16x16x32_bf16 v[8:11], v[86:89], v[24:27], v[8:11]
	v_mfma_f32_16x16x32_bf16 v[118:121], v[90:93], v[28:31], v[8:11]
	v_mfma_f32_16x16x32_bf16 v[8:11], v[216:219], v[24:27], v[12:15]
	v_mfma_f32_16x16x32_bf16 v[122:125], v[220:223], v[28:31], v[8:11]
	v_mfma_f32_16x16x32_bf16 v[8:11], v[86:89], v[40:43], v[44:47]
	v_mfma_f32_16x16x32_bf16 v[44:47], v[90:93], v[204:207], v[8:11]
	v_mfma_f32_16x16x32_bf16 v[8:11], v[216:219], v[40:43], v[102:105]
	v_mfma_f32_16x16x32_bf16 v[40:43], v[220:223], v[204:207], v[8:11]
	v_mfma_f32_16x16x32_bf16 v[8:11], v[86:89], v[224:227], v[106:109]
	v_mfma_f32_16x16x32_bf16 v[28:31], v[90:93], v[228:231], v[8:11]
	v_mfma_f32_16x16x32_bf16 v[8:11], v[216:219], v[224:227], v[114:117]
	v_mfma_f32_16x16x32_bf16 v[24:27], v[220:223], v[228:231], v[8:11]
	v_mfma_f32_16x16x32_bf16 v[8:11], v[86:89], v[244:247], v[94:97]
	v_mfma_f32_16x16x32_bf16 v[12:15], v[90:93], v[248:251], v[8:11]
	v_mfma_f32_16x16x32_bf16 v[8:11], v[216:219], v[244:247], v[98:101]
	v_mfma_f32_16x16x32_bf16 v[8:11], v[220:223], v[248:251], v[8:11]
	v_mbcnt_lo_u32_b32 v140, -1, 0
	v_mbcnt_hi_u32_b32 v140, -1, v140
	v_and_b32_e32 v140, 16, v140
	v_lshrrev_b32_e32 v141, 1, v140
	v_add_u32_e32 v140, v140, v141
	v_mov_b32_e32 v141, 0
	s_nop 0
	s_lshl_b32 s14, s36, 1
	s_and_b32 s13, s14, 0xffffff00
	v_add_u32_e32 v64, s13, v66
	v_ashrrev_i32_e32 v65, 31, v64
	s_and_b32 s18, s14, 0xf0
	v_lshlrev_b64 v[86:87], 8, v[64:65]
	s_and_b32 s13, s14, 14
	v_or_b32_e32 v65, s18, v86
	v_or_b32_e32 v86, s13, v65
	s_ashr_i32 s45, s44, 31
	v_lshlrev_b64 v[88:89], 9, v[86:87]
	s_or_b32 s19, s13, 1
	s_lshl_b64 s[14:15], s[44:45], 8
	v_lshl_add_u64 v[88:89], s[96:97], 0, v[88:89]
	v_or_b32_e32 v86, s19, v65
	v_lshl_add_u64 v[88:89], v[88:89], 0, s[14:15]
	v_lshlrev_b64 v[86:87], 9, v[86:87]
	v_lshl_add_u64 v[88:89], v[88:89], 0, s[92:93]
	v_lshl_add_u64 v[86:87], s[96:97], 0, v[86:87]
	v_lshl_add_u64 v[88:89], v[88:89], 0, v[128:129]
	v_lshl_add_u64 v[86:87], v[86:87], 0, s[14:15]
	s_barrier
	v_cvt_pk_bf16_f32 v238, v208, v209
	v_cvt_pk_bf16_f32 v239, v210, v211
	v_cvt_pk_bf16_f32 v240, v212, v213
	v_cvt_pk_bf16_f32 v241, v214, v215
	v_lshl_add_u64 v[88:89], v[88:89], 0, v[140:141]
	s_nop 0
	v_permlane16_swap_b32_e32 v238, v240
	v_permlane16_swap_b32_e32 v239, v241
	global_store_dwordx4 v[88:89], v[238:241], off
	s_nop 1
	v_lshl_add_u64 v[86:87], v[86:87], 0, s[92:93]
	v_lshl_add_u64 v[86:87], v[86:87], 0, v[128:129]
	v_cvt_pk_bf16_f32 v238, v110, v111
	v_cvt_pk_bf16_f32 v239, v112, v113
	v_cvt_pk_bf16_f32 v240, v152, v153
	v_cvt_pk_bf16_f32 v241, v154, v155
	v_lshl_add_u64 v[86:87], v[86:87], 0, v[140:141]
	s_nop 0
	v_permlane16_swap_b32_e32 v238, v240
	v_permlane16_swap_b32_e32 v239, v241
	global_store_dwordx4 v[86:87], v[238:241], off
	s_nop 1
	v_or_b32_e32 v86, 16, v64
	v_ashrrev_i32_e32 v87, 31, v86
	v_lshlrev_b64 v[86:87], 8, v[86:87]
	v_or_b32_e32 v65, s18, v86
	v_or_b32_e32 v86, s13, v65
	v_lshlrev_b64 v[88:89], 9, v[86:87]
	v_lshl_add_u64 v[88:89], s[96:97], 0, v[88:89]
	v_lshl_add_u64 v[88:89], v[88:89], 0, s[14:15]
	v_lshl_add_u64 v[88:89], v[88:89], 0, s[92:93]
	v_lshl_add_u64 v[88:89], v[88:89], 0, v[128:129]
	v_cvt_pk_bf16_f32 v238, v70, v71
	v_cvt_pk_bf16_f32 v239, v72, v73
	v_cvt_pk_bf16_f32 v240, v74, v75
	v_cvt_pk_bf16_f32 v241, v76, v77
	v_lshl_add_u64 v[88:89], v[88:89], 0, v[140:141]
	s_nop 0
	v_permlane16_swap_b32_e32 v238, v240
	v_permlane16_swap_b32_e32 v239, v241
	global_store_dwordx4 v[88:89], v[238:241], off
	s_nop 1
	v_or_b32_e32 v86, s19, v65
	v_lshlrev_b64 v[70:71], 9, v[86:87]
	v_lshl_add_u64 v[70:71], s[96:97], 0, v[70:71]
	v_lshl_add_u64 v[70:71], v[70:71], 0, s[14:15]
	v_lshl_add_u64 v[70:71], v[70:71], 0, s[92:93]
	v_lshl_add_u64 v[70:71], v[70:71], 0, v[128:129]
	v_cvt_pk_bf16_f32 v238, v156, v157
	v_cvt_pk_bf16_f32 v239, v158, v159
	v_cvt_pk_bf16_f32 v240, v184, v185
	v_cvt_pk_bf16_f32 v241, v186, v187
	v_lshl_add_u64 v[70:71], v[70:71], 0, v[140:141]
	s_nop 0
	v_permlane16_swap_b32_e32 v238, v240
	v_permlane16_swap_b32_e32 v239, v241
	global_store_dwordx4 v[70:71], v[238:241], off
	s_nop 1
	v_or_b32_e32 v70, 32, v64
	v_ashrrev_i32_e32 v71, 31, v70
	v_lshlrev_b64 v[70:71], 8, v[70:71]
	v_or_b32_e32 v65, s18, v70
	v_or_b32_e32 v70, s13, v65
	v_lshlrev_b64 v[72:73], 9, v[70:71]
	v_lshl_add_u64 v[72:73], s[96:97], 0, v[72:73]
	v_or_b32_e32 v70, s19, v65
	v_lshl_add_u64 v[72:73], v[72:73], 0, s[14:15]
	v_lshlrev_b64 v[70:71], 9, v[70:71]
	v_lshl_add_u64 v[72:73], v[72:73], 0, s[92:93]
	v_lshl_add_u64 v[70:71], s[96:97], 0, v[70:71]
	v_lshl_add_u64 v[72:73], v[72:73], 0, v[128:129]
	v_lshl_add_u64 v[70:71], v[70:71], 0, s[14:15]
	v_cvt_pk_bf16_f32 v238, v78, v79
	v_cvt_pk_bf16_f32 v239, v80, v81
	v_cvt_pk_bf16_f32 v240, v82, v83
	v_cvt_pk_bf16_f32 v241, v84, v85
	v_lshl_add_u64 v[72:73], v[72:73], 0, v[140:141]
	s_nop 0
	v_permlane16_swap_b32_e32 v238, v240
	v_permlane16_swap_b32_e32 v239, v241
	global_store_dwordx4 v[72:73], v[238:241], off
	s_nop 1
	v_lshl_add_u64 v[70:71], v[70:71], 0, s[92:93]
	v_lshl_add_u64 v[70:71], v[70:71], 0, v[128:129]
	v_cvt_pk_bf16_f32 v238, v188, v189
	v_cvt_pk_bf16_f32 v239, v190, v191
	v_cvt_pk_bf16_f32 v240, v192, v193
	v_cvt_pk_bf16_f32 v241, v194, v195
	v_lshl_add_u64 v[70:71], v[70:71], 0, v[140:141]
	s_nop 0
	v_permlane16_swap_b32_e32 v238, v240
	v_permlane16_swap_b32_e32 v239, v241
	global_store_dwordx4 v[70:71], v[238:241], off
	s_nop 1
	v_or_b32_e32 v70, 48, v64
	v_ashrrev_i32_e32 v71, 31, v70
	v_lshlrev_b64 v[70:71], 8, v[70:71]
	v_or_b32_e32 v65, s18, v70
	v_or_b32_e32 v70, s13, v65
	v_lshlrev_b64 v[72:73], 9, v[70:71]
	v_lshl_add_u64 v[72:73], s[96:97], 0, v[72:73]
	v_lshl_add_u64 v[72:73], v[72:73], 0, s[14:15]
	v_lshl_add_u64 v[72:73], v[72:73], 0, s[92:93]
	v_lshl_add_u64 v[72:73], v[72:73], 0, v[128:129]
	v_or_b32_e32 v70, s19, v65
	v_cvt_pk_bf16_f32 v238, v52, v53
	v_cvt_pk_bf16_f32 v239, v54, v55
	v_cvt_pk_bf16_f32 v240, v48, v49
	v_cvt_pk_bf16_f32 v241, v50, v51
	v_lshl_add_u64 v[72:73], v[72:73], 0, v[140:141]
	s_nop 0
	v_permlane16_swap_b32_e32 v238, v240
	v_permlane16_swap_b32_e32 v239, v241
	global_store_dwordx4 v[72:73], v[238:241], off
	s_nop 1
	v_lshlrev_b64 v[48:49], 9, v[70:71]
	v_lshl_add_u64 v[48:49], s[96:97], 0, v[48:49]
	v_lshl_add_u64 v[48:49], v[48:49], 0, s[14:15]
	v_lshl_add_u64 v[48:49], v[48:49], 0, s[92:93]
	v_lshl_add_u64 v[48:49], v[48:49], 0, v[128:129]
	v_cvt_pk_bf16_f32 v238, v196, v197
	v_cvt_pk_bf16_f32 v239, v198, v199
	v_cvt_pk_bf16_f32 v240, v200, v201
	v_cvt_pk_bf16_f32 v241, v202, v203
	v_lshl_add_u64 v[48:49], v[48:49], 0, v[140:141]
	s_nop 0
	v_permlane16_swap_b32_e32 v238, v240
	v_permlane16_swap_b32_e32 v239, v241
	global_store_dwordx4 v[48:49], v[238:241], off
	s_nop 1
	v_add_u32_e32 v48, 0x80, v64
	v_ashrrev_i32_e32 v49, 31, v48
	v_lshlrev_b64 v[48:49], 8, v[48:49]
	v_or_b32_e32 v54, s18, v48
	v_or_b32_e32 v48, s13, v54
	v_lshlrev_b64 v[50:51], 9, v[48:49]
	v_lshl_add_u64 v[50:51], s[96:97], 0, v[50:51]
	v_or_b32_e32 v48, s19, v54
	v_lshl_add_u64 v[50:51], v[50:51], 0, s[14:15]
	v_lshlrev_b64 v[48:49], 9, v[48:49]
	v_lshl_add_u64 v[50:51], v[50:51], 0, s[92:93]
	v_lshl_add_u64 v[48:49], s[96:97], 0, v[48:49]
	v_lshl_add_u64 v[50:51], v[50:51], 0, v[128:129]
	v_lshl_add_u64 v[48:49], v[48:49], 0, s[14:15]
	v_cvt_pk_bf16_f32 v238, v160, v161
	v_cvt_pk_bf16_f32 v239, v162, v163
	v_cvt_pk_bf16_f32 v240, v164, v165
	v_cvt_pk_bf16_f32 v241, v166, v167
	v_lshl_add_u64 v[50:51], v[50:51], 0, v[140:141]
	s_nop 0
	v_permlane16_swap_b32_e32 v238, v240
	v_permlane16_swap_b32_e32 v239, v241
	global_store_dwordx4 v[50:51], v[238:241], off
	s_nop 1
	v_lshl_add_u64 v[48:49], v[48:49], 0, s[92:93]
	v_lshl_add_u64 v[48:49], v[48:49], 0, v[128:129]
	v_cvt_pk_bf16_f32 v238, v118, v119
	v_cvt_pk_bf16_f32 v239, v120, v121
	v_cvt_pk_bf16_f32 v240, v122, v123
	v_cvt_pk_bf16_f32 v241, v124, v125
	v_lshl_add_u64 v[48:49], v[48:49], 0, v[140:141]
	s_nop 0
	v_permlane16_swap_b32_e32 v238, v240
	v_permlane16_swap_b32_e32 v239, v241
	global_store_dwordx4 v[48:49], v[238:241], off
	s_nop 1
	v_add_u32_e32 v48, 0x90, v64
	v_ashrrev_i32_e32 v49, 31, v48
	v_lshlrev_b64 v[48:49], 8, v[48:49]
	v_or_b32_e32 v52, s18, v48
	v_or_b32_e32 v48, s13, v52
	v_lshlrev_b64 v[50:51], 9, v[48:49]
	v_lshl_add_u64 v[50:51], s[96:97], 0, v[50:51]
	v_lshl_add_u64 v[50:51], v[50:51], 0, s[14:15]
	v_lshl_add_u64 v[50:51], v[50:51], 0, s[92:93]
	v_lshl_add_u64 v[50:51], v[50:51], 0, v[128:129]
	v_or_b32_e32 v48, s19, v52
	v_cvt_pk_bf16_f32 v238, v36, v37
	v_cvt_pk_bf16_f32 v239, v38, v39
	v_cvt_pk_bf16_f32 v240, v32, v33
	v_cvt_pk_bf16_f32 v241, v34, v35
	v_lshl_add_u64 v[50:51], v[50:51], 0, v[140:141]
	s_nop 0
	v_permlane16_swap_b32_e32 v238, v240
	v_permlane16_swap_b32_e32 v239, v241
	global_store_dwordx4 v[50:51], v[238:241], off
	s_nop 1
	v_lshlrev_b64 v[32:33], 9, v[48:49]
	v_lshl_add_u64 v[32:33], s[96:97], 0, v[32:33]
	v_lshl_add_u64 v[32:33], v[32:33], 0, s[14:15]
	v_lshl_add_u64 v[32:33], v[32:33], 0, s[92:93]
	v_lshl_add_u64 v[32:33], v[32:33], 0, v[128:129]
	v_cvt_pk_bf16_f32 v238, v44, v45
	v_cvt_pk_bf16_f32 v239, v46, v47
	v_cvt_pk_bf16_f32 v240, v40, v41
	v_cvt_pk_bf16_f32 v241, v42, v43
	v_lshl_add_u64 v[32:33], v[32:33], 0, v[140:141]
	s_nop 0
	v_permlane16_swap_b32_e32 v238, v240
	v_permlane16_swap_b32_e32 v239, v241
	global_store_dwordx4 v[32:33], v[238:241], off
	s_nop 1
	v_add_u32_e32 v32, 0xa0, v64
	v_ashrrev_i32_e32 v33, 31, v32
	v_lshlrev_b64 v[32:33], 8, v[32:33]
	v_or_b32_e32 v36, s18, v32
	v_or_b32_e32 v32, s13, v36
	v_lshlrev_b64 v[34:35], 9, v[32:33]
	v_lshl_add_u64 v[34:35], s[96:97], 0, v[34:35]
	v_lshl_add_u64 v[34:35], v[34:35], 0, s[14:15]
	v_lshl_add_u64 v[34:35], v[34:35], 0, s[92:93]
	v_lshl_add_u64 v[34:35], v[34:35], 0, v[128:129]
	v_or_b32_e32 v32, s19, v36
	v_cvt_pk_bf16_f32 v238, v20, v21
	v_cvt_pk_bf16_f32 v239, v22, v23
	v_cvt_pk_bf16_f32 v240, v16, v17
	v_cvt_pk_bf16_f32 v241, v18, v19
	v_lshl_add_u64 v[34:35], v[34:35], 0, v[140:141]
	s_nop 0
	v_permlane16_swap_b32_e32 v238, v240
	v_permlane16_swap_b32_e32 v239, v241
	global_store_dwordx4 v[34:35], v[238:241], off
	s_nop 1
	v_lshlrev_b64 v[16:17], 9, v[32:33]
	v_lshl_add_u64 v[16:17], s[96:97], 0, v[16:17]
	v_lshl_add_u64 v[16:17], v[16:17], 0, s[14:15]
	v_lshl_add_u64 v[16:17], v[16:17], 0, s[92:93]
	v_lshl_add_u64 v[16:17], v[16:17], 0, v[128:129]
	v_cvt_pk_bf16_f32 v238, v28, v29
	v_cvt_pk_bf16_f32 v239, v30, v31
	v_cvt_pk_bf16_f32 v240, v24, v25
	v_cvt_pk_bf16_f32 v241, v26, v27
	v_lshl_add_u64 v[16:17], v[16:17], 0, v[140:141]
	s_nop 0
	v_permlane16_swap_b32_e32 v238, v240
	v_permlane16_swap_b32_e32 v239, v241
	global_store_dwordx4 v[16:17], v[238:241], off
	s_nop 1
	v_add_u32_e32 v16, 0xb0, v64
	v_ashrrev_i32_e32 v17, 31, v16
	v_lshlrev_b64 v[16:17], 8, v[16:17]
	v_or_b32_e32 v20, s18, v16
	v_or_b32_e32 v16, s13, v20
	v_lshlrev_b64 v[18:19], 9, v[16:17]
	v_lshl_add_u64 v[18:19], s[96:97], 0, v[18:19]
	v_lshl_add_u64 v[18:19], v[18:19], 0, s[14:15]
	v_lshl_add_u64 v[18:19], v[18:19], 0, s[92:93]
	v_lshl_add_u64 v[18:19], v[18:19], 0, v[128:129]
	v_or_b32_e32 v16, s19, v20
	v_cvt_pk_bf16_f32 v238, v4, v5
	v_cvt_pk_bf16_f32 v239, v6, v7
	v_cvt_pk_bf16_f32 v240, v0, v1
	v_cvt_pk_bf16_f32 v241, v2, v3
	v_lshl_add_u64 v[18:19], v[18:19], 0, v[140:141]
	s_nop 0
	v_permlane16_swap_b32_e32 v238, v240
	v_permlane16_swap_b32_e32 v239, v241
	global_store_dwordx4 v[18:19], v[238:241], off
	s_nop 1
	v_lshlrev_b64 v[0:1], 9, v[16:17]
	v_lshl_add_u64 v[0:1], s[96:97], 0, v[0:1]
	v_lshl_add_u64 v[0:1], v[0:1], 0, s[14:15]
	v_lshl_add_u64 v[0:1], v[0:1], 0, s[92:93]
	v_lshl_add_u64 v[0:1], v[0:1], 0, v[128:129]
	v_cvt_pk_bf16_f32 v238, v12, v13
	v_cvt_pk_bf16_f32 v239, v14, v15
	v_cvt_pk_bf16_f32 v240, v8, v9
	v_cvt_pk_bf16_f32 v241, v10, v11
	v_lshl_add_u64 v[0:1], v[0:1], 0, v[140:141]
	s_nop 0
	v_permlane16_swap_b32_e32 v238, v240
	v_permlane16_swap_b32_e32 v239, v241
	global_store_dwordx4 v[0:1], v[238:241], off
	s_nop 1
	s_add_i32 s34, s34, s90
	s_andn2_b64 vcc, exec, s[38:39]
	s_mov_b32 s44, s12
	s_mov_b32 s36, s35
	s_mov_b64 s[18:19], s[30:31]
	s_mov_b64 s[14:15], s[42:43]
	v_readlane_b32 s20, v255, 27
	s_cbranch_vccz .LBB0_113
